# buffer placement: P6 output H1 written over the dead Z0 region (still cache-resident) instead of the H region, on top of H0 in the P region
# baseline (speedup 1.0000x reference)
; __device__ __forceinline__ float bf_lo(unsigned w) { return __uint_as_float(w << 16); }
; __device__ __forceinline__ float bf_hi(unsigned w) { return __uint_as_float(w & 0xffff0000u); }
; __global__ void __launch_bounds__(NWAVES * 64, 2) mk_fwd(Args args) {
;     ...
; #pragma unroll
;             for (int q = 0; q < 3; ++q) { const int row = row0 + q; const float* src = row < ML ? x + (size_t)row * DM : ctx + (size_t)(row - ML) * DM; load_row_f32(src, F.lane, v[q]);
;                 const bf16_t* yr = Y + (size_t)row * DM;
; #pragma unroll
;                 for (int j = 0; j < 8; ++j) yw[q][j] = *(const u32x2*)(yr + 4 * F.lane + 256 * j); }
;     ...
;             for (int q = 0; q < 3; ++q) { const int row = row0 + q; const bool lat = row < ML; const int r = lat ? row / SEQ : 8;
;                 float sy = 0.f;
; #pragma unroll
;                 for (int j = 0; j < 8; ++j) { const float a = bf_lo(yw[q][j].x), b = bf_hi(yw[q][j].x), c2 = bf_lo(yw[q][j].y), d = bf_hi(yw[q][j].y); sy += (a * a + b * b) + (c2 * c2 + d * d); }
;                 const float rsy = __builtin_amdgcn_rsqf(wave_sum(sy) * (1.f / DM) + EPS);
;                 const float* m0 = mod + (size_t)r * 6144;
; #pragma unroll
;                 for (int j = 0; j < 8; ++j) { const int col = 4 * F.lane + 256 * j; const f32x4 gt = *(const f32x4*)(m0 + 2 * DM + col), pn = *(const f32x4*)(post_norm + col);
;                     const f32x4 y4 = (f32x4){bf_lo(yw[q][j].x), bf_hi(yw[q][j].x), bf_lo(yw[q][j].y), bf_hi(yw[q][j].y)};
;                     v[q][j] = v[q][j] + gt * (y4 * rsy * pn);
.Lp6_np0:
	s_waitcnt vmcnt(16)
	v_lshlrev_b32_e32 v216, 16, v32
	v_and_b32_e32 v217, 0xffff0000, v32
	v_lshlrev_b32_e32 v218, 16, v33
	v_and_b32_e32 v219, 0xffff0000, v33
	v_mul_f32_e32 v222, v216, v216
	v_mul_f32_e32 v223, v217, v217
	v_fmac_f32_e32 v222, v218, v218
	v_fmac_f32_e32 v223, v219, v219
	v_lshlrev_b32_e32 v216, 16, v34
	v_and_b32_e32 v217, 0xffff0000, v34
	v_lshlrev_b32_e32 v218, 16, v35
	v_and_b32_e32 v219, 0xffff0000, v35
	v_fmac_f32_e32 v222, v216, v216
	v_fmac_f32_e32 v223, v217, v217
	v_fmac_f32_e32 v222, v218, v218
	v_fmac_f32_e32 v223, v219, v219
	v_lshlrev_b32_e32 v216, 16, v36
	v_and_b32_e32 v217, 0xffff0000, v36
	v_lshlrev_b32_e32 v218, 16, v37
	v_and_b32_e32 v219, 0xffff0000, v37
	v_fmac_f32_e32 v222, v216, v216
	v_fmac_f32_e32 v223, v217, v217
	v_fmac_f32_e32 v222, v218, v218
	v_fmac_f32_e32 v223, v219, v219
	v_lshlrev_b32_e32 v216, 16, v38
	v_and_b32_e32 v217, 0xffff0000, v38
	v_lshlrev_b32_e32 v218, 16, v39
	v_and_b32_e32 v219, 0xffff0000, v39
	v_fmac_f32_e32 v222, v216, v216
	v_fmac_f32_e32 v223, v217, v217
	v_fmac_f32_e32 v222, v218, v218
	v_fmac_f32_e32 v223, v219, v219
	v_lshlrev_b32_e32 v216, 16, v40
	v_and_b32_e32 v217, 0xffff0000, v40
	v_lshlrev_b32_e32 v218, 16, v41
	v_and_b32_e32 v219, 0xffff0000, v41
	v_fmac_f32_e32 v222, v216, v216
	v_fmac_f32_e32 v223, v217, v217
	v_fmac_f32_e32 v222, v218, v218
	v_fmac_f32_e32 v223, v219, v219
	v_lshlrev_b32_e32 v216, 16, v42
	v_and_b32_e32 v217, 0xffff0000, v42
	v_lshlrev_b32_e32 v218, 16, v43
	v_and_b32_e32 v219, 0xffff0000, v43
	v_fmac_f32_e32 v222, v216, v216
	v_fmac_f32_e32 v223, v217, v217
	v_fmac_f32_e32 v222, v218, v218
	v_fmac_f32_e32 v223, v219, v219
	v_lshlrev_b32_e32 v216, 16, v44
	v_and_b32_e32 v217, 0xffff0000, v44
	v_lshlrev_b32_e32 v218, 16, v45
	v_and_b32_e32 v219, 0xffff0000, v45
	v_fmac_f32_e32 v222, v216, v216
	v_fmac_f32_e32 v223, v217, v217
	v_fmac_f32_e32 v222, v218, v218
	v_fmac_f32_e32 v223, v219, v219
	v_lshlrev_b32_e32 v216, 16, v46
	v_and_b32_e32 v217, 0xffff0000, v46
	v_lshlrev_b32_e32 v218, 16, v47
	v_and_b32_e32 v219, 0xffff0000, v47
	v_fmac_f32_e32 v222, v216, v216
	v_fmac_f32_e32 v223, v217, v217
	v_fmac_f32_e32 v222, v218, v218
	v_fmac_f32_e32 v223, v219, v219
	v_add_f32_e32 v222, v222, v223
	s_nop 1
	v_add_f32_dpp v224, v222, v222 quad_perm:[1,0,3,2] row_mask:0xf bank_mask:0xf
	s_nop 1
	v_add_f32_dpp v224, v224, v224 quad_perm:[2,3,0,1] row_mask:0xf bank_mask:0xf
	s_nop 1
	v_add_f32_dpp v224, v224, v224 row_half_mirror row_mask:0xf bank_mask:0xf
	s_nop 1
	v_add_f32_dpp v224, v224, v224 row_mirror row_mask:0xf bank_mask:0xf
	s_nop 1
	v_readlane_b32 s40, v224, 0
	v_readlane_b32 s41, v224, 16
	v_readlane_b32 s42, v224, 32
	v_readlane_b32 s43, v224, 48
	s_nop 1
	v_mov_b32_e32 v225, s40
	v_add_f32_e32 v225, s41, v225
	v_add_f32_e32 v225, s42, v225
	v_add_f32_e32 v225, s43, v225
	v_fmamk_f32 v225, v225, 0x3a000000, v195
	v_rsq_f32_e32 v225, v225
	s_nop 0
	v_lshlrev_b32_e32 v216, 16, v32
	v_and_b32_e32 v217, 0xffff0000, v32
	v_lshlrev_b32_e32 v218, 16, v33
	v_and_b32_e32 v219, 0xffff0000, v33
	v_mul_f32_e32 v216, v225, v216
	v_mul_f32_e32 v217, v225, v217
	v_mul_f32_e32 v218, v225, v218
	v_mul_f32_e32 v219, v225, v219
	v_fmac_f32_e32 v0, v96, v216
	v_fmac_f32_e32 v1, v97, v217
	v_fmac_f32_e32 v2, v98, v218
	v_fmac_f32_e32 v3, v99, v219
	v_lshlrev_b32_e32 v216, 16, v34
	v_and_b32_e32 v217, 0xffff0000, v34
	v_lshlrev_b32_e32 v218, 16, v35
	v_and_b32_e32 v219, 0xffff0000, v35
	v_mul_f32_e32 v216, v225, v216
	v_mul_f32_e32 v217, v225, v217
	v_mul_f32_e32 v218, v225, v218
	v_mul_f32_e32 v219, v225, v219
	v_fmac_f32_e32 v4, v100, v216
	v_fmac_f32_e32 v5, v101, v217
	v_fmac_f32_e32 v6, v102, v218
	v_fmac_f32_e32 v7, v103, v219
	v_lshlrev_b32_e32 v216, 16, v36
	v_and_b32_e32 v217, 0xffff0000, v36
	v_lshlrev_b32_e32 v218, 16, v37
	v_and_b32_e32 v219, 0xffff0000, v37
	v_mul_f32_e32 v216, v225, v216
	v_mul_f32_e32 v217, v225, v217
	v_mul_f32_e32 v218, v225, v218
	v_mul_f32_e32 v219, v225, v219
	v_fmac_f32_e32 v8, v104, v216
	v_fmac_f32_e32 v9, v105, v217
	v_fmac_f32_e32 v10, v106, v218
	v_fmac_f32_e32 v11, v107, v219
	v_lshlrev_b32_e32 v216, 16, v38
	v_and_b32_e32 v217, 0xffff0000, v38
	v_lshlrev_b32_e32 v218, 16, v39
	v_and_b32_e32 v219, 0xffff0000, v39
	v_mul_f32_e32 v216, v225, v216
	v_mul_f32_e32 v217, v225, v217
	v_mul_f32_e32 v218, v225, v218
	v_mul_f32_e32 v219, v225, v219
	v_fmac_f32_e32 v12, v108, v216
	v_fmac_f32_e32 v13, v109, v217
	v_fmac_f32_e32 v14, v110, v218
	v_fmac_f32_e32 v15, v111, v219
	v_lshlrev_b32_e32 v216, 16, v40
	v_and_b32_e32 v217, 0xffff0000, v40
	v_lshlrev_b32_e32 v218, 16, v41
	v_and_b32_e32 v219, 0xffff0000, v41
	v_mul_f32_e32 v216, v225, v216
	v_mul_f32_e32 v217, v225, v217
	v_mul_f32_e32 v218, v225, v218
	v_mul_f32_e32 v219, v225, v219
	v_fmac_f32_e32 v16, v112, v216
	v_fmac_f32_e32 v17, v113, v217
	v_fmac_f32_e32 v18, v114, v218
	v_fmac_f32_e32 v19, v115, v219
	v_lshlrev_b32_e32 v216, 16, v42
	v_and_b32_e32 v217, 0xffff0000, v42
	v_lshlrev_b32_e32 v218, 16, v43
	v_and_b32_e32 v219, 0xffff0000, v43
	v_mul_f32_e32 v216, v225, v216
	v_mul_f32_e32 v217, v225, v217
	v_mul_f32_e32 v218, v225, v218
	v_mul_f32_e32 v219, v225, v219
	v_fmac_f32_e32 v20, v116, v216
	v_fmac_f32_e32 v21, v117, v217
	v_fmac_f32_e32 v22, v118, v218
	v_fmac_f32_e32 v23, v119, v219
	v_lshlrev_b32_e32 v216, 16, v44
	v_and_b32_e32 v217, 0xffff0000, v44
	v_lshlrev_b32_e32 v218, 16, v45
	v_and_b32_e32 v219, 0xffff0000, v45
	v_mul_f32_e32 v216, v225, v216
	v_mul_f32_e32 v217, v225, v217
	v_mul_f32_e32 v218, v225, v218
	v_mul_f32_e32 v219, v225, v219
	v_fmac_f32_e32 v24, v120, v216
	v_fmac_f32_e32 v25, v121, v217
	v_fmac_f32_e32 v26, v122, v218
; __device__ __forceinline__ unsigned cvt_pk_bf16(float lo, float hi) { unsigned r; asm volatile("v_cvt_pk_bf16_f32 %0, %1, %2" : "=v"(r) : "v"(lo), "v"(hi)); return r; }
; __device__ __forceinline__ void modulate_store(const f32x4 (&v)[8], float rstd, const float* pn, const float* modr, bf16_t* orow, int lane) {
; #pragma unroll
;     for (int j = 0; j < 8; ++j) { const int col = 4 * lane + 256 * j;
;         const f32x4 g = *(const f32x4*)(pn + col), sh = *(const f32x4*)(modr + col), sc = *(const f32x4*)(modr + DM + col);
;         const f32x4 hh = v[j] * rstd * g * (sc + 1.f) + sh;
;         u32x2 w; w.x = cvt_pk_bf16(hh[0], hh[1]); w.y = cvt_pk_bf16(hh[2], hh[3]);
;         *(u32x2*)(orow + col) = w; }
; __global__ void __launch_bounds__(NWAVES * 64, 2) mk_fwd(Args args) {
;     ...
;                     v[q][j] = v[q][j] + gt * (y4 * rsy * pn);
;                     if (lat) *(f32x4*)(args.out + (size_t)row * DM + col) = v[q][j]; }
;                 const float rstd = __builtin_amdgcn_rsqf(sumsq8(v[q]) * (1.f / DM) + EPS);
;                 modulate_store(v[q], rstd, pre_norm + DM, mod + (size_t)(9 + r) * 6144, H + (size_t)row * DM, F.lane); }
	v_fmac_f32_e32 v27, v123, v219
	v_lshlrev_b32_e32 v216, 16, v46
	v_and_b32_e32 v217, 0xffff0000, v46
	v_lshlrev_b32_e32 v218, 16, v47
	v_and_b32_e32 v219, 0xffff0000, v47
	v_mul_f32_e32 v216, v225, v216
	v_mul_f32_e32 v217, v225, v217
	v_mul_f32_e32 v218, v225, v218
	v_mul_f32_e32 v219, v225, v219
	v_fmac_f32_e32 v28, v124, v216
	v_fmac_f32_e32 v29, v125, v217
	v_fmac_f32_e32 v30, v126, v218
	v_fmac_f32_e32 v31, v127, v219
	v_mul_f32_e32 v222, v0, v0
	v_mul_f32_e32 v223, v1, v1
	v_fmac_f32_e32 v222, v2, v2
	v_fmac_f32_e32 v223, v3, v3
	v_fmac_f32_e32 v222, v4, v4
	v_fmac_f32_e32 v223, v5, v5
	v_fmac_f32_e32 v222, v6, v6
	v_fmac_f32_e32 v223, v7, v7
	v_fmac_f32_e32 v222, v8, v8
	v_fmac_f32_e32 v223, v9, v9
	v_fmac_f32_e32 v222, v10, v10
	v_fmac_f32_e32 v223, v11, v11
	v_fmac_f32_e32 v222, v12, v12
	v_fmac_f32_e32 v223, v13, v13
	v_fmac_f32_e32 v222, v14, v14
	v_fmac_f32_e32 v223, v15, v15
	v_fmac_f32_e32 v222, v16, v16
	v_fmac_f32_e32 v223, v17, v17
	v_fmac_f32_e32 v222, v18, v18
	v_fmac_f32_e32 v223, v19, v19
	v_fmac_f32_e32 v222, v20, v20
	v_fmac_f32_e32 v223, v21, v21
	v_fmac_f32_e32 v222, v22, v22
	v_fmac_f32_e32 v223, v23, v23
	v_fmac_f32_e32 v222, v24, v24
	v_fmac_f32_e32 v223, v25, v25
	v_fmac_f32_e32 v222, v26, v26
	v_fmac_f32_e32 v223, v27, v27
	v_fmac_f32_e32 v222, v28, v28
	v_fmac_f32_e32 v223, v29, v29
	v_fmac_f32_e32 v222, v30, v30
	v_fmac_f32_e32 v223, v31, v31
	v_add_f32_e32 v222, v222, v223
	s_nop 1
	v_add_f32_dpp v224, v222, v222 quad_perm:[1,0,3,2] row_mask:0xf bank_mask:0xf
	s_nop 1
	v_add_f32_dpp v224, v224, v224 quad_perm:[2,3,0,1] row_mask:0xf bank_mask:0xf
	s_nop 1
	v_add_f32_dpp v224, v224, v224 row_half_mirror row_mask:0xf bank_mask:0xf
	s_nop 1
	v_add_f32_dpp v224, v224, v224 row_mirror row_mask:0xf bank_mask:0xf
	s_nop 1
	v_readlane_b32 s40, v224, 0
	v_readlane_b32 s41, v224, 16
	v_readlane_b32 s42, v224, 32
	v_readlane_b32 s43, v224, 48
	s_nop 1
	v_mov_b32_e32 v225, s40
	v_add_f32_e32 v225, s41, v225
	v_add_f32_e32 v225, s42, v225
	v_add_f32_e32 v225, s43, v225
	v_fmamk_f32 v225, v225, 0x3a000000, v195
	v_rsq_f32_e32 v225, v225
	s_nop 0
	s_add_i32 s0, s6, 0
	s_lshl_b32 s1, s0, 12
	s_add_u32 s26, s84, s1
	s_addc_u32 s27, s85, 0
	s_add_u32 s26, s26, 0xd000000
	s_addc_u32 s27, s27, 0
	v_mul_f32_e32 v216, v225, v0
	v_mul_f32_e32 v217, v225, v1
	v_mul_f32_e32 v218, v225, v2
	v_mul_f32_e32 v219, v225, v3
	v_fma_f32 v216, v216, v128, v160
	v_fma_f32 v217, v217, v129, v161
	v_fma_f32 v218, v218, v130, v162
	v_fma_f32 v219, v219, v131, v163
	v_cvt_pk_bf16_f32 v196, v216, v217
	v_cvt_pk_bf16_f32 v197, v218, v219
	global_store_dwordx2 v194, v[196:197], s[26:27] offset:0
	v_mul_f32_e32 v216, v225, v4
	v_mul_f32_e32 v217, v225, v5
	v_mul_f32_e32 v218, v225, v6
	v_mul_f32_e32 v219, v225, v7
	v_fma_f32 v216, v216, v132, v164
	v_fma_f32 v217, v217, v133, v165
	v_fma_f32 v218, v218, v134, v166
	v_fma_f32 v219, v219, v135, v167
	v_cvt_pk_bf16_f32 v220, v216, v217
	v_cvt_pk_bf16_f32 v221, v218, v219
	global_store_dwordx2 v194, v[220:221], s[26:27] offset:512
	v_mul_f32_e32 v216, v225, v8
	v_mul_f32_e32 v217, v225, v9
	v_mul_f32_e32 v218, v225, v10
	v_mul_f32_e32 v219, v225, v11
	v_fma_f32 v216, v216, v136, v168
	v_fma_f32 v217, v217, v137, v169
	v_fma_f32 v218, v218, v138, v170
	v_fma_f32 v219, v219, v139, v171
	v_cvt_pk_bf16_f32 v196, v216, v217
	v_cvt_pk_bf16_f32 v197, v218, v219
	global_store_dwordx2 v194, v[196:197], s[26:27] offset:1024
	v_mul_f32_e32 v216, v225, v12
	v_mul_f32_e32 v217, v225, v13
	v_mul_f32_e32 v218, v225, v14
	v_mul_f32_e32 v219, v225, v15
	v_fma_f32 v216, v216, v140, v172
	v_fma_f32 v217, v217, v141, v173
	v_fma_f32 v218, v218, v142, v174
	v_fma_f32 v219, v219, v143, v175
	v_cvt_pk_bf16_f32 v220, v216, v217
	v_cvt_pk_bf16_f32 v221, v218, v219
	global_store_dwordx2 v194, v[220:221], s[26:27] offset:1536
	v_mul_f32_e32 v216, v225, v16
	v_mul_f32_e32 v217, v225, v17
	v_mul_f32_e32 v218, v225, v18
	v_mul_f32_e32 v219, v225, v19
	v_fma_f32 v216, v216, v144, v176
	v_fma_f32 v217, v217, v145, v177
	v_fma_f32 v218, v218, v146, v178
	v_fma_f32 v219, v219, v147, v179
	v_cvt_pk_bf16_f32 v196, v216, v217
	v_cvt_pk_bf16_f32 v197, v218, v219
	global_store_dwordx2 v194, v[196:197], s[26:27] offset:2048
	v_mul_f32_e32 v216, v225, v20
	v_mul_f32_e32 v217, v225, v21
	v_mul_f32_e32 v218, v225, v22
	v_mul_f32_e32 v219, v225, v23
	v_fma_f32 v216, v216, v148, v180
	v_fma_f32 v217, v217, v149, v181
	v_fma_f32 v218, v218, v150, v182
	v_fma_f32 v219, v219, v151, v183
	v_cvt_pk_bf16_f32 v220, v216, v217
	v_cvt_pk_bf16_f32 v221, v218, v219
	global_store_dwordx2 v194, v[220:221], s[26:27] offset:2560
	v_mul_f32_e32 v216, v225, v24
	v_mul_f32_e32 v217, v225, v25
	v_mul_f32_e32 v218, v225, v26
	v_mul_f32_e32 v219, v225, v27
	v_fma_f32 v216, v216, v152, v184
	v_fma_f32 v217, v217, v153, v185
	v_fma_f32 v218, v218, v154, v186
	v_fma_f32 v219, v219, v155, v187
	v_cvt_pk_bf16_f32 v196, v216, v217
	v_cvt_pk_bf16_f32 v197, v218, v219
	global_store_dwordx2 v194, v[196:197], s[26:27] offset:3072
	v_mul_f32_e32 v216, v225, v28
	v_mul_f32_e32 v217, v225, v29
	v_mul_f32_e32 v218, v225, v30
	v_mul_f32_e32 v219, v225, v31
	v_fma_f32 v216, v216, v156, v188
	v_fma_f32 v217, v217, v157, v189
	v_fma_f32 v218, v218, v158, v190
	v_fma_f32 v219, v219, v159, v191
	v_cvt_pk_bf16_f32 v220, v216, v217
	v_cvt_pk_bf16_f32 v221, v218, v219
	global_store_dwordx2 v194, v[220:221], s[26:27] offset:3584
	s_add_i32 s0, s6, 2
	s_cmp_lt_u32 s0, 0x4000
	s_cselect_b32 s10, s68, s72
	s_cselect_b32 s11, s69, s73
	s_cselect_b32 s1, 0, 0x4000
	s_sub_i32 s1, s0, s1
	s_lshl_b32 s1, s1, 13
	s_add_u32 s10, s10, s1
	s_addc_u32 s11, s11, 0
	s_add_i32 s0, s6, 2
	s_lshl_b32 s1, s0, 12
	s_add_u32 s22, s84, s1
	s_addc_u32 s23, s85, 0
	s_add_u32 s22, s22, 0x11800000
	s_addc_u32 s23, s23, 0
	global_load_dwordx4 v[0:3], v192, s[10:11] offset:0 nt
	global_load_dwordx4 v[4:7], v192, s[10:11] offset:1024 nt
	global_load_dwordx4 v[8:11], v192, s[10:11] offset:2048 nt
	global_load_dwordx4 v[12:15], v192, s[10:11] offset:3072 nt
	global_load_dwordx4 v[16:19], v193, s[10:11] offset:0 nt
	global_load_dwordx4 v[20:23], v193, s[10:11] offset:1024 nt
	global_load_dwordx4 v[24:27], v193, s[10:11] offset:2048 nt
	global_load_dwordx4 v[28:31], v193, s[10:11] offset:3072 nt
	global_load_dwordx2 v[32:33], v194, s[22:23] offset:0 nt
	global_load_dwordx2 v[34:35], v194, s[22:23] offset:512 nt
	global_load_dwordx2 v[36:37], v194, s[22:23] offset:1024 nt
	global_load_dwordx2 v[38:39], v194, s[22:23] offset:1536 nt
	global_load_dwordx2 v[40:41], v194, s[22:23] offset:2048 nt
	global_load_dwordx2 v[42:43], v194, s[22:23] offset:2560 nt
	global_load_dwordx2 v[44:45], v194, s[22:23] offset:3072 nt
	global_load_dwordx2 v[46:47], v194, s[22:23] offset:3584 nt
	s_add_i32 s0, s6, 1
	s_add_i32 s0, s6, 1
	s_lshr_b32 s8, s0, 11
	s_cmp_lt_u32 s0, 0x4000
	s_cselect_b32 s8, s8, 8
	s_cmp_eq_u32 s8, s7
	s_cbranch_scc1 .Lp6_np1
; __device__ __forceinline__ void modulate_store(const f32x4 (&v)[8], float rstd, const float* pn, const float* modr, bf16_t* orow, int lane) {
; #pragma unroll
;     for (int j = 0; j < 8; ++j) { const int col = 4 * lane + 256 * j;
;         const f32x4 g = *(const f32x4*)(pn + col), sh = *(const f32x4*)(modr + col), sc = *(const f32x4*)(modr + DM + col);
; __global__ void __launch_bounds__(NWAVES * 64, 2) mk_fwd(Args args) {
;     ...
;                 const float* m0 = mod + (size_t)r * 6144;
; #pragma unroll
;                 for (int j = 0; j < 8; ++j) { const int col = 4 * F.lane + 256 * j; const f32x4 gt = *(const f32x4*)(m0 + 2 * DM + col), pn = *(const f32x4*)(post_norm + col);
	s_mov_b32 s7, s8
	s_add_i32 s1, s8, 9
	s_mul_i32 s1, s1, 0x6000
	s_add_u32 s44, s84, s1
	s_addc_u32 s45, s85, 0
	s_add_u32 s44, s44, 0x2000
	s_addc_u32 s45, s45, 0
	s_add_i32 s1, s8, 9
	s_mul_i32 s1, s1, 0x6000
	s_add_u32 s36, s84, s1
	s_addc_u32 s37, s85, 0
	s_add_u32 s38, s80, 0x2000
	s_addc_u32 s39, s81, 0
	s_mul_i32 s1, s8, 0x6000
	s_add_u32 s34, s84, s1
	s_addc_u32 s35, s85, 0
	s_add_u32 s34, s34, 0x4000
	s_addc_u32 s35, s35, 0
	global_load_dwordx4 v[96:99], v192, s[34:35] offset:0
	global_load_dwordx4 v[200:203], v192, s[82:83] offset:0
	global_load_dwordx4 v[100:103], v192, s[34:35] offset:1024
	global_load_dwordx4 v[204:207], v192, s[82:83] offset:1024
	global_load_dwordx4 v[104:107], v192, s[34:35] offset:2048
	global_load_dwordx4 v[208:211], v192, s[82:83] offset:2048
	global_load_dwordx4 v[108:111], v192, s[34:35] offset:3072
	global_load_dwordx4 v[212:215], v192, s[82:83] offset:3072
	s_waitcnt vmcnt(0)
	v_mul_f32_e32 v96, v96, v200
	v_mul_f32_e32 v97, v97, v201
	v_mul_f32_e32 v98, v98, v202
	v_mul_f32_e32 v99, v99, v203
	v_mul_f32_e32 v100, v100, v204
	v_mul_f32_e32 v101, v101, v205
	v_mul_f32_e32 v102, v102, v206
	v_mul_f32_e32 v103, v103, v207
	v_mul_f32_e32 v104, v104, v208
	v_mul_f32_e32 v105, v105, v209
	v_mul_f32_e32 v106, v106, v210
	v_mul_f32_e32 v107, v107, v211
	v_mul_f32_e32 v108, v108, v212
	v_mul_f32_e32 v109, v109, v213
	v_mul_f32_e32 v110, v110, v214
	v_mul_f32_e32 v111, v111, v215
	global_load_dwordx4 v[128:131], v192, s[38:39] offset:0
	global_load_dwordx4 v[200:203], v192, s[44:45] offset:0
	global_load_dwordx4 v[160:163], v192, s[36:37] offset:0
	global_load_dwordx4 v[132:135], v192, s[38:39] offset:1024
	global_load_dwordx4 v[204:207], v192, s[44:45] offset:1024
	global_load_dwordx4 v[164:167], v192, s[36:37] offset:1024
	global_load_dwordx4 v[136:139], v192, s[38:39] offset:2048
	global_load_dwordx4 v[208:211], v192, s[44:45] offset:2048
	global_load_dwordx4 v[168:171], v192, s[36:37] offset:2048
	global_load_dwordx4 v[140:143], v192, s[38:39] offset:3072
	global_load_dwordx4 v[212:215], v192, s[44:45] offset:3072
	global_load_dwordx4 v[172:175], v192, s[36:37] offset:3072
	s_waitcnt vmcnt(0)
	v_add_f32_e32 v200, 1.0, v200
	v_add_f32_e32 v201, 1.0, v201
	v_add_f32_e32 v202, 1.0, v202
	v_add_f32_e32 v203, 1.0, v203
	v_mul_f32_e32 v128, v128, v200
	v_mul_f32_e32 v129, v129, v201
	v_mul_f32_e32 v130, v130, v202
	v_mul_f32_e32 v131, v131, v203
	v_add_f32_e32 v204, 1.0, v204
	v_add_f32_e32 v205, 1.0, v205
	v_add_f32_e32 v206, 1.0, v206
	v_add_f32_e32 v207, 1.0, v207
	v_mul_f32_e32 v132, v132, v204
	v_mul_f32_e32 v133, v133, v205
	v_mul_f32_e32 v134, v134, v206
	v_mul_f32_e32 v135, v135, v207
	v_add_f32_e32 v208, 1.0, v208
	v_add_f32_e32 v209, 1.0, v209
	v_add_f32_e32 v210, 1.0, v210
	v_add_f32_e32 v211, 1.0, v211
	v_mul_f32_e32 v136, v136, v208
	v_mul_f32_e32 v137, v137, v209
	v_mul_f32_e32 v138, v138, v210
	v_mul_f32_e32 v139, v139, v211
	v_add_f32_e32 v212, 1.0, v212
	v_add_f32_e32 v213, 1.0, v213
	v_add_f32_e32 v214, 1.0, v214
	v_add_f32_e32 v215, 1.0, v215
	v_mul_f32_e32 v140, v140, v212
	v_mul_f32_e32 v141, v141, v213
	v_mul_f32_e32 v142, v142, v214
	v_mul_f32_e32 v143, v143, v215
	global_load_dwordx4 v[112:115], v193, s[34:35] offset:0
	global_load_dwordx4 v[200:203], v193, s[82:83] offset:0
	global_load_dwordx4 v[116:119], v193, s[34:35] offset:1024
	global_load_dwordx4 v[204:207], v193, s[82:83] offset:1024
	global_load_dwordx4 v[120:123], v193, s[34:35] offset:2048
	global_load_dwordx4 v[208:211], v193, s[82:83] offset:2048
	global_load_dwordx4 v[124:127], v193, s[34:35] offset:3072
	global_load_dwordx4 v[212:215], v193, s[82:83] offset:3072
	s_waitcnt vmcnt(0)
	v_mul_f32_e32 v112, v112, v200
	v_mul_f32_e32 v113, v113, v201
	v_mul_f32_e32 v114, v114, v202
	v_mul_f32_e32 v115, v115, v203
	v_mul_f32_e32 v116, v116, v204
	v_mul_f32_e32 v117, v117, v205
	v_mul_f32_e32 v118, v118, v206
	v_mul_f32_e32 v119, v119, v207
	v_mul_f32_e32 v120, v120, v208
	v_mul_f32_e32 v121, v121, v209
	v_mul_f32_e32 v122, v122, v210
	v_mul_f32_e32 v123, v123, v211
	v_mul_f32_e32 v124, v124, v212
	v_mul_f32_e32 v125, v125, v213
	v_mul_f32_e32 v126, v126, v214
	v_mul_f32_e32 v127, v127, v215
	global_load_dwordx4 v[144:147], v193, s[38:39] offset:0
	global_load_dwordx4 v[200:203], v193, s[44:45] offset:0
	global_load_dwordx4 v[176:179], v193, s[36:37] offset:0
	global_load_dwordx4 v[148:151], v193, s[38:39] offset:1024
	global_load_dwordx4 v[204:207], v193, s[44:45] offset:1024
	global_load_dwordx4 v[180:183], v193, s[36:37] offset:1024
	global_load_dwordx4 v[152:155], v193, s[38:39] offset:2048
	global_load_dwordx4 v[208:211], v193, s[44:45] offset:2048
	global_load_dwordx4 v[184:187], v193, s[36:37] offset:2048
	global_load_dwordx4 v[156:159], v193, s[38:39] offset:3072
	global_load_dwordx4 v[212:215], v193, s[44:45] offset:3072
	global_load_dwordx4 v[188:191], v193, s[36:37] offset:3072
	s_waitcnt vmcnt(0)
	v_add_f32_e32 v200, 1.0, v200
	v_add_f32_e32 v201, 1.0, v201
	v_add_f32_e32 v202, 1.0, v202
	v_add_f32_e32 v203, 1.0, v203
	v_mul_f32_e32 v144, v144, v200
	v_mul_f32_e32 v145, v145, v201
	v_mul_f32_e32 v146, v146, v202
	v_mul_f32_e32 v147, v147, v203
	v_add_f32_e32 v204, 1.0, v204
	v_add_f32_e32 v205, 1.0, v205
	v_add_f32_e32 v206, 1.0, v206
	v_add_f32_e32 v207, 1.0, v207
	v_mul_f32_e32 v148, v148, v204
	v_mul_f32_e32 v149, v149, v205
	v_mul_f32_e32 v150, v150, v206
	v_mul_f32_e32 v151, v151, v207
	v_add_f32_e32 v208, 1.0, v208
	v_add_f32_e32 v209, 1.0, v209
	v_add_f32_e32 v210, 1.0, v210
	v_add_f32_e32 v211, 1.0, v211
	v_mul_f32_e32 v152, v152, v208
	v_mul_f32_e32 v153, v153, v209
	v_mul_f32_e32 v154, v154, v210
	v_mul_f32_e32 v155, v155, v211
	v_add_f32_e32 v212, 1.0, v212
	v_add_f32_e32 v213, 1.0, v213
	v_add_f32_e32 v214, 1.0, v214
	v_add_f32_e32 v215, 1.0, v215
	v_mul_f32_e32 v156, v156, v212
	v_mul_f32_e32 v157, v157, v213
	v_mul_f32_e32 v158, v158, v214
	v_mul_f32_e32 v159, v159, v215
; __device__ __forceinline__ float bf_lo(unsigned w) { return __uint_as_float(w << 16); }
; __device__ __forceinline__ float bf_hi(unsigned w) { return __uint_as_float(w & 0xffff0000u); }
; __global__ void __launch_bounds__(NWAVES * 64, 2) mk_fwd(Args args) {
;     ...
;             for (int q = 0; q < 3; ++q) { const int row = row0 + q; const bool lat = row < ML; const int r = lat ? row / SEQ : 8;
;                 float sy = 0.f;
; #pragma unroll
;                 for (int j = 0; j < 8; ++j) { const float a = bf_lo(yw[q][j].x), b = bf_hi(yw[q][j].x), c2 = bf_lo(yw[q][j].y), d = bf_hi(yw[q][j].y); sy += (a * a + b * b) + (c2 * c2 + d * d); }
;                 const float rsy = __builtin_amdgcn_rsqf(wave_sum(sy) * (1.f / DM) + EPS);
;                 const float* m0 = mod + (size_t)r * 6144;
; #pragma unroll
;                 for (int j = 0; j < 8; ++j) { const int col = 4 * F.lane + 256 * j; const f32x4 gt = *(const f32x4*)(m0 + 2 * DM + col), pn = *(const f32x4*)(post_norm + col);
;                     const f32x4 y4 = (f32x4){bf_lo(yw[q][j].x), bf_hi(yw[q][j].x), bf_lo(yw[q][j].y), bf_hi(yw[q][j].y)};
;                     v[q][j] = v[q][j] + gt * (y4 * rsy * pn);
.Lp6_np1:
	s_waitcnt vmcnt(24)
	v_lshlrev_b32_e32 v216, 16, v80
	v_and_b32_e32 v217, 0xffff0000, v80
	v_lshlrev_b32_e32 v218, 16, v81
	v_and_b32_e32 v219, 0xffff0000, v81
	v_mul_f32_e32 v222, v216, v216
	v_mul_f32_e32 v223, v217, v217
	v_fmac_f32_e32 v222, v218, v218
	v_fmac_f32_e32 v223, v219, v219
	v_lshlrev_b32_e32 v216, 16, v82
	v_and_b32_e32 v217, 0xffff0000, v82
	v_lshlrev_b32_e32 v218, 16, v83
	v_and_b32_e32 v219, 0xffff0000, v83
	v_fmac_f32_e32 v222, v216, v216
	v_fmac_f32_e32 v223, v217, v217
	v_fmac_f32_e32 v222, v218, v218
	v_fmac_f32_e32 v223, v219, v219
	v_lshlrev_b32_e32 v216, 16, v84
	v_and_b32_e32 v217, 0xffff0000, v84
	v_lshlrev_b32_e32 v218, 16, v85
	v_and_b32_e32 v219, 0xffff0000, v85
	v_fmac_f32_e32 v222, v216, v216
	v_fmac_f32_e32 v223, v217, v217
	v_fmac_f32_e32 v222, v218, v218
	v_fmac_f32_e32 v223, v219, v219
	v_lshlrev_b32_e32 v216, 16, v86
	v_and_b32_e32 v217, 0xffff0000, v86
	v_lshlrev_b32_e32 v218, 16, v87
	v_and_b32_e32 v219, 0xffff0000, v87
	v_fmac_f32_e32 v222, v216, v216
	v_fmac_f32_e32 v223, v217, v217
	v_fmac_f32_e32 v222, v218, v218
	v_fmac_f32_e32 v223, v219, v219
	v_lshlrev_b32_e32 v216, 16, v88
	v_and_b32_e32 v217, 0xffff0000, v88
	v_lshlrev_b32_e32 v218, 16, v89
	v_and_b32_e32 v219, 0xffff0000, v89
	v_fmac_f32_e32 v222, v216, v216
	v_fmac_f32_e32 v223, v217, v217
	v_fmac_f32_e32 v222, v218, v218
	v_fmac_f32_e32 v223, v219, v219
	v_lshlrev_b32_e32 v216, 16, v90
	v_and_b32_e32 v217, 0xffff0000, v90
	v_lshlrev_b32_e32 v218, 16, v91
	v_and_b32_e32 v219, 0xffff0000, v91
	v_fmac_f32_e32 v222, v216, v216
	v_fmac_f32_e32 v223, v217, v217
	v_fmac_f32_e32 v222, v218, v218
	v_fmac_f32_e32 v223, v219, v219
	v_lshlrev_b32_e32 v216, 16, v92
	v_and_b32_e32 v217, 0xffff0000, v92
	v_lshlrev_b32_e32 v218, 16, v93
	v_and_b32_e32 v219, 0xffff0000, v93
	v_fmac_f32_e32 v222, v216, v216
	v_fmac_f32_e32 v223, v217, v217
	v_fmac_f32_e32 v222, v218, v218
	v_fmac_f32_e32 v223, v219, v219
	v_lshlrev_b32_e32 v216, 16, v94
	v_and_b32_e32 v217, 0xffff0000, v94
	v_lshlrev_b32_e32 v218, 16, v95
	v_and_b32_e32 v219, 0xffff0000, v95
	v_fmac_f32_e32 v222, v216, v216
	v_fmac_f32_e32 v223, v217, v217
	v_fmac_f32_e32 v222, v218, v218
	v_fmac_f32_e32 v223, v219, v219
	v_add_f32_e32 v222, v222, v223
	s_nop 1
	v_add_f32_dpp v224, v222, v222 quad_perm:[1,0,3,2] row_mask:0xf bank_mask:0xf
	s_nop 1
	v_add_f32_dpp v224, v224, v224 quad_perm:[2,3,0,1] row_mask:0xf bank_mask:0xf
	s_nop 1
	v_add_f32_dpp v224, v224, v224 row_half_mirror row_mask:0xf bank_mask:0xf
	s_nop 1
	v_add_f32_dpp v224, v224, v224 row_mirror row_mask:0xf bank_mask:0xf
	s_nop 1
	v_readlane_b32 s40, v224, 0
	v_readlane_b32 s41, v224, 16
	v_readlane_b32 s42, v224, 32
	v_readlane_b32 s43, v224, 48
	s_nop 1
	v_mov_b32_e32 v225, s40
	v_add_f32_e32 v225, s41, v225
	v_add_f32_e32 v225, s42, v225
	v_add_f32_e32 v225, s43, v225
	v_fmamk_f32 v225, v225, 0x3a000000, v195
	v_rsq_f32_e32 v225, v225
	s_nop 0
	v_lshlrev_b32_e32 v216, 16, v80
	v_and_b32_e32 v217, 0xffff0000, v80
	v_lshlrev_b32_e32 v218, 16, v81
	v_and_b32_e32 v219, 0xffff0000, v81
	v_mul_f32_e32 v216, v225, v216
	v_mul_f32_e32 v217, v225, v217
	v_mul_f32_e32 v218, v225, v218
	v_mul_f32_e32 v219, v225, v219
	v_fmac_f32_e32 v48, v96, v216
	v_fmac_f32_e32 v49, v97, v217
	v_fmac_f32_e32 v50, v98, v218
	v_fmac_f32_e32 v51, v99, v219
	v_lshlrev_b32_e32 v216, 16, v82
	v_and_b32_e32 v217, 0xffff0000, v82
	v_lshlrev_b32_e32 v218, 16, v83
	v_and_b32_e32 v219, 0xffff0000, v83
	v_mul_f32_e32 v216, v225, v216
	v_mul_f32_e32 v217, v225, v217
	v_mul_f32_e32 v218, v225, v218
	v_mul_f32_e32 v219, v225, v219
	v_fmac_f32_e32 v52, v100, v216
	v_fmac_f32_e32 v53, v101, v217
	v_fmac_f32_e32 v54, v102, v218
	v_fmac_f32_e32 v55, v103, v219
	v_lshlrev_b32_e32 v216, 16, v84
	v_and_b32_e32 v217, 0xffff0000, v84
	v_lshlrev_b32_e32 v218, 16, v85
	v_and_b32_e32 v219, 0xffff0000, v85
	v_mul_f32_e32 v216, v225, v216
	v_mul_f32_e32 v217, v225, v217
	v_mul_f32_e32 v218, v225, v218
	v_mul_f32_e32 v219, v225, v219
	v_fmac_f32_e32 v56, v104, v216
	v_fmac_f32_e32 v57, v105, v217
	v_fmac_f32_e32 v58, v106, v218
	v_fmac_f32_e32 v59, v107, v219
	v_lshlrev_b32_e32 v216, 16, v86
	v_and_b32_e32 v217, 0xffff0000, v86
	v_lshlrev_b32_e32 v218, 16, v87
	v_and_b32_e32 v219, 0xffff0000, v87
	v_mul_f32_e32 v216, v225, v216
	v_mul_f32_e32 v217, v225, v217
	v_mul_f32_e32 v218, v225, v218
	v_mul_f32_e32 v219, v225, v219
	v_fmac_f32_e32 v60, v108, v216
	v_fmac_f32_e32 v61, v109, v217
	v_fmac_f32_e32 v62, v110, v218
	v_fmac_f32_e32 v63, v111, v219
	v_lshlrev_b32_e32 v216, 16, v88
	v_and_b32_e32 v217, 0xffff0000, v88
	v_lshlrev_b32_e32 v218, 16, v89
	v_and_b32_e32 v219, 0xffff0000, v89
	v_mul_f32_e32 v216, v225, v216
	v_mul_f32_e32 v217, v225, v217
	v_mul_f32_e32 v218, v225, v218
	v_mul_f32_e32 v219, v225, v219
	v_fmac_f32_e32 v64, v112, v216
	v_fmac_f32_e32 v65, v113, v217
	v_fmac_f32_e32 v66, v114, v218
	v_fmac_f32_e32 v67, v115, v219
	v_lshlrev_b32_e32 v216, 16, v90
	v_and_b32_e32 v217, 0xffff0000, v90
	v_lshlrev_b32_e32 v218, 16, v91
	v_and_b32_e32 v219, 0xffff0000, v91
	v_mul_f32_e32 v216, v225, v216
	v_mul_f32_e32 v217, v225, v217
	v_mul_f32_e32 v218, v225, v218
	v_mul_f32_e32 v219, v225, v219
	v_fmac_f32_e32 v68, v116, v216
	v_fmac_f32_e32 v69, v117, v217
	v_fmac_f32_e32 v70, v118, v218
	v_fmac_f32_e32 v71, v119, v219
	v_lshlrev_b32_e32 v216, 16, v92
	v_and_b32_e32 v217, 0xffff0000, v92
	v_lshlrev_b32_e32 v218, 16, v93
	v_and_b32_e32 v219, 0xffff0000, v93
	v_mul_f32_e32 v216, v225, v216
	v_mul_f32_e32 v217, v225, v217
	v_mul_f32_e32 v218, v225, v218
	v_mul_f32_e32 v219, v225, v219
	v_fmac_f32_e32 v72, v120, v216
	v_fmac_f32_e32 v73, v121, v217
	v_fmac_f32_e32 v74, v122, v218
; __device__ __forceinline__ unsigned cvt_pk_bf16(float lo, float hi) { unsigned r; asm volatile("v_cvt_pk_bf16_f32 %0, %1, %2" : "=v"(r) : "v"(lo), "v"(hi)); return r; }
; __device__ __forceinline__ void modulate_store(const f32x4 (&v)[8], float rstd, const float* pn, const float* modr, bf16_t* orow, int lane) {
; #pragma unroll
;     for (int j = 0; j < 8; ++j) { const int col = 4 * lane + 256 * j;
;         const f32x4 g = *(const f32x4*)(pn + col), sh = *(const f32x4*)(modr + col), sc = *(const f32x4*)(modr + DM + col);
;         const f32x4 hh = v[j] * rstd * g * (sc + 1.f) + sh;
;         u32x2 w; w.x = cvt_pk_bf16(hh[0], hh[1]); w.y = cvt_pk_bf16(hh[2], hh[3]);
;         *(u32x2*)(orow + col) = w; }
; __global__ void __launch_bounds__(NWAVES * 64, 2) mk_fwd(Args args) {
;     ...
;                     v[q][j] = v[q][j] + gt * (y4 * rsy * pn);
;                     if (lat) *(f32x4*)(args.out + (size_t)row * DM + col) = v[q][j]; }
;                 const float rstd = __builtin_amdgcn_rsqf(sumsq8(v[q]) * (1.f / DM) + EPS);
;                 modulate_store(v[q], rstd, pre_norm + DM, mod + (size_t)(9 + r) * 6144, H + (size_t)row * DM, F.lane); }
	v_fmac_f32_e32 v75, v123, v219
	v_lshlrev_b32_e32 v216, 16, v94
	v_and_b32_e32 v217, 0xffff0000, v94
	v_lshlrev_b32_e32 v218, 16, v95
	v_and_b32_e32 v219, 0xffff0000, v95
	v_mul_f32_e32 v216, v225, v216
	v_mul_f32_e32 v217, v225, v217
	v_mul_f32_e32 v218, v225, v218
	v_mul_f32_e32 v219, v225, v219
	v_fmac_f32_e32 v76, v124, v216
	v_fmac_f32_e32 v77, v125, v217
	v_fmac_f32_e32 v78, v126, v218
	v_fmac_f32_e32 v79, v127, v219
	v_mul_f32_e32 v222, v48, v48
	v_mul_f32_e32 v223, v49, v49
	v_fmac_f32_e32 v222, v50, v50
	v_fmac_f32_e32 v223, v51, v51
	v_fmac_f32_e32 v222, v52, v52
	v_fmac_f32_e32 v223, v53, v53
	v_fmac_f32_e32 v222, v54, v54
	v_fmac_f32_e32 v223, v55, v55
	v_fmac_f32_e32 v222, v56, v56
	v_fmac_f32_e32 v223, v57, v57
	v_fmac_f32_e32 v222, v58, v58
	v_fmac_f32_e32 v223, v59, v59
	v_fmac_f32_e32 v222, v60, v60
	v_fmac_f32_e32 v223, v61, v61
	v_fmac_f32_e32 v222, v62, v62
	v_fmac_f32_e32 v223, v63, v63
	v_fmac_f32_e32 v222, v64, v64
	v_fmac_f32_e32 v223, v65, v65
	v_fmac_f32_e32 v222, v66, v66
	v_fmac_f32_e32 v223, v67, v67
	v_fmac_f32_e32 v222, v68, v68
	v_fmac_f32_e32 v223, v69, v69
	v_fmac_f32_e32 v222, v70, v70
	v_fmac_f32_e32 v223, v71, v71
	v_fmac_f32_e32 v222, v72, v72
	v_fmac_f32_e32 v223, v73, v73
	v_fmac_f32_e32 v222, v74, v74
	v_fmac_f32_e32 v223, v75, v75
	v_fmac_f32_e32 v222, v76, v76
	v_fmac_f32_e32 v223, v77, v77
	v_fmac_f32_e32 v222, v78, v78
	v_fmac_f32_e32 v223, v79, v79
	v_add_f32_e32 v222, v222, v223
	s_nop 1
	v_add_f32_dpp v224, v222, v222 quad_perm:[1,0,3,2] row_mask:0xf bank_mask:0xf
	s_nop 1
	v_add_f32_dpp v224, v224, v224 quad_perm:[2,3,0,1] row_mask:0xf bank_mask:0xf
	s_nop 1
	v_add_f32_dpp v224, v224, v224 row_half_mirror row_mask:0xf bank_mask:0xf
	s_nop 1
	v_add_f32_dpp v224, v224, v224 row_mirror row_mask:0xf bank_mask:0xf
	s_nop 1
	v_readlane_b32 s40, v224, 0
	v_readlane_b32 s41, v224, 16
	v_readlane_b32 s42, v224, 32
	v_readlane_b32 s43, v224, 48
	s_nop 1
	v_mov_b32_e32 v225, s40
	v_add_f32_e32 v225, s41, v225
	v_add_f32_e32 v225, s42, v225
	v_add_f32_e32 v225, s43, v225
	v_fmamk_f32 v225, v225, 0x3a000000, v195
	v_rsq_f32_e32 v225, v225
	s_nop 0
	s_add_i32 s0, s6, 1
	s_lshl_b32 s1, s0, 12
	s_add_u32 s26, s84, s1
	s_addc_u32 s27, s85, 0
	s_add_u32 s26, s26, 0xd000000
	s_addc_u32 s27, s27, 0
	v_mul_f32_e32 v216, v225, v48
	v_mul_f32_e32 v217, v225, v49
	v_mul_f32_e32 v218, v225, v50
	v_mul_f32_e32 v219, v225, v51
	v_fma_f32 v216, v216, v128, v160
	v_fma_f32 v217, v217, v129, v161
	v_fma_f32 v218, v218, v130, v162
	v_fma_f32 v219, v219, v131, v163
	v_cvt_pk_bf16_f32 v196, v216, v217
	v_cvt_pk_bf16_f32 v197, v218, v219
	global_store_dwordx2 v194, v[196:197], s[26:27] offset:0
	v_mul_f32_e32 v216, v225, v52
	v_mul_f32_e32 v217, v225, v53
	v_mul_f32_e32 v218, v225, v54
	v_mul_f32_e32 v219, v225, v55
	v_fma_f32 v216, v216, v132, v164
	v_fma_f32 v217, v217, v133, v165
	v_fma_f32 v218, v218, v134, v166
	v_fma_f32 v219, v219, v135, v167
	v_cvt_pk_bf16_f32 v220, v216, v217
	v_cvt_pk_bf16_f32 v221, v218, v219
	global_store_dwordx2 v194, v[220:221], s[26:27] offset:512
	v_mul_f32_e32 v216, v225, v56
	v_mul_f32_e32 v217, v225, v57
	v_mul_f32_e32 v218, v225, v58
	v_mul_f32_e32 v219, v225, v59
	v_fma_f32 v216, v216, v136, v168
	v_fma_f32 v217, v217, v137, v169
	v_fma_f32 v218, v218, v138, v170
	v_fma_f32 v219, v219, v139, v171
	v_cvt_pk_bf16_f32 v196, v216, v217
	v_cvt_pk_bf16_f32 v197, v218, v219
	global_store_dwordx2 v194, v[196:197], s[26:27] offset:1024
	v_mul_f32_e32 v216, v225, v60
	v_mul_f32_e32 v217, v225, v61
	v_mul_f32_e32 v218, v225, v62
	v_mul_f32_e32 v219, v225, v63
	v_fma_f32 v216, v216, v140, v172
	v_fma_f32 v217, v217, v141, v173
	v_fma_f32 v218, v218, v142, v174
	v_fma_f32 v219, v219, v143, v175
	v_cvt_pk_bf16_f32 v220, v216, v217
	v_cvt_pk_bf16_f32 v221, v218, v219
	global_store_dwordx2 v194, v[220:221], s[26:27] offset:1536
	v_mul_f32_e32 v216, v225, v64
	v_mul_f32_e32 v217, v225, v65
	v_mul_f32_e32 v218, v225, v66
	v_mul_f32_e32 v219, v225, v67
	v_fma_f32 v216, v216, v144, v176
	v_fma_f32 v217, v217, v145, v177
	v_fma_f32 v218, v218, v146, v178
	v_fma_f32 v219, v219, v147, v179
	v_cvt_pk_bf16_f32 v196, v216, v217
	v_cvt_pk_bf16_f32 v197, v218, v219
	global_store_dwordx2 v194, v[196:197], s[26:27] offset:2048
	v_mul_f32_e32 v216, v225, v68
	v_mul_f32_e32 v217, v225, v69
	v_mul_f32_e32 v218, v225, v70
	v_mul_f32_e32 v219, v225, v71
	v_fma_f32 v216, v216, v148, v180
	v_fma_f32 v217, v217, v149, v181
	v_fma_f32 v218, v218, v150, v182
	v_fma_f32 v219, v219, v151, v183
	v_cvt_pk_bf16_f32 v220, v216, v217
	v_cvt_pk_bf16_f32 v221, v218, v219
	global_store_dwordx2 v194, v[220:221], s[26:27] offset:2560
	v_mul_f32_e32 v216, v225, v72
	v_mul_f32_e32 v217, v225, v73
	v_mul_f32_e32 v218, v225, v74
	v_mul_f32_e32 v219, v225, v75
	v_fma_f32 v216, v216, v152, v184
	v_fma_f32 v217, v217, v153, v185
	v_fma_f32 v218, v218, v154, v186
	v_fma_f32 v219, v219, v155, v187
	v_cvt_pk_bf16_f32 v196, v216, v217
	v_cvt_pk_bf16_f32 v197, v218, v219
	global_store_dwordx2 v194, v[196:197], s[26:27] offset:3072
	v_mul_f32_e32 v216, v225, v76
	v_mul_f32_e32 v217, v225, v77
	v_mul_f32_e32 v218, v225, v78
	v_mul_f32_e32 v219, v225, v79
	v_fma_f32 v216, v216, v156, v188
	v_fma_f32 v217, v217, v157, v189
	v_fma_f32 v218, v218, v158, v190
	v_fma_f32 v219, v219, v159, v191
	v_cvt_pk_bf16_f32 v220, v216, v217
	v_cvt_pk_bf16_f32 v221, v218, v219
	global_store_dwordx2 v194, v[220:221], s[26:27] offset:3584
	s_add_i32 s0, s6, 3
	s_cmp_lt_u32 s0, 0x4000
	s_cselect_b32 s10, s68, s72
	s_cselect_b32 s11, s69, s73
	s_cselect_b32 s1, 0, 0x4000
	s_sub_i32 s1, s0, s1
	s_lshl_b32 s1, s1, 13
	s_add_u32 s10, s10, s1
	s_addc_u32 s11, s11, 0
	s_add_i32 s0, s6, 3
	s_lshl_b32 s1, s0, 12
	s_add_u32 s22, s84, s1
	s_addc_u32 s23, s85, 0
	s_add_u32 s22, s22, 0x11800000
	s_addc_u32 s23, s23, 0
	global_load_dwordx4 v[48:51], v192, s[10:11] offset:0 nt
	global_load_dwordx4 v[52:55], v192, s[10:11] offset:1024 nt
	global_load_dwordx4 v[56:59], v192, s[10:11] offset:2048 nt
	global_load_dwordx4 v[60:63], v192, s[10:11] offset:3072 nt
	global_load_dwordx4 v[64:67], v193, s[10:11] offset:0 nt
	global_load_dwordx4 v[68:71], v193, s[10:11] offset:1024 nt
	global_load_dwordx4 v[72:75], v193, s[10:11] offset:2048 nt
	global_load_dwordx4 v[76:79], v193, s[10:11] offset:3072 nt
	global_load_dwordx2 v[80:81], v194, s[22:23] offset:0 nt
	global_load_dwordx2 v[82:83], v194, s[22:23] offset:512 nt
	global_load_dwordx2 v[84:85], v194, s[22:23] offset:1024 nt
	global_load_dwordx2 v[86:87], v194, s[22:23] offset:1536 nt
	global_load_dwordx2 v[88:89], v194, s[22:23] offset:2048 nt
	global_load_dwordx2 v[90:91], v194, s[22:23] offset:2560 nt
	global_load_dwordx2 v[92:93], v194, s[22:23] offset:3072 nt
	global_load_dwordx2 v[94:95], v194, s[22:23] offset:3584 nt
	s_add_i32 s0, s6, 2
	s_add_i32 s0, s6, 2
	s_lshr_b32 s8, s0, 11
	s_cmp_lt_u32 s0, 0x4000
	s_cselect_b32 s8, s8, 8
	s_cmp_eq_u32 s8, s7
	s_cbranch_scc1 .Lp6_np2
; __device__ __forceinline__ void modulate_store(const f32x4 (&v)[8], float rstd, const float* pn, const float* modr, bf16_t* orow, int lane) {
; #pragma unroll
;     for (int j = 0; j < 8; ++j) { const int col = 4 * lane + 256 * j;
;         const f32x4 g = *(const f32x4*)(pn + col), sh = *(const f32x4*)(modr + col), sc = *(const f32x4*)(modr + DM + col);
; __global__ void __launch_bounds__(NWAVES * 64, 2) mk_fwd(Args args) {
;     ...
;                 const float* m0 = mod + (size_t)r * 6144;
; #pragma unroll
;                 for (int j = 0; j < 8; ++j) { const int col = 4 * F.lane + 256 * j; const f32x4 gt = *(const f32x4*)(m0 + 2 * DM + col), pn = *(const f32x4*)(post_norm + col);
	s_mov_b32 s7, s8
	s_add_i32 s1, s8, 9
	s_mul_i32 s1, s1, 0x6000
	s_add_u32 s44, s84, s1
	s_addc_u32 s45, s85, 0
	s_add_u32 s44, s44, 0x2000
	s_addc_u32 s45, s45, 0
	s_add_i32 s1, s8, 9
	s_mul_i32 s1, s1, 0x6000
	s_add_u32 s36, s84, s1
	s_addc_u32 s37, s85, 0
	s_add_u32 s38, s80, 0x2000
	s_addc_u32 s39, s81, 0
	s_mul_i32 s1, s8, 0x6000
	s_add_u32 s34, s84, s1
	s_addc_u32 s35, s85, 0
	s_add_u32 s34, s34, 0x4000
	s_addc_u32 s35, s35, 0
	global_load_dwordx4 v[96:99], v192, s[34:35] offset:0
	global_load_dwordx4 v[200:203], v192, s[82:83] offset:0
	global_load_dwordx4 v[100:103], v192, s[34:35] offset:1024
	global_load_dwordx4 v[204:207], v192, s[82:83] offset:1024
	global_load_dwordx4 v[104:107], v192, s[34:35] offset:2048
	global_load_dwordx4 v[208:211], v192, s[82:83] offset:2048
	global_load_dwordx4 v[108:111], v192, s[34:35] offset:3072
	global_load_dwordx4 v[212:215], v192, s[82:83] offset:3072
	s_waitcnt vmcnt(0)
	v_mul_f32_e32 v96, v96, v200
	v_mul_f32_e32 v97, v97, v201
	v_mul_f32_e32 v98, v98, v202
	v_mul_f32_e32 v99, v99, v203
	v_mul_f32_e32 v100, v100, v204
	v_mul_f32_e32 v101, v101, v205
	v_mul_f32_e32 v102, v102, v206
	v_mul_f32_e32 v103, v103, v207
	v_mul_f32_e32 v104, v104, v208
	v_mul_f32_e32 v105, v105, v209
	v_mul_f32_e32 v106, v106, v210
	v_mul_f32_e32 v107, v107, v211
	v_mul_f32_e32 v108, v108, v212
	v_mul_f32_e32 v109, v109, v213
	v_mul_f32_e32 v110, v110, v214
	v_mul_f32_e32 v111, v111, v215
	global_load_dwordx4 v[128:131], v192, s[38:39] offset:0
	global_load_dwordx4 v[200:203], v192, s[44:45] offset:0
	global_load_dwordx4 v[160:163], v192, s[36:37] offset:0
	global_load_dwordx4 v[132:135], v192, s[38:39] offset:1024
	global_load_dwordx4 v[204:207], v192, s[44:45] offset:1024
	global_load_dwordx4 v[164:167], v192, s[36:37] offset:1024
	global_load_dwordx4 v[136:139], v192, s[38:39] offset:2048
	global_load_dwordx4 v[208:211], v192, s[44:45] offset:2048
	global_load_dwordx4 v[168:171], v192, s[36:37] offset:2048
	global_load_dwordx4 v[140:143], v192, s[38:39] offset:3072
	global_load_dwordx4 v[212:215], v192, s[44:45] offset:3072
	global_load_dwordx4 v[172:175], v192, s[36:37] offset:3072
	s_waitcnt vmcnt(0)
	v_add_f32_e32 v200, 1.0, v200
	v_add_f32_e32 v201, 1.0, v201
	v_add_f32_e32 v202, 1.0, v202
	v_add_f32_e32 v203, 1.0, v203
	v_mul_f32_e32 v128, v128, v200
	v_mul_f32_e32 v129, v129, v201
	v_mul_f32_e32 v130, v130, v202
	v_mul_f32_e32 v131, v131, v203
	v_add_f32_e32 v204, 1.0, v204
	v_add_f32_e32 v205, 1.0, v205
	v_add_f32_e32 v206, 1.0, v206
	v_add_f32_e32 v207, 1.0, v207
	v_mul_f32_e32 v132, v132, v204
	v_mul_f32_e32 v133, v133, v205
	v_mul_f32_e32 v134, v134, v206
	v_mul_f32_e32 v135, v135, v207
	v_add_f32_e32 v208, 1.0, v208
	v_add_f32_e32 v209, 1.0, v209
	v_add_f32_e32 v210, 1.0, v210
	v_add_f32_e32 v211, 1.0, v211
	v_mul_f32_e32 v136, v136, v208
	v_mul_f32_e32 v137, v137, v209
	v_mul_f32_e32 v138, v138, v210
	v_mul_f32_e32 v139, v139, v211
	v_add_f32_e32 v212, 1.0, v212
	v_add_f32_e32 v213, 1.0, v213
	v_add_f32_e32 v214, 1.0, v214
	v_add_f32_e32 v215, 1.0, v215
	v_mul_f32_e32 v140, v140, v212
	v_mul_f32_e32 v141, v141, v213
	v_mul_f32_e32 v142, v142, v214
	v_mul_f32_e32 v143, v143, v215
	global_load_dwordx4 v[112:115], v193, s[34:35] offset:0
	global_load_dwordx4 v[200:203], v193, s[82:83] offset:0
	global_load_dwordx4 v[116:119], v193, s[34:35] offset:1024
	global_load_dwordx4 v[204:207], v193, s[82:83] offset:1024
	global_load_dwordx4 v[120:123], v193, s[34:35] offset:2048
	global_load_dwordx4 v[208:211], v193, s[82:83] offset:2048
	global_load_dwordx4 v[124:127], v193, s[34:35] offset:3072
	global_load_dwordx4 v[212:215], v193, s[82:83] offset:3072
	s_waitcnt vmcnt(0)
	v_mul_f32_e32 v112, v112, v200
	v_mul_f32_e32 v113, v113, v201
	v_mul_f32_e32 v114, v114, v202
	v_mul_f32_e32 v115, v115, v203
	v_mul_f32_e32 v116, v116, v204
	v_mul_f32_e32 v117, v117, v205
	v_mul_f32_e32 v118, v118, v206
	v_mul_f32_e32 v119, v119, v207
	v_mul_f32_e32 v120, v120, v208
	v_mul_f32_e32 v121, v121, v209
	v_mul_f32_e32 v122, v122, v210
	v_mul_f32_e32 v123, v123, v211
	v_mul_f32_e32 v124, v124, v212
	v_mul_f32_e32 v125, v125, v213
	v_mul_f32_e32 v126, v126, v214
	v_mul_f32_e32 v127, v127, v215
	global_load_dwordx4 v[144:147], v193, s[38:39] offset:0
	global_load_dwordx4 v[200:203], v193, s[44:45] offset:0
	global_load_dwordx4 v[176:179], v193, s[36:37] offset:0
	global_load_dwordx4 v[148:151], v193, s[38:39] offset:1024
	global_load_dwordx4 v[204:207], v193, s[44:45] offset:1024
	global_load_dwordx4 v[180:183], v193, s[36:37] offset:1024
	global_load_dwordx4 v[152:155], v193, s[38:39] offset:2048
	global_load_dwordx4 v[208:211], v193, s[44:45] offset:2048
	global_load_dwordx4 v[184:187], v193, s[36:37] offset:2048
	global_load_dwordx4 v[156:159], v193, s[38:39] offset:3072
	global_load_dwordx4 v[212:215], v193, s[44:45] offset:3072
	global_load_dwordx4 v[188:191], v193, s[36:37] offset:3072
	s_waitcnt vmcnt(0)
	v_add_f32_e32 v200, 1.0, v200
	v_add_f32_e32 v201, 1.0, v201
	v_add_f32_e32 v202, 1.0, v202
	v_add_f32_e32 v203, 1.0, v203
	v_mul_f32_e32 v144, v144, v200
	v_mul_f32_e32 v145, v145, v201
	v_mul_f32_e32 v146, v146, v202
	v_mul_f32_e32 v147, v147, v203
	v_add_f32_e32 v204, 1.0, v204
	v_add_f32_e32 v205, 1.0, v205
	v_add_f32_e32 v206, 1.0, v206
	v_add_f32_e32 v207, 1.0, v207
	v_mul_f32_e32 v148, v148, v204
	v_mul_f32_e32 v149, v149, v205
	v_mul_f32_e32 v150, v150, v206
	v_mul_f32_e32 v151, v151, v207
	v_add_f32_e32 v208, 1.0, v208
	v_add_f32_e32 v209, 1.0, v209
	v_add_f32_e32 v210, 1.0, v210
	v_add_f32_e32 v211, 1.0, v211
	v_mul_f32_e32 v152, v152, v208
	v_mul_f32_e32 v153, v153, v209
	v_mul_f32_e32 v154, v154, v210
	v_mul_f32_e32 v155, v155, v211
	v_add_f32_e32 v212, 1.0, v212
	v_add_f32_e32 v213, 1.0, v213
	v_add_f32_e32 v214, 1.0, v214
	v_add_f32_e32 v215, 1.0, v215
	v_mul_f32_e32 v156, v156, v212
	v_mul_f32_e32 v157, v157, v213
	v_mul_f32_e32 v158, v158, v214
	v_mul_f32_e32 v159, v159, v215
; __device__ __forceinline__ float bf_lo(unsigned w) { return __uint_as_float(w << 16); }
; __device__ __forceinline__ float bf_hi(unsigned w) { return __uint_as_float(w & 0xffff0000u); }
; __global__ void __launch_bounds__(NWAVES * 64, 2) mk_fwd(Args args) {
;     ...
;             for (int q = 0; q < 3; ++q) { const int row = row0 + q; const bool lat = row < ML; const int r = lat ? row / SEQ : 8;
;                 float sy = 0.f;
; #pragma unroll
;                 for (int j = 0; j < 8; ++j) { const float a = bf_lo(yw[q][j].x), b = bf_hi(yw[q][j].x), c2 = bf_lo(yw[q][j].y), d = bf_hi(yw[q][j].y); sy += (a * a + b * b) + (c2 * c2 + d * d); }
;                 const float rsy = __builtin_amdgcn_rsqf(wave_sum(sy) * (1.f / DM) + EPS);
;                 const float* m0 = mod + (size_t)r * 6144;
; #pragma unroll
;                 for (int j = 0; j < 8; ++j) { const int col = 4 * F.lane + 256 * j; const f32x4 gt = *(const f32x4*)(m0 + 2 * DM + col), pn = *(const f32x4*)(post_norm + col);
;                     const f32x4 y4 = (f32x4){bf_lo(yw[q][j].x), bf_hi(yw[q][j].x), bf_lo(yw[q][j].y), bf_hi(yw[q][j].y)};
;                     v[q][j] = v[q][j] + gt * (y4 * rsy * pn);
.Lp6_np2:
	s_waitcnt vmcnt(24)
	v_lshlrev_b32_e32 v216, 16, v32
	v_and_b32_e32 v217, 0xffff0000, v32
	v_lshlrev_b32_e32 v218, 16, v33
	v_and_b32_e32 v219, 0xffff0000, v33
	v_mul_f32_e32 v222, v216, v216
	v_mul_f32_e32 v223, v217, v217
	v_fmac_f32_e32 v222, v218, v218
	v_fmac_f32_e32 v223, v219, v219
	v_lshlrev_b32_e32 v216, 16, v34
	v_and_b32_e32 v217, 0xffff0000, v34
	v_lshlrev_b32_e32 v218, 16, v35
	v_and_b32_e32 v219, 0xffff0000, v35
	v_fmac_f32_e32 v222, v216, v216
	v_fmac_f32_e32 v223, v217, v217
	v_fmac_f32_e32 v222, v218, v218
	v_fmac_f32_e32 v223, v219, v219
	v_lshlrev_b32_e32 v216, 16, v36
	v_and_b32_e32 v217, 0xffff0000, v36
	v_lshlrev_b32_e32 v218, 16, v37
	v_and_b32_e32 v219, 0xffff0000, v37
	v_fmac_f32_e32 v222, v216, v216
	v_fmac_f32_e32 v223, v217, v217
	v_fmac_f32_e32 v222, v218, v218
	v_fmac_f32_e32 v223, v219, v219
	v_lshlrev_b32_e32 v216, 16, v38
	v_and_b32_e32 v217, 0xffff0000, v38
	v_lshlrev_b32_e32 v218, 16, v39
	v_and_b32_e32 v219, 0xffff0000, v39
	v_fmac_f32_e32 v222, v216, v216
	v_fmac_f32_e32 v223, v217, v217
	v_fmac_f32_e32 v222, v218, v218
	v_fmac_f32_e32 v223, v219, v219
	v_lshlrev_b32_e32 v216, 16, v40
	v_and_b32_e32 v217, 0xffff0000, v40
	v_lshlrev_b32_e32 v218, 16, v41
	v_and_b32_e32 v219, 0xffff0000, v41
	v_fmac_f32_e32 v222, v216, v216
	v_fmac_f32_e32 v223, v217, v217
	v_fmac_f32_e32 v222, v218, v218
	v_fmac_f32_e32 v223, v219, v219
	v_lshlrev_b32_e32 v216, 16, v42
	v_and_b32_e32 v217, 0xffff0000, v42
	v_lshlrev_b32_e32 v218, 16, v43
	v_and_b32_e32 v219, 0xffff0000, v43
	v_fmac_f32_e32 v222, v216, v216
	v_fmac_f32_e32 v223, v217, v217
	v_fmac_f32_e32 v222, v218, v218
	v_fmac_f32_e32 v223, v219, v219
	v_lshlrev_b32_e32 v216, 16, v44
	v_and_b32_e32 v217, 0xffff0000, v44
	v_lshlrev_b32_e32 v218, 16, v45
	v_and_b32_e32 v219, 0xffff0000, v45
	v_fmac_f32_e32 v222, v216, v216
	v_fmac_f32_e32 v223, v217, v217
	v_fmac_f32_e32 v222, v218, v218
	v_fmac_f32_e32 v223, v219, v219
	v_lshlrev_b32_e32 v216, 16, v46
	v_and_b32_e32 v217, 0xffff0000, v46
	v_lshlrev_b32_e32 v218, 16, v47
	v_and_b32_e32 v219, 0xffff0000, v47
	v_fmac_f32_e32 v222, v216, v216
	v_fmac_f32_e32 v223, v217, v217
	v_fmac_f32_e32 v222, v218, v218
	v_fmac_f32_e32 v223, v219, v219
	v_add_f32_e32 v222, v222, v223
	s_nop 1
	v_add_f32_dpp v224, v222, v222 quad_perm:[1,0,3,2] row_mask:0xf bank_mask:0xf
	s_nop 1
	v_add_f32_dpp v224, v224, v224 quad_perm:[2,3,0,1] row_mask:0xf bank_mask:0xf
	s_nop 1
	v_add_f32_dpp v224, v224, v224 row_half_mirror row_mask:0xf bank_mask:0xf
	s_nop 1
	v_add_f32_dpp v224, v224, v224 row_mirror row_mask:0xf bank_mask:0xf
	s_nop 1
	v_readlane_b32 s40, v224, 0
	v_readlane_b32 s41, v224, 16
	v_readlane_b32 s42, v224, 32
	v_readlane_b32 s43, v224, 48
	s_nop 1
	v_mov_b32_e32 v225, s40
	v_add_f32_e32 v225, s41, v225
	v_add_f32_e32 v225, s42, v225
	v_add_f32_e32 v225, s43, v225
	v_fmamk_f32 v225, v225, 0x3a000000, v195
	v_rsq_f32_e32 v225, v225
	s_nop 0
	v_lshlrev_b32_e32 v216, 16, v32
	v_and_b32_e32 v217, 0xffff0000, v32
	v_lshlrev_b32_e32 v218, 16, v33
	v_and_b32_e32 v219, 0xffff0000, v33
	v_mul_f32_e32 v216, v225, v216
	v_mul_f32_e32 v217, v225, v217
	v_mul_f32_e32 v218, v225, v218
	v_mul_f32_e32 v219, v225, v219
	v_fmac_f32_e32 v0, v96, v216
	v_fmac_f32_e32 v1, v97, v217
	v_fmac_f32_e32 v2, v98, v218
	v_fmac_f32_e32 v3, v99, v219
	v_lshlrev_b32_e32 v216, 16, v34
	v_and_b32_e32 v217, 0xffff0000, v34
	v_lshlrev_b32_e32 v218, 16, v35
	v_and_b32_e32 v219, 0xffff0000, v35
	v_mul_f32_e32 v216, v225, v216
	v_mul_f32_e32 v217, v225, v217
	v_mul_f32_e32 v218, v225, v218
	v_mul_f32_e32 v219, v225, v219
	v_fmac_f32_e32 v4, v100, v216
	v_fmac_f32_e32 v5, v101, v217
	v_fmac_f32_e32 v6, v102, v218
	v_fmac_f32_e32 v7, v103, v219
	v_lshlrev_b32_e32 v216, 16, v36
	v_and_b32_e32 v217, 0xffff0000, v36
	v_lshlrev_b32_e32 v218, 16, v37
	v_and_b32_e32 v219, 0xffff0000, v37
	v_mul_f32_e32 v216, v225, v216
	v_mul_f32_e32 v217, v225, v217
	v_mul_f32_e32 v218, v225, v218
	v_mul_f32_e32 v219, v225, v219
	v_fmac_f32_e32 v8, v104, v216
	v_fmac_f32_e32 v9, v105, v217
	v_fmac_f32_e32 v10, v106, v218
	v_fmac_f32_e32 v11, v107, v219
	v_lshlrev_b32_e32 v216, 16, v38
	v_and_b32_e32 v217, 0xffff0000, v38
	v_lshlrev_b32_e32 v218, 16, v39
	v_and_b32_e32 v219, 0xffff0000, v39
	v_mul_f32_e32 v216, v225, v216
	v_mul_f32_e32 v217, v225, v217
	v_mul_f32_e32 v218, v225, v218
	v_mul_f32_e32 v219, v225, v219
	v_fmac_f32_e32 v12, v108, v216
	v_fmac_f32_e32 v13, v109, v217
	v_fmac_f32_e32 v14, v110, v218
	v_fmac_f32_e32 v15, v111, v219
	v_lshlrev_b32_e32 v216, 16, v40
	v_and_b32_e32 v217, 0xffff0000, v40
	v_lshlrev_b32_e32 v218, 16, v41
	v_and_b32_e32 v219, 0xffff0000, v41
	v_mul_f32_e32 v216, v225, v216
	v_mul_f32_e32 v217, v225, v217
	v_mul_f32_e32 v218, v225, v218
	v_mul_f32_e32 v219, v225, v219
	v_fmac_f32_e32 v16, v112, v216
	v_fmac_f32_e32 v17, v113, v217
	v_fmac_f32_e32 v18, v114, v218
	v_fmac_f32_e32 v19, v115, v219
	v_lshlrev_b32_e32 v216, 16, v42
	v_and_b32_e32 v217, 0xffff0000, v42
	v_lshlrev_b32_e32 v218, 16, v43
	v_and_b32_e32 v219, 0xffff0000, v43
	v_mul_f32_e32 v216, v225, v216
	v_mul_f32_e32 v217, v225, v217
	v_mul_f32_e32 v218, v225, v218
	v_mul_f32_e32 v219, v225, v219
	v_fmac_f32_e32 v20, v116, v216
	v_fmac_f32_e32 v21, v117, v217
	v_fmac_f32_e32 v22, v118, v218
	v_fmac_f32_e32 v23, v119, v219
	v_lshlrev_b32_e32 v216, 16, v44
	v_and_b32_e32 v217, 0xffff0000, v44
	v_lshlrev_b32_e32 v218, 16, v45
	v_and_b32_e32 v219, 0xffff0000, v45
	v_mul_f32_e32 v216, v225, v216
	v_mul_f32_e32 v217, v225, v217
	v_mul_f32_e32 v218, v225, v218
	v_mul_f32_e32 v219, v225, v219
	v_fmac_f32_e32 v24, v120, v216
	v_fmac_f32_e32 v25, v121, v217
	v_fmac_f32_e32 v26, v122, v218
; __device__ __forceinline__ unsigned cvt_pk_bf16(float lo, float hi) { unsigned r; asm volatile("v_cvt_pk_bf16_f32 %0, %1, %2" : "=v"(r) : "v"(lo), "v"(hi)); return r; }
; __device__ __forceinline__ void modulate_store(const f32x4 (&v)[8], float rstd, const float* pn, const float* modr, bf16_t* orow, int lane) {
; #pragma unroll
;     for (int j = 0; j < 8; ++j) { const int col = 4 * lane + 256 * j;
;         const f32x4 g = *(const f32x4*)(pn + col), sh = *(const f32x4*)(modr + col), sc = *(const f32x4*)(modr + DM + col);
;         const f32x4 hh = v[j] * rstd * g * (sc + 1.f) + sh;
;         u32x2 w; w.x = cvt_pk_bf16(hh[0], hh[1]); w.y = cvt_pk_bf16(hh[2], hh[3]);
;         *(u32x2*)(orow + col) = w; }
; __global__ void __launch_bounds__(NWAVES * 64, 2) mk_fwd(Args args) {
;     ...
;                     v[q][j] = v[q][j] + gt * (y4 * rsy * pn);
;                     if (lat) *(f32x4*)(args.out + (size_t)row * DM + col) = v[q][j]; }
;                 const float rstd = __builtin_amdgcn_rsqf(sumsq8(v[q]) * (1.f / DM) + EPS);
;                 modulate_store(v[q], rstd, pre_norm + DM, mod + (size_t)(9 + r) * 6144, H + (size_t)row * DM, F.lane); }
	v_fmac_f32_e32 v27, v123, v219
	v_lshlrev_b32_e32 v216, 16, v46
	v_and_b32_e32 v217, 0xffff0000, v46
	v_lshlrev_b32_e32 v218, 16, v47
	v_and_b32_e32 v219, 0xffff0000, v47
	v_mul_f32_e32 v216, v225, v216
	v_mul_f32_e32 v217, v225, v217
	v_mul_f32_e32 v218, v225, v218
	v_mul_f32_e32 v219, v225, v219
	v_fmac_f32_e32 v28, v124, v216
	v_fmac_f32_e32 v29, v125, v217
	v_fmac_f32_e32 v30, v126, v218
	v_fmac_f32_e32 v31, v127, v219
	v_mul_f32_e32 v222, v0, v0
	v_mul_f32_e32 v223, v1, v1
	v_fmac_f32_e32 v222, v2, v2
	v_fmac_f32_e32 v223, v3, v3
	v_fmac_f32_e32 v222, v4, v4
	v_fmac_f32_e32 v223, v5, v5
	v_fmac_f32_e32 v222, v6, v6
	v_fmac_f32_e32 v223, v7, v7
	v_fmac_f32_e32 v222, v8, v8
	v_fmac_f32_e32 v223, v9, v9
	v_fmac_f32_e32 v222, v10, v10
	v_fmac_f32_e32 v223, v11, v11
	v_fmac_f32_e32 v222, v12, v12
	v_fmac_f32_e32 v223, v13, v13
	v_fmac_f32_e32 v222, v14, v14
	v_fmac_f32_e32 v223, v15, v15
	v_fmac_f32_e32 v222, v16, v16
	v_fmac_f32_e32 v223, v17, v17
	v_fmac_f32_e32 v222, v18, v18
	v_fmac_f32_e32 v223, v19, v19
	v_fmac_f32_e32 v222, v20, v20
	v_fmac_f32_e32 v223, v21, v21
	v_fmac_f32_e32 v222, v22, v22
	v_fmac_f32_e32 v223, v23, v23
	v_fmac_f32_e32 v222, v24, v24
	v_fmac_f32_e32 v223, v25, v25
	v_fmac_f32_e32 v222, v26, v26
	v_fmac_f32_e32 v223, v27, v27
	v_fmac_f32_e32 v222, v28, v28
	v_fmac_f32_e32 v223, v29, v29
	v_fmac_f32_e32 v222, v30, v30
	v_fmac_f32_e32 v223, v31, v31
	v_add_f32_e32 v222, v222, v223
	s_nop 1
	v_add_f32_dpp v224, v222, v222 quad_perm:[1,0,3,2] row_mask:0xf bank_mask:0xf
	s_nop 1
	v_add_f32_dpp v224, v224, v224 quad_perm:[2,3,0,1] row_mask:0xf bank_mask:0xf
	s_nop 1
	v_add_f32_dpp v224, v224, v224 row_half_mirror row_mask:0xf bank_mask:0xf
	s_nop 1
	v_add_f32_dpp v224, v224, v224 row_mirror row_mask:0xf bank_mask:0xf
	s_nop 1
	v_readlane_b32 s40, v224, 0
	v_readlane_b32 s41, v224, 16
	v_readlane_b32 s42, v224, 32
	v_readlane_b32 s43, v224, 48
	s_nop 1
	v_mov_b32_e32 v225, s40
	v_add_f32_e32 v225, s41, v225
	v_add_f32_e32 v225, s42, v225
	v_add_f32_e32 v225, s43, v225
	v_fmamk_f32 v225, v225, 0x3a000000, v195
	v_rsq_f32_e32 v225, v225
	s_nop 0
	s_add_i32 s0, s6, 2
	s_lshl_b32 s1, s0, 12
	s_add_u32 s26, s84, s1
	s_addc_u32 s27, s85, 0
	s_add_u32 s26, s26, 0xd000000
	s_addc_u32 s27, s27, 0
	v_mul_f32_e32 v216, v225, v0
	v_mul_f32_e32 v217, v225, v1
	v_mul_f32_e32 v218, v225, v2
	v_mul_f32_e32 v219, v225, v3
	v_fma_f32 v216, v216, v128, v160
	v_fma_f32 v217, v217, v129, v161
	v_fma_f32 v218, v218, v130, v162
	v_fma_f32 v219, v219, v131, v163
	v_cvt_pk_bf16_f32 v196, v216, v217
	v_cvt_pk_bf16_f32 v197, v218, v219
	global_store_dwordx2 v194, v[196:197], s[26:27] offset:0
	v_mul_f32_e32 v216, v225, v4
	v_mul_f32_e32 v217, v225, v5
	v_mul_f32_e32 v218, v225, v6
	v_mul_f32_e32 v219, v225, v7
	v_fma_f32 v216, v216, v132, v164
	v_fma_f32 v217, v217, v133, v165
	v_fma_f32 v218, v218, v134, v166
	v_fma_f32 v219, v219, v135, v167
	v_cvt_pk_bf16_f32 v220, v216, v217
	v_cvt_pk_bf16_f32 v221, v218, v219
	global_store_dwordx2 v194, v[220:221], s[26:27] offset:512
	v_mul_f32_e32 v216, v225, v8
	v_mul_f32_e32 v217, v225, v9
	v_mul_f32_e32 v218, v225, v10
	v_mul_f32_e32 v219, v225, v11
	v_fma_f32 v216, v216, v136, v168
	v_fma_f32 v217, v217, v137, v169
	v_fma_f32 v218, v218, v138, v170
	v_fma_f32 v219, v219, v139, v171
	v_cvt_pk_bf16_f32 v196, v216, v217
	v_cvt_pk_bf16_f32 v197, v218, v219
	global_store_dwordx2 v194, v[196:197], s[26:27] offset:1024
	v_mul_f32_e32 v216, v225, v12
	v_mul_f32_e32 v217, v225, v13
	v_mul_f32_e32 v218, v225, v14
	v_mul_f32_e32 v219, v225, v15
	v_fma_f32 v216, v216, v140, v172
	v_fma_f32 v217, v217, v141, v173
	v_fma_f32 v218, v218, v142, v174
	v_fma_f32 v219, v219, v143, v175
	v_cvt_pk_bf16_f32 v220, v216, v217
	v_cvt_pk_bf16_f32 v221, v218, v219
	global_store_dwordx2 v194, v[220:221], s[26:27] offset:1536
	v_mul_f32_e32 v216, v225, v16
	v_mul_f32_e32 v217, v225, v17
	v_mul_f32_e32 v218, v225, v18
	v_mul_f32_e32 v219, v225, v19
	v_fma_f32 v216, v216, v144, v176
	v_fma_f32 v217, v217, v145, v177
	v_fma_f32 v218, v218, v146, v178
	v_fma_f32 v219, v219, v147, v179
	v_cvt_pk_bf16_f32 v196, v216, v217
	v_cvt_pk_bf16_f32 v197, v218, v219
	global_store_dwordx2 v194, v[196:197], s[26:27] offset:2048
	v_mul_f32_e32 v216, v225, v20
	v_mul_f32_e32 v217, v225, v21
	v_mul_f32_e32 v218, v225, v22
	v_mul_f32_e32 v219, v225, v23
	v_fma_f32 v216, v216, v148, v180
	v_fma_f32 v217, v217, v149, v181
	v_fma_f32 v218, v218, v150, v182
	v_fma_f32 v219, v219, v151, v183
	v_cvt_pk_bf16_f32 v220, v216, v217
	v_cvt_pk_bf16_f32 v221, v218, v219
	global_store_dwordx2 v194, v[220:221], s[26:27] offset:2560
	v_mul_f32_e32 v216, v225, v24
	v_mul_f32_e32 v217, v225, v25
	v_mul_f32_e32 v218, v225, v26
	v_mul_f32_e32 v219, v225, v27
	v_fma_f32 v216, v216, v152, v184
	v_fma_f32 v217, v217, v153, v185
	v_fma_f32 v218, v218, v154, v186
	v_fma_f32 v219, v219, v155, v187
	v_cvt_pk_bf16_f32 v196, v216, v217
	v_cvt_pk_bf16_f32 v197, v218, v219
	global_store_dwordx2 v194, v[196:197], s[26:27] offset:3072
	v_mul_f32_e32 v216, v225, v28
	v_mul_f32_e32 v217, v225, v29
	v_mul_f32_e32 v218, v225, v30
	v_mul_f32_e32 v219, v225, v31
	v_fma_f32 v216, v216, v156, v188
	v_fma_f32 v217, v217, v157, v189
	v_fma_f32 v218, v218, v158, v190
	v_fma_f32 v219, v219, v159, v191
	v_cvt_pk_bf16_f32 v220, v216, v217
	v_cvt_pk_bf16_f32 v221, v218, v219
	global_store_dwordx2 v194, v[220:221], s[26:27] offset:3584
	s_add_i32 s0, s6, 4
	s_cmp_lt_u32 s0, 0x4000
	s_cselect_b32 s10, s68, s72
	s_cselect_b32 s11, s69, s73
	s_cselect_b32 s1, 0, 0x4000
	s_sub_i32 s1, s0, s1
	s_lshl_b32 s1, s1, 13
	s_add_u32 s10, s10, s1
	s_addc_u32 s11, s11, 0
	s_add_i32 s0, s6, 4
	s_lshl_b32 s1, s0, 12
	s_add_u32 s22, s84, s1
	s_addc_u32 s23, s85, 0
	s_add_u32 s22, s22, 0x11800000
	s_addc_u32 s23, s23, 0
	global_load_dwordx4 v[0:3], v192, s[10:11] offset:0 nt
	global_load_dwordx4 v[4:7], v192, s[10:11] offset:1024 nt
	global_load_dwordx4 v[8:11], v192, s[10:11] offset:2048 nt
	global_load_dwordx4 v[12:15], v192, s[10:11] offset:3072 nt
	global_load_dwordx4 v[16:19], v193, s[10:11] offset:0 nt
	global_load_dwordx4 v[20:23], v193, s[10:11] offset:1024 nt
	global_load_dwordx4 v[24:27], v193, s[10:11] offset:2048 nt
	global_load_dwordx4 v[28:31], v193, s[10:11] offset:3072 nt
	global_load_dwordx2 v[32:33], v194, s[22:23] offset:0 nt
	global_load_dwordx2 v[34:35], v194, s[22:23] offset:512 nt
	global_load_dwordx2 v[36:37], v194, s[22:23] offset:1024 nt
	global_load_dwordx2 v[38:39], v194, s[22:23] offset:1536 nt
	global_load_dwordx2 v[40:41], v194, s[22:23] offset:2048 nt
	global_load_dwordx2 v[42:43], v194, s[22:23] offset:2560 nt
	global_load_dwordx2 v[44:45], v194, s[22:23] offset:3072 nt
	global_load_dwordx2 v[46:47], v194, s[22:23] offset:3584 nt
	s_add_i32 s0, s6, 3
	s_add_i32 s0, s6, 3
	s_lshr_b32 s8, s0, 11
	s_cmp_lt_u32 s0, 0x4000
	s_cselect_b32 s8, s8, 8
	s_cmp_eq_u32 s8, s7
	s_cbranch_scc1 .Lp6_np3
; __device__ __forceinline__ void modulate_store(const f32x4 (&v)[8], float rstd, const float* pn, const float* modr, bf16_t* orow, int lane) {
; #pragma unroll
;     for (int j = 0; j < 8; ++j) { const int col = 4 * lane + 256 * j;
;         const f32x4 g = *(const f32x4*)(pn + col), sh = *(const f32x4*)(modr + col), sc = *(const f32x4*)(modr + DM + col);
; __global__ void __launch_bounds__(NWAVES * 64, 2) mk_fwd(Args args) {
;     ...
;                 const float* m0 = mod + (size_t)r * 6144;
; #pragma unroll
;                 for (int j = 0; j < 8; ++j) { const int col = 4 * F.lane + 256 * j; const f32x4 gt = *(const f32x4*)(m0 + 2 * DM + col), pn = *(const f32x4*)(post_norm + col);
	s_mov_b32 s7, s8
	s_add_i32 s1, s8, 9
	s_mul_i32 s1, s1, 0x6000
	s_add_u32 s44, s84, s1
	s_addc_u32 s45, s85, 0
	s_add_u32 s44, s44, 0x2000
	s_addc_u32 s45, s45, 0
	s_add_i32 s1, s8, 9
	s_mul_i32 s1, s1, 0x6000
	s_add_u32 s36, s84, s1
	s_addc_u32 s37, s85, 0
	s_add_u32 s38, s80, 0x2000
	s_addc_u32 s39, s81, 0
	s_mul_i32 s1, s8, 0x6000
	s_add_u32 s34, s84, s1
	s_addc_u32 s35, s85, 0
	s_add_u32 s34, s34, 0x4000
	s_addc_u32 s35, s35, 0
	global_load_dwordx4 v[96:99], v192, s[34:35] offset:0
	global_load_dwordx4 v[200:203], v192, s[82:83] offset:0
	global_load_dwordx4 v[100:103], v192, s[34:35] offset:1024
	global_load_dwordx4 v[204:207], v192, s[82:83] offset:1024
	global_load_dwordx4 v[104:107], v192, s[34:35] offset:2048
	global_load_dwordx4 v[208:211], v192, s[82:83] offset:2048
	global_load_dwordx4 v[108:111], v192, s[34:35] offset:3072
	global_load_dwordx4 v[212:215], v192, s[82:83] offset:3072
	s_waitcnt vmcnt(0)
	v_mul_f32_e32 v96, v96, v200
	v_mul_f32_e32 v97, v97, v201
	v_mul_f32_e32 v98, v98, v202
	v_mul_f32_e32 v99, v99, v203
	v_mul_f32_e32 v100, v100, v204
	v_mul_f32_e32 v101, v101, v205
	v_mul_f32_e32 v102, v102, v206
	v_mul_f32_e32 v103, v103, v207
	v_mul_f32_e32 v104, v104, v208
	v_mul_f32_e32 v105, v105, v209
	v_mul_f32_e32 v106, v106, v210
	v_mul_f32_e32 v107, v107, v211
	v_mul_f32_e32 v108, v108, v212
	v_mul_f32_e32 v109, v109, v213
	v_mul_f32_e32 v110, v110, v214
	v_mul_f32_e32 v111, v111, v215
	global_load_dwordx4 v[128:131], v192, s[38:39] offset:0
	global_load_dwordx4 v[200:203], v192, s[44:45] offset:0
	global_load_dwordx4 v[160:163], v192, s[36:37] offset:0
	global_load_dwordx4 v[132:135], v192, s[38:39] offset:1024
	global_load_dwordx4 v[204:207], v192, s[44:45] offset:1024
	global_load_dwordx4 v[164:167], v192, s[36:37] offset:1024
	global_load_dwordx4 v[136:139], v192, s[38:39] offset:2048
	global_load_dwordx4 v[208:211], v192, s[44:45] offset:2048
	global_load_dwordx4 v[168:171], v192, s[36:37] offset:2048
	global_load_dwordx4 v[140:143], v192, s[38:39] offset:3072
	global_load_dwordx4 v[212:215], v192, s[44:45] offset:3072
	global_load_dwordx4 v[172:175], v192, s[36:37] offset:3072
	s_waitcnt vmcnt(0)
	v_add_f32_e32 v200, 1.0, v200
	v_add_f32_e32 v201, 1.0, v201
	v_add_f32_e32 v202, 1.0, v202
	v_add_f32_e32 v203, 1.0, v203
	v_mul_f32_e32 v128, v128, v200
	v_mul_f32_e32 v129, v129, v201
	v_mul_f32_e32 v130, v130, v202
	v_mul_f32_e32 v131, v131, v203
	v_add_f32_e32 v204, 1.0, v204
	v_add_f32_e32 v205, 1.0, v205
	v_add_f32_e32 v206, 1.0, v206
	v_add_f32_e32 v207, 1.0, v207
	v_mul_f32_e32 v132, v132, v204
	v_mul_f32_e32 v133, v133, v205
	v_mul_f32_e32 v134, v134, v206
	v_mul_f32_e32 v135, v135, v207
	v_add_f32_e32 v208, 1.0, v208
	v_add_f32_e32 v209, 1.0, v209
	v_add_f32_e32 v210, 1.0, v210
	v_add_f32_e32 v211, 1.0, v211
	v_mul_f32_e32 v136, v136, v208
	v_mul_f32_e32 v137, v137, v209
	v_mul_f32_e32 v138, v138, v210
	v_mul_f32_e32 v139, v139, v211
	v_add_f32_e32 v212, 1.0, v212
	v_add_f32_e32 v213, 1.0, v213
	v_add_f32_e32 v214, 1.0, v214
	v_add_f32_e32 v215, 1.0, v215
	v_mul_f32_e32 v140, v140, v212
	v_mul_f32_e32 v141, v141, v213
	v_mul_f32_e32 v142, v142, v214
	v_mul_f32_e32 v143, v143, v215
	global_load_dwordx4 v[112:115], v193, s[34:35] offset:0
	global_load_dwordx4 v[200:203], v193, s[82:83] offset:0
	global_load_dwordx4 v[116:119], v193, s[34:35] offset:1024
	global_load_dwordx4 v[204:207], v193, s[82:83] offset:1024
	global_load_dwordx4 v[120:123], v193, s[34:35] offset:2048
	global_load_dwordx4 v[208:211], v193, s[82:83] offset:2048
	global_load_dwordx4 v[124:127], v193, s[34:35] offset:3072
	global_load_dwordx4 v[212:215], v193, s[82:83] offset:3072
	s_waitcnt vmcnt(0)
	v_mul_f32_e32 v112, v112, v200
	v_mul_f32_e32 v113, v113, v201
	v_mul_f32_e32 v114, v114, v202
	v_mul_f32_e32 v115, v115, v203
	v_mul_f32_e32 v116, v116, v204
	v_mul_f32_e32 v117, v117, v205
	v_mul_f32_e32 v118, v118, v206
	v_mul_f32_e32 v119, v119, v207
	v_mul_f32_e32 v120, v120, v208
	v_mul_f32_e32 v121, v121, v209
	v_mul_f32_e32 v122, v122, v210
	v_mul_f32_e32 v123, v123, v211
	v_mul_f32_e32 v124, v124, v212
	v_mul_f32_e32 v125, v125, v213
	v_mul_f32_e32 v126, v126, v214
	v_mul_f32_e32 v127, v127, v215
	global_load_dwordx4 v[144:147], v193, s[38:39] offset:0
	global_load_dwordx4 v[200:203], v193, s[44:45] offset:0
	global_load_dwordx4 v[176:179], v193, s[36:37] offset:0
	global_load_dwordx4 v[148:151], v193, s[38:39] offset:1024
	global_load_dwordx4 v[204:207], v193, s[44:45] offset:1024
	global_load_dwordx4 v[180:183], v193, s[36:37] offset:1024
	global_load_dwordx4 v[152:155], v193, s[38:39] offset:2048
	global_load_dwordx4 v[208:211], v193, s[44:45] offset:2048
	global_load_dwordx4 v[184:187], v193, s[36:37] offset:2048
	global_load_dwordx4 v[156:159], v193, s[38:39] offset:3072
	global_load_dwordx4 v[212:215], v193, s[44:45] offset:3072
	global_load_dwordx4 v[188:191], v193, s[36:37] offset:3072
	s_waitcnt vmcnt(0)
	v_add_f32_e32 v200, 1.0, v200
	v_add_f32_e32 v201, 1.0, v201
	v_add_f32_e32 v202, 1.0, v202
	v_add_f32_e32 v203, 1.0, v203
	v_mul_f32_e32 v144, v144, v200
	v_mul_f32_e32 v145, v145, v201
	v_mul_f32_e32 v146, v146, v202
	v_mul_f32_e32 v147, v147, v203
	v_add_f32_e32 v204, 1.0, v204
	v_add_f32_e32 v205, 1.0, v205
	v_add_f32_e32 v206, 1.0, v206
	v_add_f32_e32 v207, 1.0, v207
	v_mul_f32_e32 v148, v148, v204
	v_mul_f32_e32 v149, v149, v205
	v_mul_f32_e32 v150, v150, v206
	v_mul_f32_e32 v151, v151, v207
	v_add_f32_e32 v208, 1.0, v208
	v_add_f32_e32 v209, 1.0, v209
	v_add_f32_e32 v210, 1.0, v210
	v_add_f32_e32 v211, 1.0, v211
	v_mul_f32_e32 v152, v152, v208
	v_mul_f32_e32 v153, v153, v209
	v_mul_f32_e32 v154, v154, v210
	v_mul_f32_e32 v155, v155, v211
	v_add_f32_e32 v212, 1.0, v212
	v_add_f32_e32 v213, 1.0, v213
	v_add_f32_e32 v214, 1.0, v214
	v_add_f32_e32 v215, 1.0, v215
	v_mul_f32_e32 v156, v156, v212
	v_mul_f32_e32 v157, v157, v213
	v_mul_f32_e32 v158, v158, v214
	v_mul_f32_e32 v159, v159, v215
; __device__ __forceinline__ float bf_lo(unsigned w) { return __uint_as_float(w << 16); }
; __device__ __forceinline__ float bf_hi(unsigned w) { return __uint_as_float(w & 0xffff0000u); }
; __global__ void __launch_bounds__(NWAVES * 64, 2) mk_fwd(Args args) {
;     ...
;             for (int q = 0; q < 3; ++q) { const int row = row0 + q; const bool lat = row < ML; const int r = lat ? row / SEQ : 8;
;                 float sy = 0.f;
; #pragma unroll
;                 for (int j = 0; j < 8; ++j) { const float a = bf_lo(yw[q][j].x), b = bf_hi(yw[q][j].x), c2 = bf_lo(yw[q][j].y), d = bf_hi(yw[q][j].y); sy += (a * a + b * b) + (c2 * c2 + d * d); }
;                 const float rsy = __builtin_amdgcn_rsqf(wave_sum(sy) * (1.f / DM) + EPS);
;                 const float* m0 = mod + (size_t)r * 6144;
; #pragma unroll
;                 for (int j = 0; j < 8; ++j) { const int col = 4 * F.lane + 256 * j; const f32x4 gt = *(const f32x4*)(m0 + 2 * DM + col), pn = *(const f32x4*)(post_norm + col);
;                     const f32x4 y4 = (f32x4){bf_lo(yw[q][j].x), bf_hi(yw[q][j].x), bf_lo(yw[q][j].y), bf_hi(yw[q][j].y)};
;                     v[q][j] = v[q][j] + gt * (y4 * rsy * pn);
.Lp6_np3:
	s_waitcnt vmcnt(24)
	v_lshlrev_b32_e32 v216, 16, v80
	v_and_b32_e32 v217, 0xffff0000, v80
	v_lshlrev_b32_e32 v218, 16, v81
	v_and_b32_e32 v219, 0xffff0000, v81
	v_mul_f32_e32 v222, v216, v216
	v_mul_f32_e32 v223, v217, v217
	v_fmac_f32_e32 v222, v218, v218
	v_fmac_f32_e32 v223, v219, v219
	v_lshlrev_b32_e32 v216, 16, v82
	v_and_b32_e32 v217, 0xffff0000, v82
	v_lshlrev_b32_e32 v218, 16, v83
	v_and_b32_e32 v219, 0xffff0000, v83
	v_fmac_f32_e32 v222, v216, v216
	v_fmac_f32_e32 v223, v217, v217
	v_fmac_f32_e32 v222, v218, v218
	v_fmac_f32_e32 v223, v219, v219
	v_lshlrev_b32_e32 v216, 16, v84
	v_and_b32_e32 v217, 0xffff0000, v84
	v_lshlrev_b32_e32 v218, 16, v85
	v_and_b32_e32 v219, 0xffff0000, v85
	v_fmac_f32_e32 v222, v216, v216
	v_fmac_f32_e32 v223, v217, v217
	v_fmac_f32_e32 v222, v218, v218
	v_fmac_f32_e32 v223, v219, v219
	v_lshlrev_b32_e32 v216, 16, v86
	v_and_b32_e32 v217, 0xffff0000, v86
	v_lshlrev_b32_e32 v218, 16, v87
	v_and_b32_e32 v219, 0xffff0000, v87
	v_fmac_f32_e32 v222, v216, v216
	v_fmac_f32_e32 v223, v217, v217
	v_fmac_f32_e32 v222, v218, v218
	v_fmac_f32_e32 v223, v219, v219
	v_lshlrev_b32_e32 v216, 16, v88
	v_and_b32_e32 v217, 0xffff0000, v88
	v_lshlrev_b32_e32 v218, 16, v89
	v_and_b32_e32 v219, 0xffff0000, v89
	v_fmac_f32_e32 v222, v216, v216
	v_fmac_f32_e32 v223, v217, v217
	v_fmac_f32_e32 v222, v218, v218
	v_fmac_f32_e32 v223, v219, v219
	v_lshlrev_b32_e32 v216, 16, v90
	v_and_b32_e32 v217, 0xffff0000, v90
	v_lshlrev_b32_e32 v218, 16, v91
	v_and_b32_e32 v219, 0xffff0000, v91
	v_fmac_f32_e32 v222, v216, v216
	v_fmac_f32_e32 v223, v217, v217
	v_fmac_f32_e32 v222, v218, v218
	v_fmac_f32_e32 v223, v219, v219
	v_lshlrev_b32_e32 v216, 16, v92
	v_and_b32_e32 v217, 0xffff0000, v92
	v_lshlrev_b32_e32 v218, 16, v93
	v_and_b32_e32 v219, 0xffff0000, v93
	v_fmac_f32_e32 v222, v216, v216
	v_fmac_f32_e32 v223, v217, v217
	v_fmac_f32_e32 v222, v218, v218
	v_fmac_f32_e32 v223, v219, v219
	v_lshlrev_b32_e32 v216, 16, v94
	v_and_b32_e32 v217, 0xffff0000, v94
	v_lshlrev_b32_e32 v218, 16, v95
	v_and_b32_e32 v219, 0xffff0000, v95
	v_fmac_f32_e32 v222, v216, v216
	v_fmac_f32_e32 v223, v217, v217
	v_fmac_f32_e32 v222, v218, v218
	v_fmac_f32_e32 v223, v219, v219
	v_add_f32_e32 v222, v222, v223
	s_nop 1
	v_add_f32_dpp v224, v222, v222 quad_perm:[1,0,3,2] row_mask:0xf bank_mask:0xf
	s_nop 1
	v_add_f32_dpp v224, v224, v224 quad_perm:[2,3,0,1] row_mask:0xf bank_mask:0xf
	s_nop 1
	v_add_f32_dpp v224, v224, v224 row_half_mirror row_mask:0xf bank_mask:0xf
	s_nop 1
	v_add_f32_dpp v224, v224, v224 row_mirror row_mask:0xf bank_mask:0xf
	s_nop 1
	v_readlane_b32 s40, v224, 0
	v_readlane_b32 s41, v224, 16
	v_readlane_b32 s42, v224, 32
	v_readlane_b32 s43, v224, 48
	s_nop 1
	v_mov_b32_e32 v225, s40
	v_add_f32_e32 v225, s41, v225
	v_add_f32_e32 v225, s42, v225
	v_add_f32_e32 v225, s43, v225
	v_fmamk_f32 v225, v225, 0x3a000000, v195
	v_rsq_f32_e32 v225, v225
	s_nop 0
	v_lshlrev_b32_e32 v216, 16, v80
	v_and_b32_e32 v217, 0xffff0000, v80
	v_lshlrev_b32_e32 v218, 16, v81
	v_and_b32_e32 v219, 0xffff0000, v81
	v_mul_f32_e32 v216, v225, v216
	v_mul_f32_e32 v217, v225, v217
	v_mul_f32_e32 v218, v225, v218
	v_mul_f32_e32 v219, v225, v219
	v_fmac_f32_e32 v48, v96, v216
	v_fmac_f32_e32 v49, v97, v217
	v_fmac_f32_e32 v50, v98, v218
	v_fmac_f32_e32 v51, v99, v219
	v_lshlrev_b32_e32 v216, 16, v82
	v_and_b32_e32 v217, 0xffff0000, v82
	v_lshlrev_b32_e32 v218, 16, v83
	v_and_b32_e32 v219, 0xffff0000, v83
	v_mul_f32_e32 v216, v225, v216
	v_mul_f32_e32 v217, v225, v217
	v_mul_f32_e32 v218, v225, v218
	v_mul_f32_e32 v219, v225, v219
	v_fmac_f32_e32 v52, v100, v216
	v_fmac_f32_e32 v53, v101, v217
	v_fmac_f32_e32 v54, v102, v218
	v_fmac_f32_e32 v55, v103, v219
	v_lshlrev_b32_e32 v216, 16, v84
	v_and_b32_e32 v217, 0xffff0000, v84
	v_lshlrev_b32_e32 v218, 16, v85
	v_and_b32_e32 v219, 0xffff0000, v85
	v_mul_f32_e32 v216, v225, v216
	v_mul_f32_e32 v217, v225, v217
	v_mul_f32_e32 v218, v225, v218
	v_mul_f32_e32 v219, v225, v219
	v_fmac_f32_e32 v56, v104, v216
	v_fmac_f32_e32 v57, v105, v217
	v_fmac_f32_e32 v58, v106, v218
	v_fmac_f32_e32 v59, v107, v219
	v_lshlrev_b32_e32 v216, 16, v86
	v_and_b32_e32 v217, 0xffff0000, v86
	v_lshlrev_b32_e32 v218, 16, v87
	v_and_b32_e32 v219, 0xffff0000, v87
	v_mul_f32_e32 v216, v225, v216
	v_mul_f32_e32 v217, v225, v217
	v_mul_f32_e32 v218, v225, v218
	v_mul_f32_e32 v219, v225, v219
	v_fmac_f32_e32 v60, v108, v216
	v_fmac_f32_e32 v61, v109, v217
	v_fmac_f32_e32 v62, v110, v218
	v_fmac_f32_e32 v63, v111, v219
	v_lshlrev_b32_e32 v216, 16, v88
	v_and_b32_e32 v217, 0xffff0000, v88
	v_lshlrev_b32_e32 v218, 16, v89
	v_and_b32_e32 v219, 0xffff0000, v89
	v_mul_f32_e32 v216, v225, v216
	v_mul_f32_e32 v217, v225, v217
	v_mul_f32_e32 v218, v225, v218
	v_mul_f32_e32 v219, v225, v219
	v_fmac_f32_e32 v64, v112, v216
	v_fmac_f32_e32 v65, v113, v217
	v_fmac_f32_e32 v66, v114, v218
	v_fmac_f32_e32 v67, v115, v219
	v_lshlrev_b32_e32 v216, 16, v90
	v_and_b32_e32 v217, 0xffff0000, v90
	v_lshlrev_b32_e32 v218, 16, v91
	v_and_b32_e32 v219, 0xffff0000, v91
	v_mul_f32_e32 v216, v225, v216
	v_mul_f32_e32 v217, v225, v217
	v_mul_f32_e32 v218, v225, v218
	v_mul_f32_e32 v219, v225, v219
	v_fmac_f32_e32 v68, v116, v216
	v_fmac_f32_e32 v69, v117, v217
	v_fmac_f32_e32 v70, v118, v218
	v_fmac_f32_e32 v71, v119, v219
	v_lshlrev_b32_e32 v216, 16, v92
	v_and_b32_e32 v217, 0xffff0000, v92
	v_lshlrev_b32_e32 v218, 16, v93
	v_and_b32_e32 v219, 0xffff0000, v93
	v_mul_f32_e32 v216, v225, v216
	v_mul_f32_e32 v217, v225, v217
	v_mul_f32_e32 v218, v225, v218
	v_mul_f32_e32 v219, v225, v219
	v_fmac_f32_e32 v72, v120, v216
	v_fmac_f32_e32 v73, v121, v217
	v_fmac_f32_e32 v74, v122, v218
; __device__ __forceinline__ unsigned cvt_pk_bf16(float lo, float hi) { unsigned r; asm volatile("v_cvt_pk_bf16_f32 %0, %1, %2" : "=v"(r) : "v"(lo), "v"(hi)); return r; }
; __device__ __forceinline__ void modulate_store(const f32x4 (&v)[8], float rstd, const float* pn, const float* modr, bf16_t* orow, int lane) {
; #pragma unroll
;     for (int j = 0; j < 8; ++j) { const int col = 4 * lane + 256 * j;
;         const f32x4 g = *(const f32x4*)(pn + col), sh = *(const f32x4*)(modr + col), sc = *(const f32x4*)(modr + DM + col);
;         const f32x4 hh = v[j] * rstd * g * (sc + 1.f) + sh;
;         u32x2 w; w.x = cvt_pk_bf16(hh[0], hh[1]); w.y = cvt_pk_bf16(hh[2], hh[3]);
;         *(u32x2*)(orow + col) = w; }
; __global__ void __launch_bounds__(NWAVES * 64, 2) mk_fwd(Args args) {
;     ...
;                     v[q][j] = v[q][j] + gt * (y4 * rsy * pn);
;                     if (lat) *(f32x4*)(args.out + (size_t)row * DM + col) = v[q][j]; }
;                 const float rstd = __builtin_amdgcn_rsqf(sumsq8(v[q]) * (1.f / DM) + EPS);
;                 modulate_store(v[q], rstd, pre_norm + DM, mod + (size_t)(9 + r) * 6144, H + (size_t)row * DM, F.lane); }
	v_fmac_f32_e32 v75, v123, v219
	v_lshlrev_b32_e32 v216, 16, v94
	v_and_b32_e32 v217, 0xffff0000, v94
	v_lshlrev_b32_e32 v218, 16, v95
	v_and_b32_e32 v219, 0xffff0000, v95
	v_mul_f32_e32 v216, v225, v216
	v_mul_f32_e32 v217, v225, v217
	v_mul_f32_e32 v218, v225, v218
	v_mul_f32_e32 v219, v225, v219
	v_fmac_f32_e32 v76, v124, v216
	v_fmac_f32_e32 v77, v125, v217
	v_fmac_f32_e32 v78, v126, v218
	v_fmac_f32_e32 v79, v127, v219
	v_mul_f32_e32 v222, v48, v48
	v_mul_f32_e32 v223, v49, v49
	v_fmac_f32_e32 v222, v50, v50
	v_fmac_f32_e32 v223, v51, v51
	v_fmac_f32_e32 v222, v52, v52
	v_fmac_f32_e32 v223, v53, v53
	v_fmac_f32_e32 v222, v54, v54
	v_fmac_f32_e32 v223, v55, v55
	v_fmac_f32_e32 v222, v56, v56
	v_fmac_f32_e32 v223, v57, v57
	v_fmac_f32_e32 v222, v58, v58
	v_fmac_f32_e32 v223, v59, v59
	v_fmac_f32_e32 v222, v60, v60
	v_fmac_f32_e32 v223, v61, v61
	v_fmac_f32_e32 v222, v62, v62
	v_fmac_f32_e32 v223, v63, v63
	v_fmac_f32_e32 v222, v64, v64
	v_fmac_f32_e32 v223, v65, v65
	v_fmac_f32_e32 v222, v66, v66
	v_fmac_f32_e32 v223, v67, v67
	v_fmac_f32_e32 v222, v68, v68
	v_fmac_f32_e32 v223, v69, v69
	v_fmac_f32_e32 v222, v70, v70
	v_fmac_f32_e32 v223, v71, v71
	v_fmac_f32_e32 v222, v72, v72
	v_fmac_f32_e32 v223, v73, v73
	v_fmac_f32_e32 v222, v74, v74
	v_fmac_f32_e32 v223, v75, v75
	v_fmac_f32_e32 v222, v76, v76
	v_fmac_f32_e32 v223, v77, v77
	v_fmac_f32_e32 v222, v78, v78
	v_fmac_f32_e32 v223, v79, v79
	v_add_f32_e32 v222, v222, v223
	s_nop 1
	v_add_f32_dpp v224, v222, v222 quad_perm:[1,0,3,2] row_mask:0xf bank_mask:0xf
	s_nop 1
	v_add_f32_dpp v224, v224, v224 quad_perm:[2,3,0,1] row_mask:0xf bank_mask:0xf
	s_nop 1
	v_add_f32_dpp v224, v224, v224 row_half_mirror row_mask:0xf bank_mask:0xf
	s_nop 1
	v_add_f32_dpp v224, v224, v224 row_mirror row_mask:0xf bank_mask:0xf
	s_nop 1
	v_readlane_b32 s40, v224, 0
	v_readlane_b32 s41, v224, 16
	v_readlane_b32 s42, v224, 32
	v_readlane_b32 s43, v224, 48
	s_nop 1
	v_mov_b32_e32 v225, s40
	v_add_f32_e32 v225, s41, v225
	v_add_f32_e32 v225, s42, v225
	v_add_f32_e32 v225, s43, v225
	v_fmamk_f32 v225, v225, 0x3a000000, v195
	v_rsq_f32_e32 v225, v225
	s_nop 0
	s_add_i32 s0, s6, 3
	s_lshl_b32 s1, s0, 12
	s_add_u32 s26, s84, s1
	s_addc_u32 s27, s85, 0
	s_add_u32 s26, s26, 0xd000000
	s_addc_u32 s27, s27, 0
	v_mul_f32_e32 v216, v225, v48
	v_mul_f32_e32 v217, v225, v49
	v_mul_f32_e32 v218, v225, v50
	v_mul_f32_e32 v219, v225, v51
	v_fma_f32 v216, v216, v128, v160
	v_fma_f32 v217, v217, v129, v161
	v_fma_f32 v218, v218, v130, v162
	v_fma_f32 v219, v219, v131, v163
	v_cvt_pk_bf16_f32 v196, v216, v217
	v_cvt_pk_bf16_f32 v197, v218, v219
	global_store_dwordx2 v194, v[196:197], s[26:27] offset:0
	v_mul_f32_e32 v216, v225, v52
	v_mul_f32_e32 v217, v225, v53
	v_mul_f32_e32 v218, v225, v54
	v_mul_f32_e32 v219, v225, v55
	v_fma_f32 v216, v216, v132, v164
	v_fma_f32 v217, v217, v133, v165
	v_fma_f32 v218, v218, v134, v166
	v_fma_f32 v219, v219, v135, v167
	v_cvt_pk_bf16_f32 v220, v216, v217
	v_cvt_pk_bf16_f32 v221, v218, v219
	global_store_dwordx2 v194, v[220:221], s[26:27] offset:512
	v_mul_f32_e32 v216, v225, v56
	v_mul_f32_e32 v217, v225, v57
	v_mul_f32_e32 v218, v225, v58
	v_mul_f32_e32 v219, v225, v59
	v_fma_f32 v216, v216, v136, v168
	v_fma_f32 v217, v217, v137, v169
	v_fma_f32 v218, v218, v138, v170
	v_fma_f32 v219, v219, v139, v171
	v_cvt_pk_bf16_f32 v196, v216, v217
	v_cvt_pk_bf16_f32 v197, v218, v219
	global_store_dwordx2 v194, v[196:197], s[26:27] offset:1024
	v_mul_f32_e32 v216, v225, v60
	v_mul_f32_e32 v217, v225, v61
	v_mul_f32_e32 v218, v225, v62
	v_mul_f32_e32 v219, v225, v63
	v_fma_f32 v216, v216, v140, v172
	v_fma_f32 v217, v217, v141, v173
	v_fma_f32 v218, v218, v142, v174
	v_fma_f32 v219, v219, v143, v175
	v_cvt_pk_bf16_f32 v220, v216, v217
	v_cvt_pk_bf16_f32 v221, v218, v219
	global_store_dwordx2 v194, v[220:221], s[26:27] offset:1536
	v_mul_f32_e32 v216, v225, v64
	v_mul_f32_e32 v217, v225, v65
	v_mul_f32_e32 v218, v225, v66
	v_mul_f32_e32 v219, v225, v67
	v_fma_f32 v216, v216, v144, v176
	v_fma_f32 v217, v217, v145, v177
	v_fma_f32 v218, v218, v146, v178
	v_fma_f32 v219, v219, v147, v179
	v_cvt_pk_bf16_f32 v196, v216, v217
	v_cvt_pk_bf16_f32 v197, v218, v219
	global_store_dwordx2 v194, v[196:197], s[26:27] offset:2048
	v_mul_f32_e32 v216, v225, v68
	v_mul_f32_e32 v217, v225, v69
	v_mul_f32_e32 v218, v225, v70
	v_mul_f32_e32 v219, v225, v71
	v_fma_f32 v216, v216, v148, v180
	v_fma_f32 v217, v217, v149, v181
	v_fma_f32 v218, v218, v150, v182
	v_fma_f32 v219, v219, v151, v183
	v_cvt_pk_bf16_f32 v220, v216, v217
	v_cvt_pk_bf16_f32 v221, v218, v219
	global_store_dwordx2 v194, v[220:221], s[26:27] offset:2560
	v_mul_f32_e32 v216, v225, v72
	v_mul_f32_e32 v217, v225, v73
	v_mul_f32_e32 v218, v225, v74
	v_mul_f32_e32 v219, v225, v75
	v_fma_f32 v216, v216, v152, v184
	v_fma_f32 v217, v217, v153, v185
	v_fma_f32 v218, v218, v154, v186
	v_fma_f32 v219, v219, v155, v187
	v_cvt_pk_bf16_f32 v196, v216, v217
	v_cvt_pk_bf16_f32 v197, v218, v219
	global_store_dwordx2 v194, v[196:197], s[26:27] offset:3072
	v_mul_f32_e32 v216, v225, v76
	v_mul_f32_e32 v217, v225, v77
	v_mul_f32_e32 v218, v225, v78
	v_mul_f32_e32 v219, v225, v79
	v_fma_f32 v216, v216, v156, v188
	v_fma_f32 v217, v217, v157, v189
	v_fma_f32 v218, v218, v158, v190
	v_fma_f32 v219, v219, v159, v191
	v_cvt_pk_bf16_f32 v220, v216, v217
	v_cvt_pk_bf16_f32 v221, v218, v219
	global_store_dwordx2 v194, v[220:221], s[26:27] offset:3584
	s_add_i32 s0, s6, 5
	s_cmp_lt_u32 s0, 0x4000
	s_cselect_b32 s10, s68, s72
	s_cselect_b32 s11, s69, s73
	s_cselect_b32 s1, 0, 0x4000
	s_sub_i32 s1, s0, s1
	s_lshl_b32 s1, s1, 13
	s_add_u32 s10, s10, s1
	s_addc_u32 s11, s11, 0
	s_add_i32 s0, s6, 5
	s_lshl_b32 s1, s0, 12
	s_add_u32 s22, s84, s1
	s_addc_u32 s23, s85, 0
	s_add_u32 s22, s22, 0x11800000
	s_addc_u32 s23, s23, 0
	global_load_dwordx4 v[48:51], v192, s[10:11] offset:0 nt
	global_load_dwordx4 v[52:55], v192, s[10:11] offset:1024 nt
	global_load_dwordx4 v[56:59], v192, s[10:11] offset:2048 nt
	global_load_dwordx4 v[60:63], v192, s[10:11] offset:3072 nt
	global_load_dwordx4 v[64:67], v193, s[10:11] offset:0 nt
	global_load_dwordx4 v[68:71], v193, s[10:11] offset:1024 nt
	global_load_dwordx4 v[72:75], v193, s[10:11] offset:2048 nt
	global_load_dwordx4 v[76:79], v193, s[10:11] offset:3072 nt
	global_load_dwordx2 v[80:81], v194, s[22:23] offset:0 nt
	global_load_dwordx2 v[82:83], v194, s[22:23] offset:512 nt
	global_load_dwordx2 v[84:85], v194, s[22:23] offset:1024 nt
	global_load_dwordx2 v[86:87], v194, s[22:23] offset:1536 nt
	global_load_dwordx2 v[88:89], v194, s[22:23] offset:2048 nt
	global_load_dwordx2 v[90:91], v194, s[22:23] offset:2560 nt
	global_load_dwordx2 v[92:93], v194, s[22:23] offset:3072 nt
	global_load_dwordx2 v[94:95], v194, s[22:23] offset:3584 nt
	s_add_i32 s0, s6, 4
	s_add_i32 s0, s6, 4
	s_lshr_b32 s8, s0, 11
	s_cmp_lt_u32 s0, 0x4000
	s_cselect_b32 s8, s8, 8
	s_cmp_eq_u32 s8, s7
	s_cbranch_scc1 .Lp6_np4
; __device__ __forceinline__ void modulate_store(const f32x4 (&v)[8], float rstd, const float* pn, const float* modr, bf16_t* orow, int lane) {
; #pragma unroll
;     for (int j = 0; j < 8; ++j) { const int col = 4 * lane + 256 * j;
;         const f32x4 g = *(const f32x4*)(pn + col), sh = *(const f32x4*)(modr + col), sc = *(const f32x4*)(modr + DM + col);
;         const f32x4 hh = v[j] * rstd * g * (sc + 1.f) + sh;
; __global__ void __launch_bounds__(NWAVES * 64, 2) mk_fwd(Args args) {
;     ...
;                 const float* m0 = mod + (size_t)r * 6144;
; #pragma unroll
;                 for (int j = 0; j < 8; ++j) { const int col = 4 * F.lane + 256 * j; const f32x4 gt = *(const f32x4*)(m0 + 2 * DM + col), pn = *(const f32x4*)(post_norm + col);
	s_mov_b32 s7, s8
	s_add_i32 s1, s8, 9
	s_mul_i32 s1, s1, 0x6000
	s_add_u32 s44, s84, s1
	s_addc_u32 s45, s85, 0
	s_add_u32 s44, s44, 0x2000
	s_addc_u32 s45, s45, 0
	s_add_i32 s1, s8, 9
	s_mul_i32 s1, s1, 0x6000
	s_add_u32 s36, s84, s1
	s_addc_u32 s37, s85, 0
	s_add_u32 s38, s80, 0x2000
	s_addc_u32 s39, s81, 0
	s_mul_i32 s1, s8, 0x6000
	s_add_u32 s34, s84, s1
	s_addc_u32 s35, s85, 0
	s_add_u32 s34, s34, 0x4000
	s_addc_u32 s35, s35, 0
	global_load_dwordx4 v[96:99], v192, s[34:35] offset:0
	global_load_dwordx4 v[200:203], v192, s[82:83] offset:0
	global_load_dwordx4 v[100:103], v192, s[34:35] offset:1024
	global_load_dwordx4 v[204:207], v192, s[82:83] offset:1024
	global_load_dwordx4 v[104:107], v192, s[34:35] offset:2048
	global_load_dwordx4 v[208:211], v192, s[82:83] offset:2048
	global_load_dwordx4 v[108:111], v192, s[34:35] offset:3072
	global_load_dwordx4 v[212:215], v192, s[82:83] offset:3072
	s_waitcnt vmcnt(0)
	v_mul_f32_e32 v96, v96, v200
	v_mul_f32_e32 v97, v97, v201
	v_mul_f32_e32 v98, v98, v202
	v_mul_f32_e32 v99, v99, v203
	v_mul_f32_e32 v100, v100, v204
	v_mul_f32_e32 v101, v101, v205
	v_mul_f32_e32 v102, v102, v206
	v_mul_f32_e32 v103, v103, v207
	v_mul_f32_e32 v104, v104, v208
	v_mul_f32_e32 v105, v105, v209
	v_mul_f32_e32 v106, v106, v210
	v_mul_f32_e32 v107, v107, v211
	v_mul_f32_e32 v108, v108, v212
	v_mul_f32_e32 v109, v109, v213
	v_mul_f32_e32 v110, v110, v214
	v_mul_f32_e32 v111, v111, v215
	global_load_dwordx4 v[128:131], v192, s[38:39] offset:0
	global_load_dwordx4 v[200:203], v192, s[44:45] offset:0
	global_load_dwordx4 v[160:163], v192, s[36:37] offset:0
	global_load_dwordx4 v[132:135], v192, s[38:39] offset:1024
	global_load_dwordx4 v[204:207], v192, s[44:45] offset:1024
	global_load_dwordx4 v[164:167], v192, s[36:37] offset:1024
	global_load_dwordx4 v[136:139], v192, s[38:39] offset:2048
	global_load_dwordx4 v[208:211], v192, s[44:45] offset:2048
	global_load_dwordx4 v[168:171], v192, s[36:37] offset:2048
	global_load_dwordx4 v[140:143], v192, s[38:39] offset:3072
	global_load_dwordx4 v[212:215], v192, s[44:45] offset:3072
	global_load_dwordx4 v[172:175], v192, s[36:37] offset:3072
	s_waitcnt vmcnt(0)
	v_add_f32_e32 v200, 1.0, v200
	v_add_f32_e32 v201, 1.0, v201
	v_add_f32_e32 v202, 1.0, v202
	v_add_f32_e32 v203, 1.0, v203
	v_mul_f32_e32 v128, v128, v200
	v_mul_f32_e32 v129, v129, v201
	v_mul_f32_e32 v130, v130, v202
	v_mul_f32_e32 v131, v131, v203
	v_add_f32_e32 v204, 1.0, v204
	v_add_f32_e32 v205, 1.0, v205
	v_add_f32_e32 v206, 1.0, v206
	v_add_f32_e32 v207, 1.0, v207
	v_mul_f32_e32 v132, v132, v204
	v_mul_f32_e32 v133, v133, v205
	v_mul_f32_e32 v134, v134, v206
	v_mul_f32_e32 v135, v135, v207
	v_add_f32_e32 v208, 1.0, v208
	v_add_f32_e32 v209, 1.0, v209
	v_add_f32_e32 v210, 1.0, v210
	v_add_f32_e32 v211, 1.0, v211
	v_mul_f32_e32 v136, v136, v208
	v_mul_f32_e32 v137, v137, v209
	v_mul_f32_e32 v138, v138, v210
	v_mul_f32_e32 v139, v139, v211
	v_add_f32_e32 v212, 1.0, v212
	v_add_f32_e32 v213, 1.0, v213
	v_add_f32_e32 v214, 1.0, v214
	v_add_f32_e32 v215, 1.0, v215
	v_mul_f32_e32 v140, v140, v212
	v_mul_f32_e32 v141, v141, v213
	v_mul_f32_e32 v142, v142, v214
	v_mul_f32_e32 v143, v143, v215
	global_load_dwordx4 v[112:115], v193, s[34:35] offset:0
	global_load_dwordx4 v[200:203], v193, s[82:83] offset:0
	global_load_dwordx4 v[116:119], v193, s[34:35] offset:1024
	global_load_dwordx4 v[204:207], v193, s[82:83] offset:1024
	global_load_dwordx4 v[120:123], v193, s[34:35] offset:2048
	global_load_dwordx4 v[208:211], v193, s[82:83] offset:2048
	global_load_dwordx4 v[124:127], v193, s[34:35] offset:3072
	global_load_dwordx4 v[212:215], v193, s[82:83] offset:3072
	s_waitcnt vmcnt(0)
	v_mul_f32_e32 v112, v112, v200
	v_mul_f32_e32 v113, v113, v201
	v_mul_f32_e32 v114, v114, v202
	v_mul_f32_e32 v115, v115, v203
	v_mul_f32_e32 v116, v116, v204
	v_mul_f32_e32 v117, v117, v205
	v_mul_f32_e32 v118, v118, v206
	v_mul_f32_e32 v119, v119, v207
	v_mul_f32_e32 v120, v120, v208
	v_mul_f32_e32 v121, v121, v209
	v_mul_f32_e32 v122, v122, v210
	v_mul_f32_e32 v123, v123, v211
	v_mul_f32_e32 v124, v124, v212
	v_mul_f32_e32 v125, v125, v213
	v_mul_f32_e32 v126, v126, v214
	v_mul_f32_e32 v127, v127, v215
	global_load_dwordx4 v[144:147], v193, s[38:39] offset:0
	global_load_dwordx4 v[200:203], v193, s[44:45] offset:0
	global_load_dwordx4 v[176:179], v193, s[36:37] offset:0
	global_load_dwordx4 v[148:151], v193, s[38:39] offset:1024
	global_load_dwordx4 v[204:207], v193, s[44:45] offset:1024
	global_load_dwordx4 v[180:183], v193, s[36:37] offset:1024
	global_load_dwordx4 v[152:155], v193, s[38:39] offset:2048
	global_load_dwordx4 v[208:211], v193, s[44:45] offset:2048
	global_load_dwordx4 v[184:187], v193, s[36:37] offset:2048
	global_load_dwordx4 v[156:159], v193, s[38:39] offset:3072
	global_load_dwordx4 v[212:215], v193, s[44:45] offset:3072
	global_load_dwordx4 v[188:191], v193, s[36:37] offset:3072
	s_waitcnt vmcnt(0)
	v_add_f32_e32 v200, 1.0, v200
	v_add_f32_e32 v201, 1.0, v201
	v_add_f32_e32 v202, 1.0, v202
	v_add_f32_e32 v203, 1.0, v203
	v_mul_f32_e32 v144, v144, v200
	v_mul_f32_e32 v145, v145, v201
	v_mul_f32_e32 v146, v146, v202
	v_mul_f32_e32 v147, v147, v203
	v_add_f32_e32 v204, 1.0, v204
	v_add_f32_e32 v205, 1.0, v205
	v_add_f32_e32 v206, 1.0, v206
	v_add_f32_e32 v207, 1.0, v207
	v_mul_f32_e32 v148, v148, v204
	v_mul_f32_e32 v149, v149, v205
	v_mul_f32_e32 v150, v150, v206
	v_mul_f32_e32 v151, v151, v207
	v_add_f32_e32 v208, 1.0, v208
	v_add_f32_e32 v209, 1.0, v209
	v_add_f32_e32 v210, 1.0, v210
	v_add_f32_e32 v211, 1.0, v211
	v_mul_f32_e32 v152, v152, v208
	v_mul_f32_e32 v153, v153, v209
	v_mul_f32_e32 v154, v154, v210
	v_mul_f32_e32 v155, v155, v211
	v_add_f32_e32 v212, 1.0, v212
	v_add_f32_e32 v213, 1.0, v213
	v_add_f32_e32 v214, 1.0, v214
	v_add_f32_e32 v215, 1.0, v215
	v_mul_f32_e32 v156, v156, v212
	v_mul_f32_e32 v157, v157, v213
	v_mul_f32_e32 v158, v158, v214
	v_mul_f32_e32 v159, v159, v215
; __device__ __forceinline__ float bf_lo(unsigned w) { return __uint_as_float(w << 16); }
; __device__ __forceinline__ float bf_hi(unsigned w) { return __uint_as_float(w & 0xffff0000u); }
; __global__ void __launch_bounds__(NWAVES * 64, 2) mk_fwd(Args args) {
;     ...
;                 float sy = 0.f;
; #pragma unroll
;                 for (int j = 0; j < 8; ++j) { const float a = bf_lo(yw[q][j].x), b = bf_hi(yw[q][j].x), c2 = bf_lo(yw[q][j].y), d = bf_hi(yw[q][j].y); sy += (a * a + b * b) + (c2 * c2 + d * d); }
;                 const float rsy = __builtin_amdgcn_rsqf(wave_sum(sy) * (1.f / DM) + EPS);
;                 const float* m0 = mod + (size_t)r * 6144;
; #pragma unroll
;                 for (int j = 0; j < 8; ++j) { const int col = 4 * F.lane + 256 * j; const f32x4 gt = *(const f32x4*)(m0 + 2 * DM + col), pn = *(const f32x4*)(post_norm + col);
;                     const f32x4 y4 = (f32x4){bf_lo(yw[q][j].x), bf_hi(yw[q][j].x), bf_lo(yw[q][j].y), bf_hi(yw[q][j].y)};
;                     v[q][j] = v[q][j] + gt * (y4 * rsy * pn);
.Lp6_np4:
	s_waitcnt vmcnt(24)
	v_lshlrev_b32_e32 v216, 16, v32
	v_and_b32_e32 v217, 0xffff0000, v32
	v_lshlrev_b32_e32 v218, 16, v33
	v_and_b32_e32 v219, 0xffff0000, v33
	v_mul_f32_e32 v222, v216, v216
	v_mul_f32_e32 v223, v217, v217
	v_fmac_f32_e32 v222, v218, v218
	v_fmac_f32_e32 v223, v219, v219
	v_lshlrev_b32_e32 v216, 16, v34
	v_and_b32_e32 v217, 0xffff0000, v34
	v_lshlrev_b32_e32 v218, 16, v35
	v_and_b32_e32 v219, 0xffff0000, v35
	v_fmac_f32_e32 v222, v216, v216
	v_fmac_f32_e32 v223, v217, v217
	v_fmac_f32_e32 v222, v218, v218
	v_fmac_f32_e32 v223, v219, v219
	v_lshlrev_b32_e32 v216, 16, v36
	v_and_b32_e32 v217, 0xffff0000, v36
	v_lshlrev_b32_e32 v218, 16, v37
	v_and_b32_e32 v219, 0xffff0000, v37
	v_fmac_f32_e32 v222, v216, v216
	v_fmac_f32_e32 v223, v217, v217
	v_fmac_f32_e32 v222, v218, v218
	v_fmac_f32_e32 v223, v219, v219
	v_lshlrev_b32_e32 v216, 16, v38
	v_and_b32_e32 v217, 0xffff0000, v38
	v_lshlrev_b32_e32 v218, 16, v39
	v_and_b32_e32 v219, 0xffff0000, v39
	v_fmac_f32_e32 v222, v216, v216
	v_fmac_f32_e32 v223, v217, v217
	v_fmac_f32_e32 v222, v218, v218
	v_fmac_f32_e32 v223, v219, v219
	v_lshlrev_b32_e32 v216, 16, v40
	v_and_b32_e32 v217, 0xffff0000, v40
	v_lshlrev_b32_e32 v218, 16, v41
	v_and_b32_e32 v219, 0xffff0000, v41
	v_fmac_f32_e32 v222, v216, v216
	v_fmac_f32_e32 v223, v217, v217
	v_fmac_f32_e32 v222, v218, v218
	v_fmac_f32_e32 v223, v219, v219
	v_lshlrev_b32_e32 v216, 16, v42
	v_and_b32_e32 v217, 0xffff0000, v42
	v_lshlrev_b32_e32 v218, 16, v43
	v_and_b32_e32 v219, 0xffff0000, v43
	v_fmac_f32_e32 v222, v216, v216
	v_fmac_f32_e32 v223, v217, v217
	v_fmac_f32_e32 v222, v218, v218
	v_fmac_f32_e32 v223, v219, v219
	v_lshlrev_b32_e32 v216, 16, v44
	v_and_b32_e32 v217, 0xffff0000, v44
	v_lshlrev_b32_e32 v218, 16, v45
	v_and_b32_e32 v219, 0xffff0000, v45
	v_fmac_f32_e32 v222, v216, v216
	v_fmac_f32_e32 v223, v217, v217
	v_fmac_f32_e32 v222, v218, v218
	v_fmac_f32_e32 v223, v219, v219
	v_lshlrev_b32_e32 v216, 16, v46
	v_and_b32_e32 v217, 0xffff0000, v46
	v_lshlrev_b32_e32 v218, 16, v47
	v_and_b32_e32 v219, 0xffff0000, v47
	v_fmac_f32_e32 v222, v216, v216
	v_fmac_f32_e32 v223, v217, v217
	v_fmac_f32_e32 v222, v218, v218
	v_fmac_f32_e32 v223, v219, v219
	v_add_f32_e32 v222, v222, v223
	s_nop 1
	v_add_f32_dpp v224, v222, v222 quad_perm:[1,0,3,2] row_mask:0xf bank_mask:0xf
	s_nop 1
	v_add_f32_dpp v224, v224, v224 quad_perm:[2,3,0,1] row_mask:0xf bank_mask:0xf
	s_nop 1
	v_add_f32_dpp v224, v224, v224 row_half_mirror row_mask:0xf bank_mask:0xf
	s_nop 1
	v_add_f32_dpp v224, v224, v224 row_mirror row_mask:0xf bank_mask:0xf
	s_nop 1
	v_readlane_b32 s40, v224, 0
	v_readlane_b32 s41, v224, 16
	v_readlane_b32 s42, v224, 32
	v_readlane_b32 s43, v224, 48
	s_nop 1
	v_mov_b32_e32 v225, s40
	v_add_f32_e32 v225, s41, v225
	v_add_f32_e32 v225, s42, v225
	v_add_f32_e32 v225, s43, v225
	v_fmamk_f32 v225, v225, 0x3a000000, v195
	v_rsq_f32_e32 v225, v225
	s_nop 0
	v_lshlrev_b32_e32 v216, 16, v32
	v_and_b32_e32 v217, 0xffff0000, v32
	v_lshlrev_b32_e32 v218, 16, v33
	v_and_b32_e32 v219, 0xffff0000, v33
	v_mul_f32_e32 v216, v225, v216
	v_mul_f32_e32 v217, v225, v217
	v_mul_f32_e32 v218, v225, v218
	v_mul_f32_e32 v219, v225, v219
	v_fmac_f32_e32 v0, v96, v216
	v_fmac_f32_e32 v1, v97, v217
	v_fmac_f32_e32 v2, v98, v218
	v_fmac_f32_e32 v3, v99, v219
	v_lshlrev_b32_e32 v216, 16, v34
	v_and_b32_e32 v217, 0xffff0000, v34
	v_lshlrev_b32_e32 v218, 16, v35
	v_and_b32_e32 v219, 0xffff0000, v35
	v_mul_f32_e32 v216, v225, v216
	v_mul_f32_e32 v217, v225, v217
	v_mul_f32_e32 v218, v225, v218
	v_mul_f32_e32 v219, v225, v219
	v_fmac_f32_e32 v4, v100, v216
	v_fmac_f32_e32 v5, v101, v217
	v_fmac_f32_e32 v6, v102, v218
	v_fmac_f32_e32 v7, v103, v219
	v_lshlrev_b32_e32 v216, 16, v36
	v_and_b32_e32 v217, 0xffff0000, v36
	v_lshlrev_b32_e32 v218, 16, v37
	v_and_b32_e32 v219, 0xffff0000, v37
	v_mul_f32_e32 v216, v225, v216
	v_mul_f32_e32 v217, v225, v217
	v_mul_f32_e32 v218, v225, v218
	v_mul_f32_e32 v219, v225, v219
	v_fmac_f32_e32 v8, v104, v216
	v_fmac_f32_e32 v9, v105, v217
	v_fmac_f32_e32 v10, v106, v218
	v_fmac_f32_e32 v11, v107, v219
	v_lshlrev_b32_e32 v216, 16, v38
	v_and_b32_e32 v217, 0xffff0000, v38
	v_lshlrev_b32_e32 v218, 16, v39
	v_and_b32_e32 v219, 0xffff0000, v39
	v_mul_f32_e32 v216, v225, v216
	v_mul_f32_e32 v217, v225, v217
	v_mul_f32_e32 v218, v225, v218
	v_mul_f32_e32 v219, v225, v219
	v_fmac_f32_e32 v12, v108, v216
	v_fmac_f32_e32 v13, v109, v217
	v_fmac_f32_e32 v14, v110, v218
	v_fmac_f32_e32 v15, v111, v219
	v_lshlrev_b32_e32 v216, 16, v40
	v_and_b32_e32 v217, 0xffff0000, v40
	v_lshlrev_b32_e32 v218, 16, v41
	v_and_b32_e32 v219, 0xffff0000, v41
	v_mul_f32_e32 v216, v225, v216
	v_mul_f32_e32 v217, v225, v217
	v_mul_f32_e32 v218, v225, v218
	v_mul_f32_e32 v219, v225, v219
	v_fmac_f32_e32 v16, v112, v216
	v_fmac_f32_e32 v17, v113, v217
	v_fmac_f32_e32 v18, v114, v218
	v_fmac_f32_e32 v19, v115, v219
	v_lshlrev_b32_e32 v216, 16, v42
	v_and_b32_e32 v217, 0xffff0000, v42
	v_lshlrev_b32_e32 v218, 16, v43
	v_and_b32_e32 v219, 0xffff0000, v43
	v_mul_f32_e32 v216, v225, v216
	v_mul_f32_e32 v217, v225, v217
	v_mul_f32_e32 v218, v225, v218
	v_mul_f32_e32 v219, v225, v219
	v_fmac_f32_e32 v20, v116, v216
	v_fmac_f32_e32 v21, v117, v217
	v_fmac_f32_e32 v22, v118, v218
	v_fmac_f32_e32 v23, v119, v219
	v_lshlrev_b32_e32 v216, 16, v44
	v_and_b32_e32 v217, 0xffff0000, v44
	v_lshlrev_b32_e32 v218, 16, v45
	v_and_b32_e32 v219, 0xffff0000, v45
	v_mul_f32_e32 v216, v225, v216
	v_mul_f32_e32 v217, v225, v217
	v_mul_f32_e32 v218, v225, v218
	v_mul_f32_e32 v219, v225, v219
	v_fmac_f32_e32 v24, v120, v216
	v_fmac_f32_e32 v25, v121, v217
	v_fmac_f32_e32 v26, v122, v218
; __device__ __forceinline__ unsigned cvt_pk_bf16(float lo, float hi) { unsigned r; asm volatile("v_cvt_pk_bf16_f32 %0, %1, %2" : "=v"(r) : "v"(lo), "v"(hi)); return r; }
; __device__ __forceinline__ float sumsq8(const f32x4 (&v)[8]) {
;     float s = 0.f;
; #pragma unroll
;     for (int j = 0; j < 8; ++j) s += (v[j][0] * v[j][0] + v[j][1] * v[j][1]) + (v[j][2] * v[j][2] + v[j][3] * v[j][3]);
;     return wave_sum(s);
; }
; __device__ __forceinline__ void modulate_store(const f32x4 (&v)[8], float rstd, const float* pn, const float* modr, bf16_t* orow, int lane) {
; #pragma unroll
;     for (int j = 0; j < 8; ++j) { const int col = 4 * lane + 256 * j;
;         const f32x4 g = *(const f32x4*)(pn + col), sh = *(const f32x4*)(modr + col), sc = *(const f32x4*)(modr + DM + col);
;         const f32x4 hh = v[j] * rstd * g * (sc + 1.f) + sh;
;         u32x2 w; w.x = cvt_pk_bf16(hh[0], hh[1]); w.y = cvt_pk_bf16(hh[2], hh[3]);
;         *(u32x2*)(orow + col) = w; }
; __global__ void __launch_bounds__(NWAVES * 64, 2) mk_fwd(Args args) {
;     ...
;                 const float rstd = __builtin_amdgcn_rsqf(sumsq8(v[q]) * (1.f / DM) + EPS);
;                 modulate_store(v[q], rstd, pre_norm + DM, mod + (size_t)(9 + r) * 6144, H + (size_t)row * DM, F.lane); }
	v_fmac_f32_e32 v27, v123, v219
	v_lshlrev_b32_e32 v216, 16, v46
	v_and_b32_e32 v217, 0xffff0000, v46
	v_lshlrev_b32_e32 v218, 16, v47
	v_and_b32_e32 v219, 0xffff0000, v47
	v_mul_f32_e32 v216, v225, v216
	v_mul_f32_e32 v217, v225, v217
	v_mul_f32_e32 v218, v225, v218
	v_mul_f32_e32 v219, v225, v219
	v_fmac_f32_e32 v28, v124, v216
	v_fmac_f32_e32 v29, v125, v217
	v_fmac_f32_e32 v30, v126, v218
	v_fmac_f32_e32 v31, v127, v219
	v_mul_f32_e32 v222, v0, v0
	v_mul_f32_e32 v223, v1, v1
	v_fmac_f32_e32 v222, v2, v2
	v_fmac_f32_e32 v223, v3, v3
	v_fmac_f32_e32 v222, v4, v4
	v_fmac_f32_e32 v223, v5, v5
	v_fmac_f32_e32 v222, v6, v6
	v_fmac_f32_e32 v223, v7, v7
	v_fmac_f32_e32 v222, v8, v8
	v_fmac_f32_e32 v223, v9, v9
	v_fmac_f32_e32 v222, v10, v10
	v_fmac_f32_e32 v223, v11, v11
	v_fmac_f32_e32 v222, v12, v12
	v_fmac_f32_e32 v223, v13, v13
	v_fmac_f32_e32 v222, v14, v14
	v_fmac_f32_e32 v223, v15, v15
	v_fmac_f32_e32 v222, v16, v16
	v_fmac_f32_e32 v223, v17, v17
	v_fmac_f32_e32 v222, v18, v18
	v_fmac_f32_e32 v223, v19, v19
	v_fmac_f32_e32 v222, v20, v20
	v_fmac_f32_e32 v223, v21, v21
	v_fmac_f32_e32 v222, v22, v22
	v_fmac_f32_e32 v223, v23, v23
	v_fmac_f32_e32 v222, v24, v24
	v_fmac_f32_e32 v223, v25, v25
	v_fmac_f32_e32 v222, v26, v26
	v_fmac_f32_e32 v223, v27, v27
	v_fmac_f32_e32 v222, v28, v28
	v_fmac_f32_e32 v223, v29, v29
	v_fmac_f32_e32 v222, v30, v30
	v_fmac_f32_e32 v223, v31, v31
	v_add_f32_e32 v222, v222, v223
	s_nop 1
	v_add_f32_dpp v224, v222, v222 quad_perm:[1,0,3,2] row_mask:0xf bank_mask:0xf
	s_nop 1
	v_add_f32_dpp v224, v224, v224 quad_perm:[2,3,0,1] row_mask:0xf bank_mask:0xf
	s_nop 1
	v_add_f32_dpp v224, v224, v224 row_half_mirror row_mask:0xf bank_mask:0xf
	s_nop 1
	v_add_f32_dpp v224, v224, v224 row_mirror row_mask:0xf bank_mask:0xf
	s_nop 1
	v_readlane_b32 s40, v224, 0
	v_readlane_b32 s41, v224, 16
	v_readlane_b32 s42, v224, 32
	v_readlane_b32 s43, v224, 48
	s_nop 1
	v_mov_b32_e32 v225, s40
	v_add_f32_e32 v225, s41, v225
	v_add_f32_e32 v225, s42, v225
	v_add_f32_e32 v225, s43, v225
	v_fmamk_f32 v225, v225, 0x3a000000, v195
	v_rsq_f32_e32 v225, v225
	s_nop 0
	s_add_i32 s0, s6, 4
	s_lshl_b32 s1, s0, 12
	s_add_u32 s26, s84, s1
	s_addc_u32 s27, s85, 0
	s_add_u32 s26, s26, 0xd000000
	s_addc_u32 s27, s27, 0
	v_mul_f32_e32 v216, v225, v0
	v_mul_f32_e32 v217, v225, v1
	v_mul_f32_e32 v218, v225, v2
	v_mul_f32_e32 v219, v225, v3
	v_fma_f32 v216, v216, v128, v160
	v_fma_f32 v217, v217, v129, v161
	v_fma_f32 v218, v218, v130, v162
	v_fma_f32 v219, v219, v131, v163
	v_cvt_pk_bf16_f32 v196, v216, v217
	v_cvt_pk_bf16_f32 v197, v218, v219
	global_store_dwordx2 v194, v[196:197], s[26:27] offset:0
	v_mul_f32_e32 v216, v225, v4
	v_mul_f32_e32 v217, v225, v5
	v_mul_f32_e32 v218, v225, v6
	v_mul_f32_e32 v219, v225, v7
	v_fma_f32 v216, v216, v132, v164
	v_fma_f32 v217, v217, v133, v165
	v_fma_f32 v218, v218, v134, v166
	v_fma_f32 v219, v219, v135, v167
	v_cvt_pk_bf16_f32 v220, v216, v217
	v_cvt_pk_bf16_f32 v221, v218, v219
	global_store_dwordx2 v194, v[220:221], s[26:27] offset:512
	v_mul_f32_e32 v216, v225, v8
	v_mul_f32_e32 v217, v225, v9
	v_mul_f32_e32 v218, v225, v10
	v_mul_f32_e32 v219, v225, v11
	v_fma_f32 v216, v216, v136, v168
	v_fma_f32 v217, v217, v137, v169
	v_fma_f32 v218, v218, v138, v170
	v_fma_f32 v219, v219, v139, v171
	v_cvt_pk_bf16_f32 v196, v216, v217
	v_cvt_pk_bf16_f32 v197, v218, v219
	global_store_dwordx2 v194, v[196:197], s[26:27] offset:1024
	v_mul_f32_e32 v216, v225, v12
	v_mul_f32_e32 v217, v225, v13
	v_mul_f32_e32 v218, v225, v14
	v_mul_f32_e32 v219, v225, v15
	v_fma_f32 v216, v216, v140, v172
	v_fma_f32 v217, v217, v141, v173
	v_fma_f32 v218, v218, v142, v174
	v_fma_f32 v219, v219, v143, v175
	v_cvt_pk_bf16_f32 v220, v216, v217
	v_cvt_pk_bf16_f32 v221, v218, v219
	global_store_dwordx2 v194, v[220:221], s[26:27] offset:1536
	v_mul_f32_e32 v216, v225, v16
	v_mul_f32_e32 v217, v225, v17
	v_mul_f32_e32 v218, v225, v18
	v_mul_f32_e32 v219, v225, v19
	v_fma_f32 v216, v216, v144, v176
	v_fma_f32 v217, v217, v145, v177
	v_fma_f32 v218, v218, v146, v178
	v_fma_f32 v219, v219, v147, v179
	v_cvt_pk_bf16_f32 v196, v216, v217
	v_cvt_pk_bf16_f32 v197, v218, v219
	global_store_dwordx2 v194, v[196:197], s[26:27] offset:2048
	v_mul_f32_e32 v216, v225, v20
	v_mul_f32_e32 v217, v225, v21
	v_mul_f32_e32 v218, v225, v22
	v_mul_f32_e32 v219, v225, v23
	v_fma_f32 v216, v216, v148, v180
	v_fma_f32 v217, v217, v149, v181
	v_fma_f32 v218, v218, v150, v182
	v_fma_f32 v219, v219, v151, v183
	v_cvt_pk_bf16_f32 v220, v216, v217
	v_cvt_pk_bf16_f32 v221, v218, v219
	global_store_dwordx2 v194, v[220:221], s[26:27] offset:2560
	v_mul_f32_e32 v216, v225, v24
	v_mul_f32_e32 v217, v225, v25
	v_mul_f32_e32 v218, v225, v26
	v_mul_f32_e32 v219, v225, v27
	v_fma_f32 v216, v216, v152, v184
	v_fma_f32 v217, v217, v153, v185
	v_fma_f32 v218, v218, v154, v186
	v_fma_f32 v219, v219, v155, v187
	v_cvt_pk_bf16_f32 v196, v216, v217
	v_cvt_pk_bf16_f32 v197, v218, v219
	global_store_dwordx2 v194, v[196:197], s[26:27] offset:3072
	v_mul_f32_e32 v216, v225, v28
	v_mul_f32_e32 v217, v225, v29
	v_mul_f32_e32 v218, v225, v30
	v_mul_f32_e32 v219, v225, v31
	v_fma_f32 v216, v216, v156, v188
	v_fma_f32 v217, v217, v157, v189
	v_fma_f32 v218, v218, v158, v190
	v_fma_f32 v219, v219, v159, v191
	v_cvt_pk_bf16_f32 v220, v216, v217
	v_cvt_pk_bf16_f32 v221, v218, v219
	global_store_dwordx2 v194, v[220:221], s[26:27] offset:3584
	s_add_i32 s0, s6, 6
	s_cmp_lt_u32 s0, 0x4000
	s_cselect_b32 s10, s68, s72
	s_cselect_b32 s11, s69, s73
	s_cselect_b32 s1, 0, 0x4000
	s_sub_i32 s1, s0, s1
	s_lshl_b32 s1, s1, 13
	s_add_u32 s10, s10, s1
	s_addc_u32 s11, s11, 0
	s_add_i32 s0, s6, 6
	s_lshl_b32 s1, s0, 12
	s_add_u32 s22, s84, s1
	s_addc_u32 s23, s85, 0
	s_add_u32 s22, s22, 0x11800000
	s_addc_u32 s23, s23, 0
	global_load_dwordx4 v[0:3], v192, s[10:11] offset:0 nt
	global_load_dwordx4 v[4:7], v192, s[10:11] offset:1024 nt
	global_load_dwordx4 v[8:11], v192, s[10:11] offset:2048 nt
	global_load_dwordx4 v[12:15], v192, s[10:11] offset:3072 nt
	global_load_dwordx4 v[16:19], v193, s[10:11] offset:0 nt
	global_load_dwordx4 v[20:23], v193, s[10:11] offset:1024 nt
	global_load_dwordx4 v[24:27], v193, s[10:11] offset:2048 nt
	global_load_dwordx4 v[28:31], v193, s[10:11] offset:3072 nt
	global_load_dwordx2 v[32:33], v194, s[22:23] offset:0 nt
	global_load_dwordx2 v[34:35], v194, s[22:23] offset:512 nt
	global_load_dwordx2 v[36:37], v194, s[22:23] offset:1024 nt
	global_load_dwordx2 v[38:39], v194, s[22:23] offset:1536 nt
	global_load_dwordx2 v[40:41], v194, s[22:23] offset:2048 nt
	global_load_dwordx2 v[42:43], v194, s[22:23] offset:2560 nt
	global_load_dwordx2 v[44:45], v194, s[22:23] offset:3072 nt
	global_load_dwordx2 v[46:47], v194, s[22:23] offset:3584 nt
	s_add_i32 s0, s6, 5
	s_add_i32 s0, s6, 5
	s_lshr_b32 s8, s0, 11
	s_cmp_lt_u32 s0, 0x4000
	s_cselect_b32 s8, s8, 8
	s_cmp_eq_u32 s8, s7
	s_cbranch_scc1 .Lp6_np5
; __device__ __forceinline__ void modulate_store(const f32x4 (&v)[8], float rstd, const float* pn, const float* modr, bf16_t* orow, int lane) {
; #pragma unroll
;     for (int j = 0; j < 8; ++j) { const int col = 4 * lane + 256 * j;
;         const f32x4 g = *(const f32x4*)(pn + col), sh = *(const f32x4*)(modr + col), sc = *(const f32x4*)(modr + DM + col);
;         const f32x4 hh = v[j] * rstd * g * (sc + 1.f) + sh;
; __global__ void __launch_bounds__(NWAVES * 64, 2) mk_fwd(Args args) {
;     ...
;                 const float* m0 = mod + (size_t)r * 6144;
; #pragma unroll
;                 for (int j = 0; j < 8; ++j) { const int col = 4 * F.lane + 256 * j; const f32x4 gt = *(const f32x4*)(m0 + 2 * DM + col), pn = *(const f32x4*)(post_norm + col);
	s_mov_b32 s7, s8
	s_add_i32 s1, s8, 9
	s_mul_i32 s1, s1, 0x6000
	s_add_u32 s44, s84, s1
	s_addc_u32 s45, s85, 0
	s_add_u32 s44, s44, 0x2000
	s_addc_u32 s45, s45, 0
	s_add_i32 s1, s8, 9
	s_mul_i32 s1, s1, 0x6000
	s_add_u32 s36, s84, s1
	s_addc_u32 s37, s85, 0
	s_add_u32 s38, s80, 0x2000
	s_addc_u32 s39, s81, 0
	s_mul_i32 s1, s8, 0x6000
	s_add_u32 s34, s84, s1
	s_addc_u32 s35, s85, 0
	s_add_u32 s34, s34, 0x4000
	s_addc_u32 s35, s35, 0
	global_load_dwordx4 v[96:99], v192, s[34:35] offset:0
	global_load_dwordx4 v[200:203], v192, s[82:83] offset:0
	global_load_dwordx4 v[100:103], v192, s[34:35] offset:1024
	global_load_dwordx4 v[204:207], v192, s[82:83] offset:1024
	global_load_dwordx4 v[104:107], v192, s[34:35] offset:2048
	global_load_dwordx4 v[208:211], v192, s[82:83] offset:2048
	global_load_dwordx4 v[108:111], v192, s[34:35] offset:3072
	global_load_dwordx4 v[212:215], v192, s[82:83] offset:3072
	s_waitcnt vmcnt(0)
	v_mul_f32_e32 v96, v96, v200
	v_mul_f32_e32 v97, v97, v201
	v_mul_f32_e32 v98, v98, v202
	v_mul_f32_e32 v99, v99, v203
	v_mul_f32_e32 v100, v100, v204
	v_mul_f32_e32 v101, v101, v205
	v_mul_f32_e32 v102, v102, v206
	v_mul_f32_e32 v103, v103, v207
	v_mul_f32_e32 v104, v104, v208
	v_mul_f32_e32 v105, v105, v209
	v_mul_f32_e32 v106, v106, v210
	v_mul_f32_e32 v107, v107, v211
	v_mul_f32_e32 v108, v108, v212
	v_mul_f32_e32 v109, v109, v213
	v_mul_f32_e32 v110, v110, v214
	v_mul_f32_e32 v111, v111, v215
	global_load_dwordx4 v[128:131], v192, s[38:39] offset:0
	global_load_dwordx4 v[200:203], v192, s[44:45] offset:0
	global_load_dwordx4 v[160:163], v192, s[36:37] offset:0
	global_load_dwordx4 v[132:135], v192, s[38:39] offset:1024
	global_load_dwordx4 v[204:207], v192, s[44:45] offset:1024
	global_load_dwordx4 v[164:167], v192, s[36:37] offset:1024
	global_load_dwordx4 v[136:139], v192, s[38:39] offset:2048
	global_load_dwordx4 v[208:211], v192, s[44:45] offset:2048
	global_load_dwordx4 v[168:171], v192, s[36:37] offset:2048
	global_load_dwordx4 v[140:143], v192, s[38:39] offset:3072
	global_load_dwordx4 v[212:215], v192, s[44:45] offset:3072
	global_load_dwordx4 v[172:175], v192, s[36:37] offset:3072
	s_waitcnt vmcnt(0)
	v_add_f32_e32 v200, 1.0, v200
	v_add_f32_e32 v201, 1.0, v201
	v_add_f32_e32 v202, 1.0, v202
	v_add_f32_e32 v203, 1.0, v203
	v_mul_f32_e32 v128, v128, v200
	v_mul_f32_e32 v129, v129, v201
	v_mul_f32_e32 v130, v130, v202
	v_mul_f32_e32 v131, v131, v203
	v_add_f32_e32 v204, 1.0, v204
	v_add_f32_e32 v205, 1.0, v205
	v_add_f32_e32 v206, 1.0, v206
	v_add_f32_e32 v207, 1.0, v207
	v_mul_f32_e32 v132, v132, v204
	v_mul_f32_e32 v133, v133, v205
	v_mul_f32_e32 v134, v134, v206
	v_mul_f32_e32 v135, v135, v207
	v_add_f32_e32 v208, 1.0, v208
	v_add_f32_e32 v209, 1.0, v209
	v_add_f32_e32 v210, 1.0, v210
	v_add_f32_e32 v211, 1.0, v211
	v_mul_f32_e32 v136, v136, v208
	v_mul_f32_e32 v137, v137, v209
	v_mul_f32_e32 v138, v138, v210
	v_mul_f32_e32 v139, v139, v211
	v_add_f32_e32 v212, 1.0, v212
	v_add_f32_e32 v213, 1.0, v213
	v_add_f32_e32 v214, 1.0, v214
	v_add_f32_e32 v215, 1.0, v215
	v_mul_f32_e32 v140, v140, v212
	v_mul_f32_e32 v141, v141, v213
	v_mul_f32_e32 v142, v142, v214
	v_mul_f32_e32 v143, v143, v215
	global_load_dwordx4 v[112:115], v193, s[34:35] offset:0
	global_load_dwordx4 v[200:203], v193, s[82:83] offset:0
	global_load_dwordx4 v[116:119], v193, s[34:35] offset:1024
	global_load_dwordx4 v[204:207], v193, s[82:83] offset:1024
	global_load_dwordx4 v[120:123], v193, s[34:35] offset:2048
	global_load_dwordx4 v[208:211], v193, s[82:83] offset:2048
	global_load_dwordx4 v[124:127], v193, s[34:35] offset:3072
	global_load_dwordx4 v[212:215], v193, s[82:83] offset:3072
	s_waitcnt vmcnt(0)
	v_mul_f32_e32 v112, v112, v200
	v_mul_f32_e32 v113, v113, v201
	v_mul_f32_e32 v114, v114, v202
	v_mul_f32_e32 v115, v115, v203
	v_mul_f32_e32 v116, v116, v204
	v_mul_f32_e32 v117, v117, v205
	v_mul_f32_e32 v118, v118, v206
	v_mul_f32_e32 v119, v119, v207
	v_mul_f32_e32 v120, v120, v208
	v_mul_f32_e32 v121, v121, v209
	v_mul_f32_e32 v122, v122, v210
	v_mul_f32_e32 v123, v123, v211
	v_mul_f32_e32 v124, v124, v212
	v_mul_f32_e32 v125, v125, v213
	v_mul_f32_e32 v126, v126, v214
	v_mul_f32_e32 v127, v127, v215
	global_load_dwordx4 v[144:147], v193, s[38:39] offset:0
	global_load_dwordx4 v[200:203], v193, s[44:45] offset:0
	global_load_dwordx4 v[176:179], v193, s[36:37] offset:0
	global_load_dwordx4 v[148:151], v193, s[38:39] offset:1024
	global_load_dwordx4 v[204:207], v193, s[44:45] offset:1024
	global_load_dwordx4 v[180:183], v193, s[36:37] offset:1024
	global_load_dwordx4 v[152:155], v193, s[38:39] offset:2048
	global_load_dwordx4 v[208:211], v193, s[44:45] offset:2048
	global_load_dwordx4 v[184:187], v193, s[36:37] offset:2048
	global_load_dwordx4 v[156:159], v193, s[38:39] offset:3072
	global_load_dwordx4 v[212:215], v193, s[44:45] offset:3072
	global_load_dwordx4 v[188:191], v193, s[36:37] offset:3072
	s_waitcnt vmcnt(0)
	v_add_f32_e32 v200, 1.0, v200
	v_add_f32_e32 v201, 1.0, v201
	v_add_f32_e32 v202, 1.0, v202
	v_add_f32_e32 v203, 1.0, v203
	v_mul_f32_e32 v144, v144, v200
	v_mul_f32_e32 v145, v145, v201
	v_mul_f32_e32 v146, v146, v202
	v_mul_f32_e32 v147, v147, v203
	v_add_f32_e32 v204, 1.0, v204
	v_add_f32_e32 v205, 1.0, v205
	v_add_f32_e32 v206, 1.0, v206
	v_add_f32_e32 v207, 1.0, v207
	v_mul_f32_e32 v148, v148, v204
	v_mul_f32_e32 v149, v149, v205
	v_mul_f32_e32 v150, v150, v206
	v_mul_f32_e32 v151, v151, v207
	v_add_f32_e32 v208, 1.0, v208
	v_add_f32_e32 v209, 1.0, v209
	v_add_f32_e32 v210, 1.0, v210
	v_add_f32_e32 v211, 1.0, v211
	v_mul_f32_e32 v152, v152, v208
	v_mul_f32_e32 v153, v153, v209
	v_mul_f32_e32 v154, v154, v210
	v_mul_f32_e32 v155, v155, v211
	v_add_f32_e32 v212, 1.0, v212
	v_add_f32_e32 v213, 1.0, v213
	v_add_f32_e32 v214, 1.0, v214
	v_add_f32_e32 v215, 1.0, v215
	v_mul_f32_e32 v156, v156, v212
	v_mul_f32_e32 v157, v157, v213
	v_mul_f32_e32 v158, v158, v214
	v_mul_f32_e32 v159, v159, v215
; __device__ __forceinline__ float bf_lo(unsigned w) { return __uint_as_float(w << 16); }
; __device__ __forceinline__ float bf_hi(unsigned w) { return __uint_as_float(w & 0xffff0000u); }
; __global__ void __launch_bounds__(NWAVES * 64, 2) mk_fwd(Args args) {
;     ...
;                 float sy = 0.f;
; #pragma unroll
;                 for (int j = 0; j < 8; ++j) { const float a = bf_lo(yw[q][j].x), b = bf_hi(yw[q][j].x), c2 = bf_lo(yw[q][j].y), d = bf_hi(yw[q][j].y); sy += (a * a + b * b) + (c2 * c2 + d * d); }
;                 const float rsy = __builtin_amdgcn_rsqf(wave_sum(sy) * (1.f / DM) + EPS);
;                 const float* m0 = mod + (size_t)r * 6144;
; #pragma unroll
;                 for (int j = 0; j < 8; ++j) { const int col = 4 * F.lane + 256 * j; const f32x4 gt = *(const f32x4*)(m0 + 2 * DM + col), pn = *(const f32x4*)(post_norm + col);
;                     const f32x4 y4 = (f32x4){bf_lo(yw[q][j].x), bf_hi(yw[q][j].x), bf_lo(yw[q][j].y), bf_hi(yw[q][j].y)};
;                     v[q][j] = v[q][j] + gt * (y4 * rsy * pn);
.Lp6_np5:
	s_waitcnt vmcnt(24)
	v_lshlrev_b32_e32 v216, 16, v80
	v_and_b32_e32 v217, 0xffff0000, v80
	v_lshlrev_b32_e32 v218, 16, v81
	v_and_b32_e32 v219, 0xffff0000, v81
	v_mul_f32_e32 v222, v216, v216
	v_mul_f32_e32 v223, v217, v217
	v_fmac_f32_e32 v222, v218, v218
	v_fmac_f32_e32 v223, v219, v219
	v_lshlrev_b32_e32 v216, 16, v82
	v_and_b32_e32 v217, 0xffff0000, v82
	v_lshlrev_b32_e32 v218, 16, v83
	v_and_b32_e32 v219, 0xffff0000, v83
	v_fmac_f32_e32 v222, v216, v216
	v_fmac_f32_e32 v223, v217, v217
	v_fmac_f32_e32 v222, v218, v218
	v_fmac_f32_e32 v223, v219, v219
	v_lshlrev_b32_e32 v216, 16, v84
	v_and_b32_e32 v217, 0xffff0000, v84
	v_lshlrev_b32_e32 v218, 16, v85
	v_and_b32_e32 v219, 0xffff0000, v85
	v_fmac_f32_e32 v222, v216, v216
	v_fmac_f32_e32 v223, v217, v217
	v_fmac_f32_e32 v222, v218, v218
	v_fmac_f32_e32 v223, v219, v219
	v_lshlrev_b32_e32 v216, 16, v86
	v_and_b32_e32 v217, 0xffff0000, v86
	v_lshlrev_b32_e32 v218, 16, v87
	v_and_b32_e32 v219, 0xffff0000, v87
	v_fmac_f32_e32 v222, v216, v216
	v_fmac_f32_e32 v223, v217, v217
	v_fmac_f32_e32 v222, v218, v218
	v_fmac_f32_e32 v223, v219, v219
	v_lshlrev_b32_e32 v216, 16, v88
	v_and_b32_e32 v217, 0xffff0000, v88
	v_lshlrev_b32_e32 v218, 16, v89
	v_and_b32_e32 v219, 0xffff0000, v89
	v_fmac_f32_e32 v222, v216, v216
	v_fmac_f32_e32 v223, v217, v217
	v_fmac_f32_e32 v222, v218, v218
	v_fmac_f32_e32 v223, v219, v219
	v_lshlrev_b32_e32 v216, 16, v90
	v_and_b32_e32 v217, 0xffff0000, v90
	v_lshlrev_b32_e32 v218, 16, v91
	v_and_b32_e32 v219, 0xffff0000, v91
	v_fmac_f32_e32 v222, v216, v216
	v_fmac_f32_e32 v223, v217, v217
	v_fmac_f32_e32 v222, v218, v218
	v_fmac_f32_e32 v223, v219, v219
	v_lshlrev_b32_e32 v216, 16, v92
	v_and_b32_e32 v217, 0xffff0000, v92
	v_lshlrev_b32_e32 v218, 16, v93
	v_and_b32_e32 v219, 0xffff0000, v93
	v_fmac_f32_e32 v222, v216, v216
	v_fmac_f32_e32 v223, v217, v217
	v_fmac_f32_e32 v222, v218, v218
	v_fmac_f32_e32 v223, v219, v219
	v_lshlrev_b32_e32 v216, 16, v94
	v_and_b32_e32 v217, 0xffff0000, v94
	v_lshlrev_b32_e32 v218, 16, v95
	v_and_b32_e32 v219, 0xffff0000, v95
	v_fmac_f32_e32 v222, v216, v216
	v_fmac_f32_e32 v223, v217, v217
	v_fmac_f32_e32 v222, v218, v218
	v_fmac_f32_e32 v223, v219, v219
	v_add_f32_e32 v222, v222, v223
	s_nop 1
	v_add_f32_dpp v224, v222, v222 quad_perm:[1,0,3,2] row_mask:0xf bank_mask:0xf
	s_nop 1
	v_add_f32_dpp v224, v224, v224 quad_perm:[2,3,0,1] row_mask:0xf bank_mask:0xf
	s_nop 1
	v_add_f32_dpp v224, v224, v224 row_half_mirror row_mask:0xf bank_mask:0xf
	s_nop 1
	v_add_f32_dpp v224, v224, v224 row_mirror row_mask:0xf bank_mask:0xf
	s_nop 1
	v_readlane_b32 s40, v224, 0
	v_readlane_b32 s41, v224, 16
	v_readlane_b32 s42, v224, 32
	v_readlane_b32 s43, v224, 48
	s_nop 1
	v_mov_b32_e32 v225, s40
	v_add_f32_e32 v225, s41, v225
	v_add_f32_e32 v225, s42, v225
	v_add_f32_e32 v225, s43, v225
	v_fmamk_f32 v225, v225, 0x3a000000, v195
	v_rsq_f32_e32 v225, v225
	s_nop 0
	v_lshlrev_b32_e32 v216, 16, v80
	v_and_b32_e32 v217, 0xffff0000, v80
	v_lshlrev_b32_e32 v218, 16, v81
	v_and_b32_e32 v219, 0xffff0000, v81
	v_mul_f32_e32 v216, v225, v216
	v_mul_f32_e32 v217, v225, v217
	v_mul_f32_e32 v218, v225, v218
	v_mul_f32_e32 v219, v225, v219
	v_fmac_f32_e32 v48, v96, v216
	v_fmac_f32_e32 v49, v97, v217
	v_fmac_f32_e32 v50, v98, v218
	v_fmac_f32_e32 v51, v99, v219
	v_lshlrev_b32_e32 v216, 16, v82
	v_and_b32_e32 v217, 0xffff0000, v82
	v_lshlrev_b32_e32 v218, 16, v83
	v_and_b32_e32 v219, 0xffff0000, v83
	v_mul_f32_e32 v216, v225, v216
	v_mul_f32_e32 v217, v225, v217
	v_mul_f32_e32 v218, v225, v218
	v_mul_f32_e32 v219, v225, v219
	v_fmac_f32_e32 v52, v100, v216
	v_fmac_f32_e32 v53, v101, v217
	v_fmac_f32_e32 v54, v102, v218
	v_fmac_f32_e32 v55, v103, v219
	v_lshlrev_b32_e32 v216, 16, v84
	v_and_b32_e32 v217, 0xffff0000, v84
	v_lshlrev_b32_e32 v218, 16, v85
	v_and_b32_e32 v219, 0xffff0000, v85
	v_mul_f32_e32 v216, v225, v216
	v_mul_f32_e32 v217, v225, v217
	v_mul_f32_e32 v218, v225, v218
	v_mul_f32_e32 v219, v225, v219
	v_fmac_f32_e32 v56, v104, v216
	v_fmac_f32_e32 v57, v105, v217
	v_fmac_f32_e32 v58, v106, v218
	v_fmac_f32_e32 v59, v107, v219
	v_lshlrev_b32_e32 v216, 16, v86
	v_and_b32_e32 v217, 0xffff0000, v86
	v_lshlrev_b32_e32 v218, 16, v87
	v_and_b32_e32 v219, 0xffff0000, v87
	v_mul_f32_e32 v216, v225, v216
	v_mul_f32_e32 v217, v225, v217
	v_mul_f32_e32 v218, v225, v218
	v_mul_f32_e32 v219, v225, v219
	v_fmac_f32_e32 v60, v108, v216
	v_fmac_f32_e32 v61, v109, v217
	v_fmac_f32_e32 v62, v110, v218
	v_fmac_f32_e32 v63, v111, v219
	v_lshlrev_b32_e32 v216, 16, v88
	v_and_b32_e32 v217, 0xffff0000, v88
	v_lshlrev_b32_e32 v218, 16, v89
	v_and_b32_e32 v219, 0xffff0000, v89
	v_mul_f32_e32 v216, v225, v216
	v_mul_f32_e32 v217, v225, v217
	v_mul_f32_e32 v218, v225, v218
	v_mul_f32_e32 v219, v225, v219
	v_fmac_f32_e32 v64, v112, v216
	v_fmac_f32_e32 v65, v113, v217
	v_fmac_f32_e32 v66, v114, v218
	v_fmac_f32_e32 v67, v115, v219
	v_lshlrev_b32_e32 v216, 16, v90
	v_and_b32_e32 v217, 0xffff0000, v90
	v_lshlrev_b32_e32 v218, 16, v91
	v_and_b32_e32 v219, 0xffff0000, v91
	v_mul_f32_e32 v216, v225, v216
	v_mul_f32_e32 v217, v225, v217
	v_mul_f32_e32 v218, v225, v218
	v_mul_f32_e32 v219, v225, v219
	v_fmac_f32_e32 v68, v116, v216
	v_fmac_f32_e32 v69, v117, v217
	v_fmac_f32_e32 v70, v118, v218
	v_fmac_f32_e32 v71, v119, v219
	v_lshlrev_b32_e32 v216, 16, v92
	v_and_b32_e32 v217, 0xffff0000, v92
	v_lshlrev_b32_e32 v218, 16, v93
	v_and_b32_e32 v219, 0xffff0000, v93
	v_mul_f32_e32 v216, v225, v216
	v_mul_f32_e32 v217, v225, v217
	v_mul_f32_e32 v218, v225, v218
	v_mul_f32_e32 v219, v225, v219
	v_fmac_f32_e32 v72, v120, v216
	v_fmac_f32_e32 v73, v121, v217
	v_fmac_f32_e32 v74, v122, v218
; __device__ __forceinline__ unsigned cvt_pk_bf16(float lo, float hi) { unsigned r; asm volatile("v_cvt_pk_bf16_f32 %0, %1, %2" : "=v"(r) : "v"(lo), "v"(hi)); return r; }
; __device__ __forceinline__ float sumsq8(const f32x4 (&v)[8]) {
;     float s = 0.f;
; #pragma unroll
;     for (int j = 0; j < 8; ++j) s += (v[j][0] * v[j][0] + v[j][1] * v[j][1]) + (v[j][2] * v[j][2] + v[j][3] * v[j][3]);
;     return wave_sum(s);
; }
; __device__ __forceinline__ void modulate_store(const f32x4 (&v)[8], float rstd, const float* pn, const float* modr, bf16_t* orow, int lane) {
; #pragma unroll
;     for (int j = 0; j < 8; ++j) { const int col = 4 * lane + 256 * j;
;         const f32x4 g = *(const f32x4*)(pn + col), sh = *(const f32x4*)(modr + col), sc = *(const f32x4*)(modr + DM + col);
;         const f32x4 hh = v[j] * rstd * g * (sc + 1.f) + sh;
;         u32x2 w; w.x = cvt_pk_bf16(hh[0], hh[1]); w.y = cvt_pk_bf16(hh[2], hh[3]);
;         *(u32x2*)(orow + col) = w; }
; __global__ void __launch_bounds__(NWAVES * 64, 2) mk_fwd(Args args) {
;     ...
;                 const float rstd = __builtin_amdgcn_rsqf(sumsq8(v[q]) * (1.f / DM) + EPS);
;                 modulate_store(v[q], rstd, pre_norm + DM, mod + (size_t)(9 + r) * 6144, H + (size_t)row * DM, F.lane); }
	v_fmac_f32_e32 v75, v123, v219
	v_lshlrev_b32_e32 v216, 16, v94
	v_and_b32_e32 v217, 0xffff0000, v94
	v_lshlrev_b32_e32 v218, 16, v95
	v_and_b32_e32 v219, 0xffff0000, v95
	v_mul_f32_e32 v216, v225, v216
	v_mul_f32_e32 v217, v225, v217
	v_mul_f32_e32 v218, v225, v218
	v_mul_f32_e32 v219, v225, v219
	v_fmac_f32_e32 v76, v124, v216
	v_fmac_f32_e32 v77, v125, v217
	v_fmac_f32_e32 v78, v126, v218
	v_fmac_f32_e32 v79, v127, v219
	v_mul_f32_e32 v222, v48, v48
	v_mul_f32_e32 v223, v49, v49
	v_fmac_f32_e32 v222, v50, v50
	v_fmac_f32_e32 v223, v51, v51
	v_fmac_f32_e32 v222, v52, v52
	v_fmac_f32_e32 v223, v53, v53
	v_fmac_f32_e32 v222, v54, v54
	v_fmac_f32_e32 v223, v55, v55
	v_fmac_f32_e32 v222, v56, v56
	v_fmac_f32_e32 v223, v57, v57
	v_fmac_f32_e32 v222, v58, v58
	v_fmac_f32_e32 v223, v59, v59
	v_fmac_f32_e32 v222, v60, v60
	v_fmac_f32_e32 v223, v61, v61
	v_fmac_f32_e32 v222, v62, v62
	v_fmac_f32_e32 v223, v63, v63
	v_fmac_f32_e32 v222, v64, v64
	v_fmac_f32_e32 v223, v65, v65
	v_fmac_f32_e32 v222, v66, v66
	v_fmac_f32_e32 v223, v67, v67
	v_fmac_f32_e32 v222, v68, v68
	v_fmac_f32_e32 v223, v69, v69
	v_fmac_f32_e32 v222, v70, v70
	v_fmac_f32_e32 v223, v71, v71
	v_fmac_f32_e32 v222, v72, v72
	v_fmac_f32_e32 v223, v73, v73
	v_fmac_f32_e32 v222, v74, v74
	v_fmac_f32_e32 v223, v75, v75
	v_fmac_f32_e32 v222, v76, v76
	v_fmac_f32_e32 v223, v77, v77
	v_fmac_f32_e32 v222, v78, v78
	v_fmac_f32_e32 v223, v79, v79
	v_add_f32_e32 v222, v222, v223
	s_nop 1
	v_add_f32_dpp v224, v222, v222 quad_perm:[1,0,3,2] row_mask:0xf bank_mask:0xf
	s_nop 1
	v_add_f32_dpp v224, v224, v224 quad_perm:[2,3,0,1] row_mask:0xf bank_mask:0xf
	s_nop 1
	v_add_f32_dpp v224, v224, v224 row_half_mirror row_mask:0xf bank_mask:0xf
	s_nop 1
	v_add_f32_dpp v224, v224, v224 row_mirror row_mask:0xf bank_mask:0xf
	s_nop 1
	v_readlane_b32 s40, v224, 0
	v_readlane_b32 s41, v224, 16
	v_readlane_b32 s42, v224, 32
	v_readlane_b32 s43, v224, 48
	s_nop 1
	v_mov_b32_e32 v225, s40
	v_add_f32_e32 v225, s41, v225
	v_add_f32_e32 v225, s42, v225
	v_add_f32_e32 v225, s43, v225
	v_fmamk_f32 v225, v225, 0x3a000000, v195
	v_rsq_f32_e32 v225, v225
	s_nop 0
	s_add_i32 s0, s6, 5
	s_lshl_b32 s1, s0, 12
	s_add_u32 s26, s84, s1
	s_addc_u32 s27, s85, 0
	s_add_u32 s26, s26, 0xd000000
	s_addc_u32 s27, s27, 0
	v_mul_f32_e32 v216, v225, v48
	v_mul_f32_e32 v217, v225, v49
	v_mul_f32_e32 v218, v225, v50
	v_mul_f32_e32 v219, v225, v51
	v_fma_f32 v216, v216, v128, v160
	v_fma_f32 v217, v217, v129, v161
	v_fma_f32 v218, v218, v130, v162
	v_fma_f32 v219, v219, v131, v163
	v_cvt_pk_bf16_f32 v196, v216, v217
	v_cvt_pk_bf16_f32 v197, v218, v219
	global_store_dwordx2 v194, v[196:197], s[26:27] offset:0
	v_mul_f32_e32 v216, v225, v52
	v_mul_f32_e32 v217, v225, v53
	v_mul_f32_e32 v218, v225, v54
	v_mul_f32_e32 v219, v225, v55
	v_fma_f32 v216, v216, v132, v164
	v_fma_f32 v217, v217, v133, v165
	v_fma_f32 v218, v218, v134, v166
	v_fma_f32 v219, v219, v135, v167
	v_cvt_pk_bf16_f32 v220, v216, v217
	v_cvt_pk_bf16_f32 v221, v218, v219
	global_store_dwordx2 v194, v[220:221], s[26:27] offset:512
	v_mul_f32_e32 v216, v225, v56
	v_mul_f32_e32 v217, v225, v57
	v_mul_f32_e32 v218, v225, v58
	v_mul_f32_e32 v219, v225, v59
	v_fma_f32 v216, v216, v136, v168
	v_fma_f32 v217, v217, v137, v169
	v_fma_f32 v218, v218, v138, v170
	v_fma_f32 v219, v219, v139, v171
	v_cvt_pk_bf16_f32 v196, v216, v217
	v_cvt_pk_bf16_f32 v197, v218, v219
	global_store_dwordx2 v194, v[196:197], s[26:27] offset:1024
	v_mul_f32_e32 v216, v225, v60
	v_mul_f32_e32 v217, v225, v61
	v_mul_f32_e32 v218, v225, v62
	v_mul_f32_e32 v219, v225, v63
	v_fma_f32 v216, v216, v140, v172
	v_fma_f32 v217, v217, v141, v173
	v_fma_f32 v218, v218, v142, v174
	v_fma_f32 v219, v219, v143, v175
	v_cvt_pk_bf16_f32 v220, v216, v217
	v_cvt_pk_bf16_f32 v221, v218, v219
	global_store_dwordx2 v194, v[220:221], s[26:27] offset:1536
	v_mul_f32_e32 v216, v225, v64
	v_mul_f32_e32 v217, v225, v65
	v_mul_f32_e32 v218, v225, v66
	v_mul_f32_e32 v219, v225, v67
	v_fma_f32 v216, v216, v144, v176
	v_fma_f32 v217, v217, v145, v177
	v_fma_f32 v218, v218, v146, v178
	v_fma_f32 v219, v219, v147, v179
	v_cvt_pk_bf16_f32 v196, v216, v217
	v_cvt_pk_bf16_f32 v197, v218, v219
	global_store_dwordx2 v194, v[196:197], s[26:27] offset:2048
	v_mul_f32_e32 v216, v225, v68
	v_mul_f32_e32 v217, v225, v69
	v_mul_f32_e32 v218, v225, v70
	v_mul_f32_e32 v219, v225, v71
	v_fma_f32 v216, v216, v148, v180
	v_fma_f32 v217, v217, v149, v181
	v_fma_f32 v218, v218, v150, v182
	v_fma_f32 v219, v219, v151, v183
	v_cvt_pk_bf16_f32 v220, v216, v217
	v_cvt_pk_bf16_f32 v221, v218, v219
	global_store_dwordx2 v194, v[220:221], s[26:27] offset:2560
	v_mul_f32_e32 v216, v225, v72
	v_mul_f32_e32 v217, v225, v73
	v_mul_f32_e32 v218, v225, v74
	v_mul_f32_e32 v219, v225, v75
	v_fma_f32 v216, v216, v152, v184
	v_fma_f32 v217, v217, v153, v185
	v_fma_f32 v218, v218, v154, v186
	v_fma_f32 v219, v219, v155, v187
	v_cvt_pk_bf16_f32 v196, v216, v217
	v_cvt_pk_bf16_f32 v197, v218, v219
	global_store_dwordx2 v194, v[196:197], s[26:27] offset:3072
	v_mul_f32_e32 v216, v225, v76
	v_mul_f32_e32 v217, v225, v77
	v_mul_f32_e32 v218, v225, v78
	v_mul_f32_e32 v219, v225, v79
	v_fma_f32 v216, v216, v156, v188
	v_fma_f32 v217, v217, v157, v189
	v_fma_f32 v218, v218, v158, v190
	v_fma_f32 v219, v219, v159, v191
	v_cvt_pk_bf16_f32 v220, v216, v217
	v_cvt_pk_bf16_f32 v221, v218, v219
	global_store_dwordx2 v194, v[220:221], s[26:27] offset:3584
	s_add_i32 s0, s6, 7
	s_cmp_lt_u32 s0, 0x4000
	s_cselect_b32 s10, s68, s72
	s_cselect_b32 s11, s69, s73
	s_cselect_b32 s1, 0, 0x4000
	s_sub_i32 s1, s0, s1
	s_lshl_b32 s1, s1, 13
	s_add_u32 s10, s10, s1
	s_addc_u32 s11, s11, 0
	s_add_i32 s0, s6, 7
	s_lshl_b32 s1, s0, 12
	s_add_u32 s22, s84, s1
	s_addc_u32 s23, s85, 0
	s_add_u32 s22, s22, 0x11800000
	s_addc_u32 s23, s23, 0
	global_load_dwordx4 v[48:51], v192, s[10:11] offset:0 nt
	global_load_dwordx4 v[52:55], v192, s[10:11] offset:1024 nt
	global_load_dwordx4 v[56:59], v192, s[10:11] offset:2048 nt
	global_load_dwordx4 v[60:63], v192, s[10:11] offset:3072 nt
	global_load_dwordx4 v[64:67], v193, s[10:11] offset:0 nt
	global_load_dwordx4 v[68:71], v193, s[10:11] offset:1024 nt
	global_load_dwordx4 v[72:75], v193, s[10:11] offset:2048 nt
	global_load_dwordx4 v[76:79], v193, s[10:11] offset:3072 nt
	global_load_dwordx2 v[80:81], v194, s[22:23] offset:0 nt
	global_load_dwordx2 v[82:83], v194, s[22:23] offset:512 nt
	global_load_dwordx2 v[84:85], v194, s[22:23] offset:1024 nt
	global_load_dwordx2 v[86:87], v194, s[22:23] offset:1536 nt
	global_load_dwordx2 v[88:89], v194, s[22:23] offset:2048 nt
	global_load_dwordx2 v[90:91], v194, s[22:23] offset:2560 nt
	global_load_dwordx2 v[92:93], v194, s[22:23] offset:3072 nt
	global_load_dwordx2 v[94:95], v194, s[22:23] offset:3584 nt
	s_add_i32 s0, s6, 6
	s_add_i32 s0, s6, 6
	s_lshr_b32 s8, s0, 11
	s_cmp_lt_u32 s0, 0x4000
	s_cselect_b32 s8, s8, 8
	s_cmp_eq_u32 s8, s7
	s_cbranch_scc1 .Lp6_np6
; __device__ __forceinline__ void modulate_store(const f32x4 (&v)[8], float rstd, const float* pn, const float* modr, bf16_t* orow, int lane) {
; #pragma unroll
;     for (int j = 0; j < 8; ++j) { const int col = 4 * lane + 256 * j;
;         const f32x4 g = *(const f32x4*)(pn + col), sh = *(const f32x4*)(modr + col), sc = *(const f32x4*)(modr + DM + col);
;         const f32x4 hh = v[j] * rstd * g * (sc + 1.f) + sh;
; __global__ void __launch_bounds__(NWAVES * 64, 2) mk_fwd(Args args) {
;     ...
;                 const float* m0 = mod + (size_t)r * 6144;
; #pragma unroll
;                 for (int j = 0; j < 8; ++j) { const int col = 4 * F.lane + 256 * j; const f32x4 gt = *(const f32x4*)(m0 + 2 * DM + col), pn = *(const f32x4*)(post_norm + col);
	s_mov_b32 s7, s8
	s_add_i32 s1, s8, 9
	s_mul_i32 s1, s1, 0x6000
	s_add_u32 s44, s84, s1
	s_addc_u32 s45, s85, 0
	s_add_u32 s44, s44, 0x2000
	s_addc_u32 s45, s45, 0
	s_add_i32 s1, s8, 9
	s_mul_i32 s1, s1, 0x6000
	s_add_u32 s36, s84, s1
	s_addc_u32 s37, s85, 0
	s_add_u32 s38, s80, 0x2000
	s_addc_u32 s39, s81, 0
	s_mul_i32 s1, s8, 0x6000
	s_add_u32 s34, s84, s1
	s_addc_u32 s35, s85, 0
	s_add_u32 s34, s34, 0x4000
	s_addc_u32 s35, s35, 0
	global_load_dwordx4 v[96:99], v192, s[34:35] offset:0
	global_load_dwordx4 v[200:203], v192, s[82:83] offset:0
	global_load_dwordx4 v[100:103], v192, s[34:35] offset:1024
	global_load_dwordx4 v[204:207], v192, s[82:83] offset:1024
	global_load_dwordx4 v[104:107], v192, s[34:35] offset:2048
	global_load_dwordx4 v[208:211], v192, s[82:83] offset:2048
	global_load_dwordx4 v[108:111], v192, s[34:35] offset:3072
	global_load_dwordx4 v[212:215], v192, s[82:83] offset:3072
	s_waitcnt vmcnt(0)
	v_mul_f32_e32 v96, v96, v200
	v_mul_f32_e32 v97, v97, v201
	v_mul_f32_e32 v98, v98, v202
	v_mul_f32_e32 v99, v99, v203
	v_mul_f32_e32 v100, v100, v204
	v_mul_f32_e32 v101, v101, v205
	v_mul_f32_e32 v102, v102, v206
	v_mul_f32_e32 v103, v103, v207
	v_mul_f32_e32 v104, v104, v208
	v_mul_f32_e32 v105, v105, v209
	v_mul_f32_e32 v106, v106, v210
	v_mul_f32_e32 v107, v107, v211
	v_mul_f32_e32 v108, v108, v212
	v_mul_f32_e32 v109, v109, v213
	v_mul_f32_e32 v110, v110, v214
	v_mul_f32_e32 v111, v111, v215
	global_load_dwordx4 v[128:131], v192, s[38:39] offset:0
	global_load_dwordx4 v[200:203], v192, s[44:45] offset:0
	global_load_dwordx4 v[160:163], v192, s[36:37] offset:0
	global_load_dwordx4 v[132:135], v192, s[38:39] offset:1024
	global_load_dwordx4 v[204:207], v192, s[44:45] offset:1024
	global_load_dwordx4 v[164:167], v192, s[36:37] offset:1024
	global_load_dwordx4 v[136:139], v192, s[38:39] offset:2048
	global_load_dwordx4 v[208:211], v192, s[44:45] offset:2048
	global_load_dwordx4 v[168:171], v192, s[36:37] offset:2048
	global_load_dwordx4 v[140:143], v192, s[38:39] offset:3072
	global_load_dwordx4 v[212:215], v192, s[44:45] offset:3072
	global_load_dwordx4 v[172:175], v192, s[36:37] offset:3072
	s_waitcnt vmcnt(0)
	v_add_f32_e32 v200, 1.0, v200
	v_add_f32_e32 v201, 1.0, v201
	v_add_f32_e32 v202, 1.0, v202
	v_add_f32_e32 v203, 1.0, v203
	v_mul_f32_e32 v128, v128, v200
	v_mul_f32_e32 v129, v129, v201
	v_mul_f32_e32 v130, v130, v202
	v_mul_f32_e32 v131, v131, v203
	v_add_f32_e32 v204, 1.0, v204
	v_add_f32_e32 v205, 1.0, v205
	v_add_f32_e32 v206, 1.0, v206
	v_add_f32_e32 v207, 1.0, v207
	v_mul_f32_e32 v132, v132, v204
	v_mul_f32_e32 v133, v133, v205
	v_mul_f32_e32 v134, v134, v206
	v_mul_f32_e32 v135, v135, v207
	v_add_f32_e32 v208, 1.0, v208
	v_add_f32_e32 v209, 1.0, v209
	v_add_f32_e32 v210, 1.0, v210
	v_add_f32_e32 v211, 1.0, v211
	v_mul_f32_e32 v136, v136, v208
	v_mul_f32_e32 v137, v137, v209
	v_mul_f32_e32 v138, v138, v210
	v_mul_f32_e32 v139, v139, v211
	v_add_f32_e32 v212, 1.0, v212
	v_add_f32_e32 v213, 1.0, v213
	v_add_f32_e32 v214, 1.0, v214
	v_add_f32_e32 v215, 1.0, v215
	v_mul_f32_e32 v140, v140, v212
	v_mul_f32_e32 v141, v141, v213
	v_mul_f32_e32 v142, v142, v214
	v_mul_f32_e32 v143, v143, v215
	global_load_dwordx4 v[112:115], v193, s[34:35] offset:0
	global_load_dwordx4 v[200:203], v193, s[82:83] offset:0
	global_load_dwordx4 v[116:119], v193, s[34:35] offset:1024
	global_load_dwordx4 v[204:207], v193, s[82:83] offset:1024
	global_load_dwordx4 v[120:123], v193, s[34:35] offset:2048
	global_load_dwordx4 v[208:211], v193, s[82:83] offset:2048
	global_load_dwordx4 v[124:127], v193, s[34:35] offset:3072
	global_load_dwordx4 v[212:215], v193, s[82:83] offset:3072
	s_waitcnt vmcnt(0)
	v_mul_f32_e32 v112, v112, v200
	v_mul_f32_e32 v113, v113, v201
	v_mul_f32_e32 v114, v114, v202
	v_mul_f32_e32 v115, v115, v203
	v_mul_f32_e32 v116, v116, v204
	v_mul_f32_e32 v117, v117, v205
	v_mul_f32_e32 v118, v118, v206
	v_mul_f32_e32 v119, v119, v207
	v_mul_f32_e32 v120, v120, v208
	v_mul_f32_e32 v121, v121, v209
	v_mul_f32_e32 v122, v122, v210
	v_mul_f32_e32 v123, v123, v211
	v_mul_f32_e32 v124, v124, v212
	v_mul_f32_e32 v125, v125, v213
	v_mul_f32_e32 v126, v126, v214
	v_mul_f32_e32 v127, v127, v215
	global_load_dwordx4 v[144:147], v193, s[38:39] offset:0
	global_load_dwordx4 v[200:203], v193, s[44:45] offset:0
	global_load_dwordx4 v[176:179], v193, s[36:37] offset:0
	global_load_dwordx4 v[148:151], v193, s[38:39] offset:1024
	global_load_dwordx4 v[204:207], v193, s[44:45] offset:1024
	global_load_dwordx4 v[180:183], v193, s[36:37] offset:1024
	global_load_dwordx4 v[152:155], v193, s[38:39] offset:2048
	global_load_dwordx4 v[208:211], v193, s[44:45] offset:2048
	global_load_dwordx4 v[184:187], v193, s[36:37] offset:2048
	global_load_dwordx4 v[156:159], v193, s[38:39] offset:3072
	global_load_dwordx4 v[212:215], v193, s[44:45] offset:3072
	global_load_dwordx4 v[188:191], v193, s[36:37] offset:3072
	s_waitcnt vmcnt(0)
	v_add_f32_e32 v200, 1.0, v200
	v_add_f32_e32 v201, 1.0, v201
	v_add_f32_e32 v202, 1.0, v202
	v_add_f32_e32 v203, 1.0, v203
	v_mul_f32_e32 v144, v144, v200
	v_mul_f32_e32 v145, v145, v201
	v_mul_f32_e32 v146, v146, v202
	v_mul_f32_e32 v147, v147, v203
	v_add_f32_e32 v204, 1.0, v204
	v_add_f32_e32 v205, 1.0, v205
	v_add_f32_e32 v206, 1.0, v206
	v_add_f32_e32 v207, 1.0, v207
	v_mul_f32_e32 v148, v148, v204
	v_mul_f32_e32 v149, v149, v205
	v_mul_f32_e32 v150, v150, v206
	v_mul_f32_e32 v151, v151, v207
	v_add_f32_e32 v208, 1.0, v208
	v_add_f32_e32 v209, 1.0, v209
	v_add_f32_e32 v210, 1.0, v210
	v_add_f32_e32 v211, 1.0, v211
	v_mul_f32_e32 v152, v152, v208
	v_mul_f32_e32 v153, v153, v209
	v_mul_f32_e32 v154, v154, v210
	v_mul_f32_e32 v155, v155, v211
	v_add_f32_e32 v212, 1.0, v212
	v_add_f32_e32 v213, 1.0, v213
	v_add_f32_e32 v214, 1.0, v214
	v_add_f32_e32 v215, 1.0, v215
	v_mul_f32_e32 v156, v156, v212
	v_mul_f32_e32 v157, v157, v213
	v_mul_f32_e32 v158, v158, v214
	v_mul_f32_e32 v159, v159, v215
; __device__ __forceinline__ float bf_lo(unsigned w) { return __uint_as_float(w << 16); }
; __device__ __forceinline__ float bf_hi(unsigned w) { return __uint_as_float(w & 0xffff0000u); }
; __global__ void __launch_bounds__(NWAVES * 64, 2) mk_fwd(Args args) {
;     ...
;                 float sy = 0.f;
; #pragma unroll
;                 for (int j = 0; j < 8; ++j) { const float a = bf_lo(yw[q][j].x), b = bf_hi(yw[q][j].x), c2 = bf_lo(yw[q][j].y), d = bf_hi(yw[q][j].y); sy += (a * a + b * b) + (c2 * c2 + d * d); }
;                 const float rsy = __builtin_amdgcn_rsqf(wave_sum(sy) * (1.f / DM) + EPS);
;                 const float* m0 = mod + (size_t)r * 6144;
; #pragma unroll
;                 for (int j = 0; j < 8; ++j) { const int col = 4 * F.lane + 256 * j; const f32x4 gt = *(const f32x4*)(m0 + 2 * DM + col), pn = *(const f32x4*)(post_norm + col);
;                     const f32x4 y4 = (f32x4){bf_lo(yw[q][j].x), bf_hi(yw[q][j].x), bf_lo(yw[q][j].y), bf_hi(yw[q][j].y)};
;                     v[q][j] = v[q][j] + gt * (y4 * rsy * pn);
.Lp6_np6:
	s_waitcnt vmcnt(24)
	v_lshlrev_b32_e32 v216, 16, v32
	v_and_b32_e32 v217, 0xffff0000, v32
	v_lshlrev_b32_e32 v218, 16, v33
	v_and_b32_e32 v219, 0xffff0000, v33
	v_mul_f32_e32 v222, v216, v216
	v_mul_f32_e32 v223, v217, v217
	v_fmac_f32_e32 v222, v218, v218
	v_fmac_f32_e32 v223, v219, v219
	v_lshlrev_b32_e32 v216, 16, v34
	v_and_b32_e32 v217, 0xffff0000, v34
	v_lshlrev_b32_e32 v218, 16, v35
	v_and_b32_e32 v219, 0xffff0000, v35
	v_fmac_f32_e32 v222, v216, v216
	v_fmac_f32_e32 v223, v217, v217
	v_fmac_f32_e32 v222, v218, v218
	v_fmac_f32_e32 v223, v219, v219
	v_lshlrev_b32_e32 v216, 16, v36
	v_and_b32_e32 v217, 0xffff0000, v36
	v_lshlrev_b32_e32 v218, 16, v37
	v_and_b32_e32 v219, 0xffff0000, v37
	v_fmac_f32_e32 v222, v216, v216
	v_fmac_f32_e32 v223, v217, v217
	v_fmac_f32_e32 v222, v218, v218
	v_fmac_f32_e32 v223, v219, v219
	v_lshlrev_b32_e32 v216, 16, v38
	v_and_b32_e32 v217, 0xffff0000, v38
	v_lshlrev_b32_e32 v218, 16, v39
	v_and_b32_e32 v219, 0xffff0000, v39
	v_fmac_f32_e32 v222, v216, v216
	v_fmac_f32_e32 v223, v217, v217
	v_fmac_f32_e32 v222, v218, v218
	v_fmac_f32_e32 v223, v219, v219
	v_lshlrev_b32_e32 v216, 16, v40
	v_and_b32_e32 v217, 0xffff0000, v40
	v_lshlrev_b32_e32 v218, 16, v41
	v_and_b32_e32 v219, 0xffff0000, v41
	v_fmac_f32_e32 v222, v216, v216
	v_fmac_f32_e32 v223, v217, v217
	v_fmac_f32_e32 v222, v218, v218
	v_fmac_f32_e32 v223, v219, v219
	v_lshlrev_b32_e32 v216, 16, v42
	v_and_b32_e32 v217, 0xffff0000, v42
	v_lshlrev_b32_e32 v218, 16, v43
	v_and_b32_e32 v219, 0xffff0000, v43
	v_fmac_f32_e32 v222, v216, v216
	v_fmac_f32_e32 v223, v217, v217
	v_fmac_f32_e32 v222, v218, v218
	v_fmac_f32_e32 v223, v219, v219
	v_lshlrev_b32_e32 v216, 16, v44
	v_and_b32_e32 v217, 0xffff0000, v44
	v_lshlrev_b32_e32 v218, 16, v45
	v_and_b32_e32 v219, 0xffff0000, v45
	v_fmac_f32_e32 v222, v216, v216
	v_fmac_f32_e32 v223, v217, v217
	v_fmac_f32_e32 v222, v218, v218
	v_fmac_f32_e32 v223, v219, v219
	v_lshlrev_b32_e32 v216, 16, v46
	v_and_b32_e32 v217, 0xffff0000, v46
	v_lshlrev_b32_e32 v218, 16, v47
	v_and_b32_e32 v219, 0xffff0000, v47
	v_fmac_f32_e32 v222, v216, v216
	v_fmac_f32_e32 v223, v217, v217
	v_fmac_f32_e32 v222, v218, v218
	v_fmac_f32_e32 v223, v219, v219
	v_add_f32_e32 v222, v222, v223
	s_nop 1
	v_add_f32_dpp v224, v222, v222 quad_perm:[1,0,3,2] row_mask:0xf bank_mask:0xf
	s_nop 1
	v_add_f32_dpp v224, v224, v224 quad_perm:[2,3,0,1] row_mask:0xf bank_mask:0xf
	s_nop 1
	v_add_f32_dpp v224, v224, v224 row_half_mirror row_mask:0xf bank_mask:0xf
	s_nop 1
	v_add_f32_dpp v224, v224, v224 row_mirror row_mask:0xf bank_mask:0xf
	s_nop 1
	v_readlane_b32 s40, v224, 0
	v_readlane_b32 s41, v224, 16
	v_readlane_b32 s42, v224, 32
	v_readlane_b32 s43, v224, 48
	s_nop 1
	v_mov_b32_e32 v225, s40
	v_add_f32_e32 v225, s41, v225
	v_add_f32_e32 v225, s42, v225
	v_add_f32_e32 v225, s43, v225
	v_fmamk_f32 v225, v225, 0x3a000000, v195
	v_rsq_f32_e32 v225, v225
	s_nop 0
	v_lshlrev_b32_e32 v216, 16, v32
	v_and_b32_e32 v217, 0xffff0000, v32
	v_lshlrev_b32_e32 v218, 16, v33
	v_and_b32_e32 v219, 0xffff0000, v33
	v_mul_f32_e32 v216, v225, v216
	v_mul_f32_e32 v217, v225, v217
	v_mul_f32_e32 v218, v225, v218
	v_mul_f32_e32 v219, v225, v219
	v_fmac_f32_e32 v0, v96, v216
	v_fmac_f32_e32 v1, v97, v217
	v_fmac_f32_e32 v2, v98, v218
	v_fmac_f32_e32 v3, v99, v219
	v_lshlrev_b32_e32 v216, 16, v34
	v_and_b32_e32 v217, 0xffff0000, v34
	v_lshlrev_b32_e32 v218, 16, v35
	v_and_b32_e32 v219, 0xffff0000, v35
	v_mul_f32_e32 v216, v225, v216
	v_mul_f32_e32 v217, v225, v217
	v_mul_f32_e32 v218, v225, v218
	v_mul_f32_e32 v219, v225, v219
	v_fmac_f32_e32 v4, v100, v216
	v_fmac_f32_e32 v5, v101, v217
	v_fmac_f32_e32 v6, v102, v218
	v_fmac_f32_e32 v7, v103, v219
	v_lshlrev_b32_e32 v216, 16, v36
	v_and_b32_e32 v217, 0xffff0000, v36
	v_lshlrev_b32_e32 v218, 16, v37
	v_and_b32_e32 v219, 0xffff0000, v37
	v_mul_f32_e32 v216, v225, v216
	v_mul_f32_e32 v217, v225, v217
	v_mul_f32_e32 v218, v225, v218
	v_mul_f32_e32 v219, v225, v219
	v_fmac_f32_e32 v8, v104, v216
	v_fmac_f32_e32 v9, v105, v217
	v_fmac_f32_e32 v10, v106, v218
	v_fmac_f32_e32 v11, v107, v219
	v_lshlrev_b32_e32 v216, 16, v38
	v_and_b32_e32 v217, 0xffff0000, v38
	v_lshlrev_b32_e32 v218, 16, v39
	v_and_b32_e32 v219, 0xffff0000, v39
	v_mul_f32_e32 v216, v225, v216
	v_mul_f32_e32 v217, v225, v217
	v_mul_f32_e32 v218, v225, v218
	v_mul_f32_e32 v219, v225, v219
	v_fmac_f32_e32 v12, v108, v216
	v_fmac_f32_e32 v13, v109, v217
	v_fmac_f32_e32 v14, v110, v218
	v_fmac_f32_e32 v15, v111, v219
	v_lshlrev_b32_e32 v216, 16, v40
	v_and_b32_e32 v217, 0xffff0000, v40
	v_lshlrev_b32_e32 v218, 16, v41
	v_and_b32_e32 v219, 0xffff0000, v41
	v_mul_f32_e32 v216, v225, v216
	v_mul_f32_e32 v217, v225, v217
	v_mul_f32_e32 v218, v225, v218
	v_mul_f32_e32 v219, v225, v219
	v_fmac_f32_e32 v16, v112, v216
	v_fmac_f32_e32 v17, v113, v217
	v_fmac_f32_e32 v18, v114, v218
	v_fmac_f32_e32 v19, v115, v219
	v_lshlrev_b32_e32 v216, 16, v42
	v_and_b32_e32 v217, 0xffff0000, v42
	v_lshlrev_b32_e32 v218, 16, v43
	v_and_b32_e32 v219, 0xffff0000, v43
	v_mul_f32_e32 v216, v225, v216
	v_mul_f32_e32 v217, v225, v217
	v_mul_f32_e32 v218, v225, v218
	v_mul_f32_e32 v219, v225, v219
	v_fmac_f32_e32 v20, v116, v216
	v_fmac_f32_e32 v21, v117, v217
	v_fmac_f32_e32 v22, v118, v218
	v_fmac_f32_e32 v23, v119, v219
	v_lshlrev_b32_e32 v216, 16, v44
	v_and_b32_e32 v217, 0xffff0000, v44
	v_lshlrev_b32_e32 v218, 16, v45
	v_and_b32_e32 v219, 0xffff0000, v45
	v_mul_f32_e32 v216, v225, v216
	v_mul_f32_e32 v217, v225, v217
	v_mul_f32_e32 v218, v225, v218
	v_mul_f32_e32 v219, v225, v219
	v_fmac_f32_e32 v24, v120, v216
	v_fmac_f32_e32 v25, v121, v217
	v_fmac_f32_e32 v26, v122, v218
; __device__ __forceinline__ unsigned cvt_pk_bf16(float lo, float hi) { unsigned r; asm volatile("v_cvt_pk_bf16_f32 %0, %1, %2" : "=v"(r) : "v"(lo), "v"(hi)); return r; }
; __device__ __forceinline__ float sumsq8(const f32x4 (&v)[8]) {
;     float s = 0.f;
; #pragma unroll
;     for (int j = 0; j < 8; ++j) s += (v[j][0] * v[j][0] + v[j][1] * v[j][1]) + (v[j][2] * v[j][2] + v[j][3] * v[j][3]);
;     return wave_sum(s);
; }
; __device__ __forceinline__ void modulate_store(const f32x4 (&v)[8], float rstd, const float* pn, const float* modr, bf16_t* orow, int lane) {
; #pragma unroll
;     for (int j = 0; j < 8; ++j) { const int col = 4 * lane + 256 * j;
;         const f32x4 g = *(const f32x4*)(pn + col), sh = *(const f32x4*)(modr + col), sc = *(const f32x4*)(modr + DM + col);
;         const f32x4 hh = v[j] * rstd * g * (sc + 1.f) + sh;
;         u32x2 w; w.x = cvt_pk_bf16(hh[0], hh[1]); w.y = cvt_pk_bf16(hh[2], hh[3]);
;         *(u32x2*)(orow + col) = w; }
; __global__ void __launch_bounds__(NWAVES * 64, 2) mk_fwd(Args args) {
;     ...
;                 const float rstd = __builtin_amdgcn_rsqf(sumsq8(v[q]) * (1.f / DM) + EPS);
;                 modulate_store(v[q], rstd, pre_norm + DM, mod + (size_t)(9 + r) * 6144, H + (size_t)row * DM, F.lane); }
	v_fmac_f32_e32 v27, v123, v219
	v_lshlrev_b32_e32 v216, 16, v46
	v_and_b32_e32 v217, 0xffff0000, v46
	v_lshlrev_b32_e32 v218, 16, v47
	v_and_b32_e32 v219, 0xffff0000, v47
	v_mul_f32_e32 v216, v225, v216
	v_mul_f32_e32 v217, v225, v217
	v_mul_f32_e32 v218, v225, v218
	v_mul_f32_e32 v219, v225, v219
	v_fmac_f32_e32 v28, v124, v216
	v_fmac_f32_e32 v29, v125, v217
	v_fmac_f32_e32 v30, v126, v218
	v_fmac_f32_e32 v31, v127, v219
	v_mul_f32_e32 v222, v0, v0
	v_mul_f32_e32 v223, v1, v1
	v_fmac_f32_e32 v222, v2, v2
	v_fmac_f32_e32 v223, v3, v3
	v_fmac_f32_e32 v222, v4, v4
	v_fmac_f32_e32 v223, v5, v5
	v_fmac_f32_e32 v222, v6, v6
	v_fmac_f32_e32 v223, v7, v7
	v_fmac_f32_e32 v222, v8, v8
	v_fmac_f32_e32 v223, v9, v9
	v_fmac_f32_e32 v222, v10, v10
	v_fmac_f32_e32 v223, v11, v11
	v_fmac_f32_e32 v222, v12, v12
	v_fmac_f32_e32 v223, v13, v13
	v_fmac_f32_e32 v222, v14, v14
	v_fmac_f32_e32 v223, v15, v15
	v_fmac_f32_e32 v222, v16, v16
	v_fmac_f32_e32 v223, v17, v17
	v_fmac_f32_e32 v222, v18, v18
	v_fmac_f32_e32 v223, v19, v19
	v_fmac_f32_e32 v222, v20, v20
	v_fmac_f32_e32 v223, v21, v21
	v_fmac_f32_e32 v222, v22, v22
	v_fmac_f32_e32 v223, v23, v23
	v_fmac_f32_e32 v222, v24, v24
	v_fmac_f32_e32 v223, v25, v25
	v_fmac_f32_e32 v222, v26, v26
	v_fmac_f32_e32 v223, v27, v27
	v_fmac_f32_e32 v222, v28, v28
	v_fmac_f32_e32 v223, v29, v29
	v_fmac_f32_e32 v222, v30, v30
	v_fmac_f32_e32 v223, v31, v31
	v_add_f32_e32 v222, v222, v223
	s_nop 1
	v_add_f32_dpp v224, v222, v222 quad_perm:[1,0,3,2] row_mask:0xf bank_mask:0xf
	s_nop 1
	v_add_f32_dpp v224, v224, v224 quad_perm:[2,3,0,1] row_mask:0xf bank_mask:0xf
	s_nop 1
	v_add_f32_dpp v224, v224, v224 row_half_mirror row_mask:0xf bank_mask:0xf
	s_nop 1
	v_add_f32_dpp v224, v224, v224 row_mirror row_mask:0xf bank_mask:0xf
	s_nop 1
	v_readlane_b32 s40, v224, 0
	v_readlane_b32 s41, v224, 16
	v_readlane_b32 s42, v224, 32
	v_readlane_b32 s43, v224, 48
	s_nop 1
	v_mov_b32_e32 v225, s40
	v_add_f32_e32 v225, s41, v225
	v_add_f32_e32 v225, s42, v225
	v_add_f32_e32 v225, s43, v225
	v_fmamk_f32 v225, v225, 0x3a000000, v195
	v_rsq_f32_e32 v225, v225
	s_nop 0
	s_add_i32 s0, s6, 6
	s_lshl_b32 s1, s0, 12
	s_add_u32 s26, s84, s1
	s_addc_u32 s27, s85, 0
	s_add_u32 s26, s26, 0xd000000
	s_addc_u32 s27, s27, 0
	v_mul_f32_e32 v216, v225, v0
	v_mul_f32_e32 v217, v225, v1
	v_mul_f32_e32 v218, v225, v2
	v_mul_f32_e32 v219, v225, v3
	v_fma_f32 v216, v216, v128, v160
	v_fma_f32 v217, v217, v129, v161
	v_fma_f32 v218, v218, v130, v162
	v_fma_f32 v219, v219, v131, v163
	v_cvt_pk_bf16_f32 v196, v216, v217
	v_cvt_pk_bf16_f32 v197, v218, v219
	global_store_dwordx2 v194, v[196:197], s[26:27] offset:0
	v_mul_f32_e32 v216, v225, v4
	v_mul_f32_e32 v217, v225, v5
	v_mul_f32_e32 v218, v225, v6
	v_mul_f32_e32 v219, v225, v7
	v_fma_f32 v216, v216, v132, v164
	v_fma_f32 v217, v217, v133, v165
	v_fma_f32 v218, v218, v134, v166
	v_fma_f32 v219, v219, v135, v167
	v_cvt_pk_bf16_f32 v220, v216, v217
	v_cvt_pk_bf16_f32 v221, v218, v219
	global_store_dwordx2 v194, v[220:221], s[26:27] offset:512
	v_mul_f32_e32 v216, v225, v8
	v_mul_f32_e32 v217, v225, v9
	v_mul_f32_e32 v218, v225, v10
	v_mul_f32_e32 v219, v225, v11
	v_fma_f32 v216, v216, v136, v168
	v_fma_f32 v217, v217, v137, v169
	v_fma_f32 v218, v218, v138, v170
	v_fma_f32 v219, v219, v139, v171
	v_cvt_pk_bf16_f32 v196, v216, v217
	v_cvt_pk_bf16_f32 v197, v218, v219
	global_store_dwordx2 v194, v[196:197], s[26:27] offset:1024
	v_mul_f32_e32 v216, v225, v12
	v_mul_f32_e32 v217, v225, v13
	v_mul_f32_e32 v218, v225, v14
	v_mul_f32_e32 v219, v225, v15
	v_fma_f32 v216, v216, v140, v172
	v_fma_f32 v217, v217, v141, v173
	v_fma_f32 v218, v218, v142, v174
	v_fma_f32 v219, v219, v143, v175
	v_cvt_pk_bf16_f32 v220, v216, v217
	v_cvt_pk_bf16_f32 v221, v218, v219
	global_store_dwordx2 v194, v[220:221], s[26:27] offset:1536
	v_mul_f32_e32 v216, v225, v16
	v_mul_f32_e32 v217, v225, v17
	v_mul_f32_e32 v218, v225, v18
	v_mul_f32_e32 v219, v225, v19
	v_fma_f32 v216, v216, v144, v176
	v_fma_f32 v217, v217, v145, v177
	v_fma_f32 v218, v218, v146, v178
	v_fma_f32 v219, v219, v147, v179
	v_cvt_pk_bf16_f32 v196, v216, v217
	v_cvt_pk_bf16_f32 v197, v218, v219
	global_store_dwordx2 v194, v[196:197], s[26:27] offset:2048
	v_mul_f32_e32 v216, v225, v20
	v_mul_f32_e32 v217, v225, v21
	v_mul_f32_e32 v218, v225, v22
	v_mul_f32_e32 v219, v225, v23
	v_fma_f32 v216, v216, v148, v180
	v_fma_f32 v217, v217, v149, v181
	v_fma_f32 v218, v218, v150, v182
	v_fma_f32 v219, v219, v151, v183
	v_cvt_pk_bf16_f32 v220, v216, v217
	v_cvt_pk_bf16_f32 v221, v218, v219
	global_store_dwordx2 v194, v[220:221], s[26:27] offset:2560
	v_mul_f32_e32 v216, v225, v24
	v_mul_f32_e32 v217, v225, v25
	v_mul_f32_e32 v218, v225, v26
	v_mul_f32_e32 v219, v225, v27
	v_fma_f32 v216, v216, v152, v184
	v_fma_f32 v217, v217, v153, v185
	v_fma_f32 v218, v218, v154, v186
	v_fma_f32 v219, v219, v155, v187
	v_cvt_pk_bf16_f32 v196, v216, v217
	v_cvt_pk_bf16_f32 v197, v218, v219
	global_store_dwordx2 v194, v[196:197], s[26:27] offset:3072
	v_mul_f32_e32 v216, v225, v28
	v_mul_f32_e32 v217, v225, v29
	v_mul_f32_e32 v218, v225, v30
	v_mul_f32_e32 v219, v225, v31
	v_fma_f32 v216, v216, v156, v188
	v_fma_f32 v217, v217, v157, v189
	v_fma_f32 v218, v218, v158, v190
	v_fma_f32 v219, v219, v159, v191
	v_cvt_pk_bf16_f32 v220, v216, v217
	v_cvt_pk_bf16_f32 v221, v218, v219
	global_store_dwordx2 v194, v[220:221], s[26:27] offset:3584
	s_add_i32 s0, s6, 8
	s_cmp_lt_u32 s0, 0x4000
	s_cselect_b32 s10, s68, s72
	s_cselect_b32 s11, s69, s73
	s_cselect_b32 s1, 0, 0x4000
	s_sub_i32 s1, s0, s1
	s_lshl_b32 s1, s1, 13
	s_add_u32 s10, s10, s1
	s_addc_u32 s11, s11, 0
	s_add_i32 s0, s6, 8
	s_lshl_b32 s1, s0, 12
	s_add_u32 s22, s84, s1
	s_addc_u32 s23, s85, 0
	s_add_u32 s22, s22, 0x11800000
	s_addc_u32 s23, s23, 0
	global_load_dwordx4 v[0:3], v192, s[10:11] offset:0 nt
	global_load_dwordx4 v[4:7], v192, s[10:11] offset:1024 nt
	global_load_dwordx4 v[8:11], v192, s[10:11] offset:2048 nt
	global_load_dwordx4 v[12:15], v192, s[10:11] offset:3072 nt
	global_load_dwordx4 v[16:19], v193, s[10:11] offset:0 nt
	global_load_dwordx4 v[20:23], v193, s[10:11] offset:1024 nt
	global_load_dwordx4 v[24:27], v193, s[10:11] offset:2048 nt
	global_load_dwordx4 v[28:31], v193, s[10:11] offset:3072 nt
	global_load_dwordx2 v[32:33], v194, s[22:23] offset:0 nt
	global_load_dwordx2 v[34:35], v194, s[22:23] offset:512 nt
	global_load_dwordx2 v[36:37], v194, s[22:23] offset:1024 nt
	global_load_dwordx2 v[38:39], v194, s[22:23] offset:1536 nt
	global_load_dwordx2 v[40:41], v194, s[22:23] offset:2048 nt
	global_load_dwordx2 v[42:43], v194, s[22:23] offset:2560 nt
	global_load_dwordx2 v[44:45], v194, s[22:23] offset:3072 nt
	global_load_dwordx2 v[46:47], v194, s[22:23] offset:3584 nt
	s_add_i32 s0, s6, 7
	s_add_i32 s0, s6, 7
	s_lshr_b32 s8, s0, 11
	s_cmp_lt_u32 s0, 0x4000
	s_cselect_b32 s8, s8, 8
	s_cmp_eq_u32 s8, s7
	s_cbranch_scc1 .Lp6_np7
; __device__ __forceinline__ void modulate_store(const f32x4 (&v)[8], float rstd, const float* pn, const float* modr, bf16_t* orow, int lane) {
; #pragma unroll
;     for (int j = 0; j < 8; ++j) { const int col = 4 * lane + 256 * j;
;         const f32x4 g = *(const f32x4*)(pn + col), sh = *(const f32x4*)(modr + col), sc = *(const f32x4*)(modr + DM + col);
;         const f32x4 hh = v[j] * rstd * g * (sc + 1.f) + sh;
; __global__ void __launch_bounds__(NWAVES * 64, 2) mk_fwd(Args args) {
;     ...
;                 const float* m0 = mod + (size_t)r * 6144;
; #pragma unroll
;                 for (int j = 0; j < 8; ++j) { const int col = 4 * F.lane + 256 * j; const f32x4 gt = *(const f32x4*)(m0 + 2 * DM + col), pn = *(const f32x4*)(post_norm + col);
	s_mov_b32 s7, s8
	s_add_i32 s1, s8, 9
	s_mul_i32 s1, s1, 0x6000
	s_add_u32 s44, s84, s1
	s_addc_u32 s45, s85, 0
	s_add_u32 s44, s44, 0x2000
	s_addc_u32 s45, s45, 0
	s_add_i32 s1, s8, 9
	s_mul_i32 s1, s1, 0x6000
	s_add_u32 s36, s84, s1
	s_addc_u32 s37, s85, 0
	s_add_u32 s38, s80, 0x2000
	s_addc_u32 s39, s81, 0
	s_mul_i32 s1, s8, 0x6000
	s_add_u32 s34, s84, s1
	s_addc_u32 s35, s85, 0
	s_add_u32 s34, s34, 0x4000
	s_addc_u32 s35, s35, 0
	global_load_dwordx4 v[96:99], v192, s[34:35] offset:0
	global_load_dwordx4 v[200:203], v192, s[82:83] offset:0
	global_load_dwordx4 v[100:103], v192, s[34:35] offset:1024
	global_load_dwordx4 v[204:207], v192, s[82:83] offset:1024
	global_load_dwordx4 v[104:107], v192, s[34:35] offset:2048
	global_load_dwordx4 v[208:211], v192, s[82:83] offset:2048
	global_load_dwordx4 v[108:111], v192, s[34:35] offset:3072
	global_load_dwordx4 v[212:215], v192, s[82:83] offset:3072
	s_waitcnt vmcnt(0)
	v_mul_f32_e32 v96, v96, v200
	v_mul_f32_e32 v97, v97, v201
	v_mul_f32_e32 v98, v98, v202
	v_mul_f32_e32 v99, v99, v203
	v_mul_f32_e32 v100, v100, v204
	v_mul_f32_e32 v101, v101, v205
	v_mul_f32_e32 v102, v102, v206
	v_mul_f32_e32 v103, v103, v207
	v_mul_f32_e32 v104, v104, v208
	v_mul_f32_e32 v105, v105, v209
	v_mul_f32_e32 v106, v106, v210
	v_mul_f32_e32 v107, v107, v211
	v_mul_f32_e32 v108, v108, v212
	v_mul_f32_e32 v109, v109, v213
	v_mul_f32_e32 v110, v110, v214
	v_mul_f32_e32 v111, v111, v215
	global_load_dwordx4 v[128:131], v192, s[38:39] offset:0
	global_load_dwordx4 v[200:203], v192, s[44:45] offset:0
	global_load_dwordx4 v[160:163], v192, s[36:37] offset:0
	global_load_dwordx4 v[132:135], v192, s[38:39] offset:1024
	global_load_dwordx4 v[204:207], v192, s[44:45] offset:1024
	global_load_dwordx4 v[164:167], v192, s[36:37] offset:1024
	global_load_dwordx4 v[136:139], v192, s[38:39] offset:2048
	global_load_dwordx4 v[208:211], v192, s[44:45] offset:2048
	global_load_dwordx4 v[168:171], v192, s[36:37] offset:2048
	global_load_dwordx4 v[140:143], v192, s[38:39] offset:3072
	global_load_dwordx4 v[212:215], v192, s[44:45] offset:3072
	global_load_dwordx4 v[172:175], v192, s[36:37] offset:3072
	s_waitcnt vmcnt(0)
	v_add_f32_e32 v200, 1.0, v200
	v_add_f32_e32 v201, 1.0, v201
	v_add_f32_e32 v202, 1.0, v202
	v_add_f32_e32 v203, 1.0, v203
	v_mul_f32_e32 v128, v128, v200
	v_mul_f32_e32 v129, v129, v201
	v_mul_f32_e32 v130, v130, v202
	v_mul_f32_e32 v131, v131, v203
	v_add_f32_e32 v204, 1.0, v204
	v_add_f32_e32 v205, 1.0, v205
	v_add_f32_e32 v206, 1.0, v206
	v_add_f32_e32 v207, 1.0, v207
	v_mul_f32_e32 v132, v132, v204
	v_mul_f32_e32 v133, v133, v205
	v_mul_f32_e32 v134, v134, v206
	v_mul_f32_e32 v135, v135, v207
	v_add_f32_e32 v208, 1.0, v208
	v_add_f32_e32 v209, 1.0, v209
	v_add_f32_e32 v210, 1.0, v210
	v_add_f32_e32 v211, 1.0, v211
	v_mul_f32_e32 v136, v136, v208
	v_mul_f32_e32 v137, v137, v209
	v_mul_f32_e32 v138, v138, v210
	v_mul_f32_e32 v139, v139, v211
	v_add_f32_e32 v212, 1.0, v212
	v_add_f32_e32 v213, 1.0, v213
	v_add_f32_e32 v214, 1.0, v214
	v_add_f32_e32 v215, 1.0, v215
	v_mul_f32_e32 v140, v140, v212
	v_mul_f32_e32 v141, v141, v213
	v_mul_f32_e32 v142, v142, v214
	v_mul_f32_e32 v143, v143, v215
	global_load_dwordx4 v[112:115], v193, s[34:35] offset:0
	global_load_dwordx4 v[200:203], v193, s[82:83] offset:0
	global_load_dwordx4 v[116:119], v193, s[34:35] offset:1024
	global_load_dwordx4 v[204:207], v193, s[82:83] offset:1024
	global_load_dwordx4 v[120:123], v193, s[34:35] offset:2048
	global_load_dwordx4 v[208:211], v193, s[82:83] offset:2048
	global_load_dwordx4 v[124:127], v193, s[34:35] offset:3072
	global_load_dwordx4 v[212:215], v193, s[82:83] offset:3072
	s_waitcnt vmcnt(0)
	v_mul_f32_e32 v112, v112, v200
	v_mul_f32_e32 v113, v113, v201
	v_mul_f32_e32 v114, v114, v202
	v_mul_f32_e32 v115, v115, v203
	v_mul_f32_e32 v116, v116, v204
	v_mul_f32_e32 v117, v117, v205
	v_mul_f32_e32 v118, v118, v206
	v_mul_f32_e32 v119, v119, v207
	v_mul_f32_e32 v120, v120, v208
	v_mul_f32_e32 v121, v121, v209
	v_mul_f32_e32 v122, v122, v210
	v_mul_f32_e32 v123, v123, v211
	v_mul_f32_e32 v124, v124, v212
	v_mul_f32_e32 v125, v125, v213
	v_mul_f32_e32 v126, v126, v214
	v_mul_f32_e32 v127, v127, v215
	global_load_dwordx4 v[144:147], v193, s[38:39] offset:0
	global_load_dwordx4 v[200:203], v193, s[44:45] offset:0
	global_load_dwordx4 v[176:179], v193, s[36:37] offset:0
	global_load_dwordx4 v[148:151], v193, s[38:39] offset:1024
	global_load_dwordx4 v[204:207], v193, s[44:45] offset:1024
	global_load_dwordx4 v[180:183], v193, s[36:37] offset:1024
	global_load_dwordx4 v[152:155], v193, s[38:39] offset:2048
	global_load_dwordx4 v[208:211], v193, s[44:45] offset:2048
	global_load_dwordx4 v[184:187], v193, s[36:37] offset:2048
	global_load_dwordx4 v[156:159], v193, s[38:39] offset:3072
	global_load_dwordx4 v[212:215], v193, s[44:45] offset:3072
	global_load_dwordx4 v[188:191], v193, s[36:37] offset:3072
	s_waitcnt vmcnt(0)
	v_add_f32_e32 v200, 1.0, v200
	v_add_f32_e32 v201, 1.0, v201
	v_add_f32_e32 v202, 1.0, v202
	v_add_f32_e32 v203, 1.0, v203
	v_mul_f32_e32 v144, v144, v200
	v_mul_f32_e32 v145, v145, v201
	v_mul_f32_e32 v146, v146, v202
	v_mul_f32_e32 v147, v147, v203
	v_add_f32_e32 v204, 1.0, v204
	v_add_f32_e32 v205, 1.0, v205
	v_add_f32_e32 v206, 1.0, v206
	v_add_f32_e32 v207, 1.0, v207
	v_mul_f32_e32 v148, v148, v204
	v_mul_f32_e32 v149, v149, v205
	v_mul_f32_e32 v150, v150, v206
	v_mul_f32_e32 v151, v151, v207
	v_add_f32_e32 v208, 1.0, v208
	v_add_f32_e32 v209, 1.0, v209
	v_add_f32_e32 v210, 1.0, v210
	v_add_f32_e32 v211, 1.0, v211
	v_mul_f32_e32 v152, v152, v208
	v_mul_f32_e32 v153, v153, v209
	v_mul_f32_e32 v154, v154, v210
	v_mul_f32_e32 v155, v155, v211
	v_add_f32_e32 v212, 1.0, v212
	v_add_f32_e32 v213, 1.0, v213
	v_add_f32_e32 v214, 1.0, v214
	v_add_f32_e32 v215, 1.0, v215
	v_mul_f32_e32 v156, v156, v212
	v_mul_f32_e32 v157, v157, v213
	v_mul_f32_e32 v158, v158, v214
	v_mul_f32_e32 v159, v159, v215
; __device__ __forceinline__ float bf_lo(unsigned w) { return __uint_as_float(w << 16); }
; __device__ __forceinline__ float bf_hi(unsigned w) { return __uint_as_float(w & 0xffff0000u); }
; __global__ void __launch_bounds__(NWAVES * 64, 2) mk_fwd(Args args) {
;     ...
;                 float sy = 0.f;
; #pragma unroll
;                 for (int j = 0; j < 8; ++j) { const float a = bf_lo(yw[q][j].x), b = bf_hi(yw[q][j].x), c2 = bf_lo(yw[q][j].y), d = bf_hi(yw[q][j].y); sy += (a * a + b * b) + (c2 * c2 + d * d); }
;                 const float rsy = __builtin_amdgcn_rsqf(wave_sum(sy) * (1.f / DM) + EPS);
;                 const float* m0 = mod + (size_t)r * 6144;
; #pragma unroll
;                 for (int j = 0; j < 8; ++j) { const int col = 4 * F.lane + 256 * j; const f32x4 gt = *(const f32x4*)(m0 + 2 * DM + col), pn = *(const f32x4*)(post_norm + col);
;                     const f32x4 y4 = (f32x4){bf_lo(yw[q][j].x), bf_hi(yw[q][j].x), bf_lo(yw[q][j].y), bf_hi(yw[q][j].y)};
;                     v[q][j] = v[q][j] + gt * (y4 * rsy * pn);
.Lp6_np7:
	s_waitcnt vmcnt(24)
	v_lshlrev_b32_e32 v216, 16, v80
	v_and_b32_e32 v217, 0xffff0000, v80
	v_lshlrev_b32_e32 v218, 16, v81
	v_and_b32_e32 v219, 0xffff0000, v81
	v_mul_f32_e32 v222, v216, v216
	v_mul_f32_e32 v223, v217, v217
	v_fmac_f32_e32 v222, v218, v218
	v_fmac_f32_e32 v223, v219, v219
	v_lshlrev_b32_e32 v216, 16, v82
	v_and_b32_e32 v217, 0xffff0000, v82
	v_lshlrev_b32_e32 v218, 16, v83
	v_and_b32_e32 v219, 0xffff0000, v83
	v_fmac_f32_e32 v222, v216, v216
	v_fmac_f32_e32 v223, v217, v217
	v_fmac_f32_e32 v222, v218, v218
	v_fmac_f32_e32 v223, v219, v219
	v_lshlrev_b32_e32 v216, 16, v84
	v_and_b32_e32 v217, 0xffff0000, v84
	v_lshlrev_b32_e32 v218, 16, v85
	v_and_b32_e32 v219, 0xffff0000, v85
	v_fmac_f32_e32 v222, v216, v216
	v_fmac_f32_e32 v223, v217, v217
	v_fmac_f32_e32 v222, v218, v218
	v_fmac_f32_e32 v223, v219, v219
	v_lshlrev_b32_e32 v216, 16, v86
	v_and_b32_e32 v217, 0xffff0000, v86
	v_lshlrev_b32_e32 v218, 16, v87
	v_and_b32_e32 v219, 0xffff0000, v87
	v_fmac_f32_e32 v222, v216, v216
	v_fmac_f32_e32 v223, v217, v217
	v_fmac_f32_e32 v222, v218, v218
	v_fmac_f32_e32 v223, v219, v219
	v_lshlrev_b32_e32 v216, 16, v88
	v_and_b32_e32 v217, 0xffff0000, v88
	v_lshlrev_b32_e32 v218, 16, v89
	v_and_b32_e32 v219, 0xffff0000, v89
	v_fmac_f32_e32 v222, v216, v216
	v_fmac_f32_e32 v223, v217, v217
	v_fmac_f32_e32 v222, v218, v218
	v_fmac_f32_e32 v223, v219, v219
	v_lshlrev_b32_e32 v216, 16, v90
	v_and_b32_e32 v217, 0xffff0000, v90
	v_lshlrev_b32_e32 v218, 16, v91
	v_and_b32_e32 v219, 0xffff0000, v91
	v_fmac_f32_e32 v222, v216, v216
	v_fmac_f32_e32 v223, v217, v217
	v_fmac_f32_e32 v222, v218, v218
	v_fmac_f32_e32 v223, v219, v219
	v_lshlrev_b32_e32 v216, 16, v92
	v_and_b32_e32 v217, 0xffff0000, v92
	v_lshlrev_b32_e32 v218, 16, v93
	v_and_b32_e32 v219, 0xffff0000, v93
	v_fmac_f32_e32 v222, v216, v216
	v_fmac_f32_e32 v223, v217, v217
	v_fmac_f32_e32 v222, v218, v218
	v_fmac_f32_e32 v223, v219, v219
	v_lshlrev_b32_e32 v216, 16, v94
	v_and_b32_e32 v217, 0xffff0000, v94
	v_lshlrev_b32_e32 v218, 16, v95
	v_and_b32_e32 v219, 0xffff0000, v95
	v_fmac_f32_e32 v222, v216, v216
	v_fmac_f32_e32 v223, v217, v217
	v_fmac_f32_e32 v222, v218, v218
	v_fmac_f32_e32 v223, v219, v219
	v_add_f32_e32 v222, v222, v223
	s_nop 1
	v_add_f32_dpp v224, v222, v222 quad_perm:[1,0,3,2] row_mask:0xf bank_mask:0xf
	s_nop 1
	v_add_f32_dpp v224, v224, v224 quad_perm:[2,3,0,1] row_mask:0xf bank_mask:0xf
	s_nop 1
	v_add_f32_dpp v224, v224, v224 row_half_mirror row_mask:0xf bank_mask:0xf
	s_nop 1
	v_add_f32_dpp v224, v224, v224 row_mirror row_mask:0xf bank_mask:0xf
	s_nop 1
	v_readlane_b32 s40, v224, 0
	v_readlane_b32 s41, v224, 16
	v_readlane_b32 s42, v224, 32
	v_readlane_b32 s43, v224, 48
	s_nop 1
	v_mov_b32_e32 v225, s40
	v_add_f32_e32 v225, s41, v225
	v_add_f32_e32 v225, s42, v225
	v_add_f32_e32 v225, s43, v225
	v_fmamk_f32 v225, v225, 0x3a000000, v195
	v_rsq_f32_e32 v225, v225
	s_nop 0
	v_lshlrev_b32_e32 v216, 16, v80
	v_and_b32_e32 v217, 0xffff0000, v80
	v_lshlrev_b32_e32 v218, 16, v81
	v_and_b32_e32 v219, 0xffff0000, v81
	v_mul_f32_e32 v216, v225, v216
	v_mul_f32_e32 v217, v225, v217
	v_mul_f32_e32 v218, v225, v218
	v_mul_f32_e32 v219, v225, v219
	v_fmac_f32_e32 v48, v96, v216
	v_fmac_f32_e32 v49, v97, v217
	v_fmac_f32_e32 v50, v98, v218
	v_fmac_f32_e32 v51, v99, v219
	v_lshlrev_b32_e32 v216, 16, v82
	v_and_b32_e32 v217, 0xffff0000, v82
	v_lshlrev_b32_e32 v218, 16, v83
	v_and_b32_e32 v219, 0xffff0000, v83
	v_mul_f32_e32 v216, v225, v216
	v_mul_f32_e32 v217, v225, v217
	v_mul_f32_e32 v218, v225, v218
	v_mul_f32_e32 v219, v225, v219
	v_fmac_f32_e32 v52, v100, v216
	v_fmac_f32_e32 v53, v101, v217
	v_fmac_f32_e32 v54, v102, v218
	v_fmac_f32_e32 v55, v103, v219
	v_lshlrev_b32_e32 v216, 16, v84
	v_and_b32_e32 v217, 0xffff0000, v84
	v_lshlrev_b32_e32 v218, 16, v85
	v_and_b32_e32 v219, 0xffff0000, v85
	v_mul_f32_e32 v216, v225, v216
	v_mul_f32_e32 v217, v225, v217
	v_mul_f32_e32 v218, v225, v218
	v_mul_f32_e32 v219, v225, v219
	v_fmac_f32_e32 v56, v104, v216
	v_fmac_f32_e32 v57, v105, v217
	v_fmac_f32_e32 v58, v106, v218
	v_fmac_f32_e32 v59, v107, v219
	v_lshlrev_b32_e32 v216, 16, v86
	v_and_b32_e32 v217, 0xffff0000, v86
	v_lshlrev_b32_e32 v218, 16, v87
	v_and_b32_e32 v219, 0xffff0000, v87
	v_mul_f32_e32 v216, v225, v216
	v_mul_f32_e32 v217, v225, v217
	v_mul_f32_e32 v218, v225, v218
	v_mul_f32_e32 v219, v225, v219
	v_fmac_f32_e32 v60, v108, v216
	v_fmac_f32_e32 v61, v109, v217
	v_fmac_f32_e32 v62, v110, v218
	v_fmac_f32_e32 v63, v111, v219
	v_lshlrev_b32_e32 v216, 16, v88
	v_and_b32_e32 v217, 0xffff0000, v88
	v_lshlrev_b32_e32 v218, 16, v89
	v_and_b32_e32 v219, 0xffff0000, v89
	v_mul_f32_e32 v216, v225, v216
	v_mul_f32_e32 v217, v225, v217
	v_mul_f32_e32 v218, v225, v218
	v_mul_f32_e32 v219, v225, v219
	v_fmac_f32_e32 v64, v112, v216
	v_fmac_f32_e32 v65, v113, v217
	v_fmac_f32_e32 v66, v114, v218
	v_fmac_f32_e32 v67, v115, v219
	v_lshlrev_b32_e32 v216, 16, v90
	v_and_b32_e32 v217, 0xffff0000, v90
	v_lshlrev_b32_e32 v218, 16, v91
	v_and_b32_e32 v219, 0xffff0000, v91
	v_mul_f32_e32 v216, v225, v216
	v_mul_f32_e32 v217, v225, v217
	v_mul_f32_e32 v218, v225, v218
	v_mul_f32_e32 v219, v225, v219
	v_fmac_f32_e32 v68, v116, v216
	v_fmac_f32_e32 v69, v117, v217
	v_fmac_f32_e32 v70, v118, v218
	v_fmac_f32_e32 v71, v119, v219
	v_lshlrev_b32_e32 v216, 16, v92
	v_and_b32_e32 v217, 0xffff0000, v92
	v_lshlrev_b32_e32 v218, 16, v93
	v_and_b32_e32 v219, 0xffff0000, v93
	v_mul_f32_e32 v216, v225, v216
	v_mul_f32_e32 v217, v225, v217
	v_mul_f32_e32 v218, v225, v218
	v_mul_f32_e32 v219, v225, v219
	v_fmac_f32_e32 v72, v120, v216
	v_fmac_f32_e32 v73, v121, v217
	v_fmac_f32_e32 v74, v122, v218
; __device__ __forceinline__ unsigned cvt_pk_bf16(float lo, float hi) { unsigned r; asm volatile("v_cvt_pk_bf16_f32 %0, %1, %2" : "=v"(r) : "v"(lo), "v"(hi)); return r; }
; __device__ __forceinline__ float sumsq8(const f32x4 (&v)[8]) {
;     float s = 0.f;
; #pragma unroll
;     for (int j = 0; j < 8; ++j) s += (v[j][0] * v[j][0] + v[j][1] * v[j][1]) + (v[j][2] * v[j][2] + v[j][3] * v[j][3]);
;     return wave_sum(s);
; }
; __device__ __forceinline__ void modulate_store(const f32x4 (&v)[8], float rstd, const float* pn, const float* modr, bf16_t* orow, int lane) {
; #pragma unroll
;     for (int j = 0; j < 8; ++j) { const int col = 4 * lane + 256 * j;
;         const f32x4 g = *(const f32x4*)(pn + col), sh = *(const f32x4*)(modr + col), sc = *(const f32x4*)(modr + DM + col);
;         const f32x4 hh = v[j] * rstd * g * (sc + 1.f) + sh;
;         u32x2 w; w.x = cvt_pk_bf16(hh[0], hh[1]); w.y = cvt_pk_bf16(hh[2], hh[3]);
;         *(u32x2*)(orow + col) = w; }
; __global__ void __launch_bounds__(NWAVES * 64, 2) mk_fwd(Args args) {
;     ...
;                 const float rstd = __builtin_amdgcn_rsqf(sumsq8(v[q]) * (1.f / DM) + EPS);
;                 modulate_store(v[q], rstd, pre_norm + DM, mod + (size_t)(9 + r) * 6144, H + (size_t)row * DM, F.lane); }
	v_fmac_f32_e32 v75, v123, v219
	v_lshlrev_b32_e32 v216, 16, v94
	v_and_b32_e32 v217, 0xffff0000, v94
	v_lshlrev_b32_e32 v218, 16, v95
	v_and_b32_e32 v219, 0xffff0000, v95
	v_mul_f32_e32 v216, v225, v216
	v_mul_f32_e32 v217, v225, v217
	v_mul_f32_e32 v218, v225, v218
	v_mul_f32_e32 v219, v225, v219
	v_fmac_f32_e32 v76, v124, v216
	v_fmac_f32_e32 v77, v125, v217
	v_fmac_f32_e32 v78, v126, v218
	v_fmac_f32_e32 v79, v127, v219
	v_mul_f32_e32 v222, v48, v48
	v_mul_f32_e32 v223, v49, v49
	v_fmac_f32_e32 v222, v50, v50
	v_fmac_f32_e32 v223, v51, v51
	v_fmac_f32_e32 v222, v52, v52
	v_fmac_f32_e32 v223, v53, v53
	v_fmac_f32_e32 v222, v54, v54
	v_fmac_f32_e32 v223, v55, v55
	v_fmac_f32_e32 v222, v56, v56
	v_fmac_f32_e32 v223, v57, v57
	v_fmac_f32_e32 v222, v58, v58
	v_fmac_f32_e32 v223, v59, v59
	v_fmac_f32_e32 v222, v60, v60
	v_fmac_f32_e32 v223, v61, v61
	v_fmac_f32_e32 v222, v62, v62
	v_fmac_f32_e32 v223, v63, v63
	v_fmac_f32_e32 v222, v64, v64
	v_fmac_f32_e32 v223, v65, v65
	v_fmac_f32_e32 v222, v66, v66
	v_fmac_f32_e32 v223, v67, v67
	v_fmac_f32_e32 v222, v68, v68
	v_fmac_f32_e32 v223, v69, v69
	v_fmac_f32_e32 v222, v70, v70
	v_fmac_f32_e32 v223, v71, v71
	v_fmac_f32_e32 v222, v72, v72
	v_fmac_f32_e32 v223, v73, v73
	v_fmac_f32_e32 v222, v74, v74
	v_fmac_f32_e32 v223, v75, v75
	v_fmac_f32_e32 v222, v76, v76
	v_fmac_f32_e32 v223, v77, v77
	v_fmac_f32_e32 v222, v78, v78
	v_fmac_f32_e32 v223, v79, v79
	v_add_f32_e32 v222, v222, v223
	s_nop 1
	v_add_f32_dpp v224, v222, v222 quad_perm:[1,0,3,2] row_mask:0xf bank_mask:0xf
	s_nop 1
	v_add_f32_dpp v224, v224, v224 quad_perm:[2,3,0,1] row_mask:0xf bank_mask:0xf
	s_nop 1
	v_add_f32_dpp v224, v224, v224 row_half_mirror row_mask:0xf bank_mask:0xf
	s_nop 1
	v_add_f32_dpp v224, v224, v224 row_mirror row_mask:0xf bank_mask:0xf
	s_nop 1
	v_readlane_b32 s40, v224, 0
	v_readlane_b32 s41, v224, 16
	v_readlane_b32 s42, v224, 32
	v_readlane_b32 s43, v224, 48
	s_nop 1
	v_mov_b32_e32 v225, s40
	v_add_f32_e32 v225, s41, v225
	v_add_f32_e32 v225, s42, v225
	v_add_f32_e32 v225, s43, v225
	v_fmamk_f32 v225, v225, 0x3a000000, v195
	v_rsq_f32_e32 v225, v225
	s_nop 0
	s_add_i32 s0, s6, 7
	s_lshl_b32 s1, s0, 12
	s_add_u32 s26, s84, s1
	s_addc_u32 s27, s85, 0
	s_add_u32 s26, s26, 0xd000000
	s_addc_u32 s27, s27, 0
	v_mul_f32_e32 v216, v225, v48
	v_mul_f32_e32 v217, v225, v49
	v_mul_f32_e32 v218, v225, v50
	v_mul_f32_e32 v219, v225, v51
	v_fma_f32 v216, v216, v128, v160
	v_fma_f32 v217, v217, v129, v161
	v_fma_f32 v218, v218, v130, v162
	v_fma_f32 v219, v219, v131, v163
	v_cvt_pk_bf16_f32 v196, v216, v217
	v_cvt_pk_bf16_f32 v197, v218, v219
	global_store_dwordx2 v194, v[196:197], s[26:27] offset:0
	v_mul_f32_e32 v216, v225, v52
	v_mul_f32_e32 v217, v225, v53
	v_mul_f32_e32 v218, v225, v54
	v_mul_f32_e32 v219, v225, v55
	v_fma_f32 v216, v216, v132, v164
	v_fma_f32 v217, v217, v133, v165
	v_fma_f32 v218, v218, v134, v166
	v_fma_f32 v219, v219, v135, v167
	v_cvt_pk_bf16_f32 v220, v216, v217
	v_cvt_pk_bf16_f32 v221, v218, v219
	global_store_dwordx2 v194, v[220:221], s[26:27] offset:512
	v_mul_f32_e32 v216, v225, v56
	v_mul_f32_e32 v217, v225, v57
	v_mul_f32_e32 v218, v225, v58
	v_mul_f32_e32 v219, v225, v59
	v_fma_f32 v216, v216, v136, v168
	v_fma_f32 v217, v217, v137, v169
	v_fma_f32 v218, v218, v138, v170
	v_fma_f32 v219, v219, v139, v171
	v_cvt_pk_bf16_f32 v196, v216, v217
	v_cvt_pk_bf16_f32 v197, v218, v219
	global_store_dwordx2 v194, v[196:197], s[26:27] offset:1024
	v_mul_f32_e32 v216, v225, v60
	v_mul_f32_e32 v217, v225, v61
	v_mul_f32_e32 v218, v225, v62
	v_mul_f32_e32 v219, v225, v63
	v_fma_f32 v216, v216, v140, v172
	v_fma_f32 v217, v217, v141, v173
	v_fma_f32 v218, v218, v142, v174
	v_fma_f32 v219, v219, v143, v175
	v_cvt_pk_bf16_f32 v220, v216, v217
	v_cvt_pk_bf16_f32 v221, v218, v219
	global_store_dwordx2 v194, v[220:221], s[26:27] offset:1536
	v_mul_f32_e32 v216, v225, v64
	v_mul_f32_e32 v217, v225, v65
	v_mul_f32_e32 v218, v225, v66
	v_mul_f32_e32 v219, v225, v67
	v_fma_f32 v216, v216, v144, v176
	v_fma_f32 v217, v217, v145, v177
	v_fma_f32 v218, v218, v146, v178
	v_fma_f32 v219, v219, v147, v179
	v_cvt_pk_bf16_f32 v196, v216, v217
	v_cvt_pk_bf16_f32 v197, v218, v219
	global_store_dwordx2 v194, v[196:197], s[26:27] offset:2048
	v_mul_f32_e32 v216, v225, v68
	v_mul_f32_e32 v217, v225, v69
	v_mul_f32_e32 v218, v225, v70
	v_mul_f32_e32 v219, v225, v71
	v_fma_f32 v216, v216, v148, v180
	v_fma_f32 v217, v217, v149, v181
	v_fma_f32 v218, v218, v150, v182
	v_fma_f32 v219, v219, v151, v183
	v_cvt_pk_bf16_f32 v220, v216, v217
	v_cvt_pk_bf16_f32 v221, v218, v219
	global_store_dwordx2 v194, v[220:221], s[26:27] offset:2560
	v_mul_f32_e32 v216, v225, v72
	v_mul_f32_e32 v217, v225, v73
	v_mul_f32_e32 v218, v225, v74
	v_mul_f32_e32 v219, v225, v75
	v_fma_f32 v216, v216, v152, v184
	v_fma_f32 v217, v217, v153, v185
	v_fma_f32 v218, v218, v154, v186
	v_fma_f32 v219, v219, v155, v187
	v_cvt_pk_bf16_f32 v196, v216, v217
	v_cvt_pk_bf16_f32 v197, v218, v219
	global_store_dwordx2 v194, v[196:197], s[26:27] offset:3072
	v_mul_f32_e32 v216, v225, v76
	v_mul_f32_e32 v217, v225, v77
	v_mul_f32_e32 v218, v225, v78
	v_mul_f32_e32 v219, v225, v79
	v_fma_f32 v216, v216, v156, v188
	v_fma_f32 v217, v217, v157, v189
	v_fma_f32 v218, v218, v158, v190
	v_fma_f32 v219, v219, v159, v191
	v_cvt_pk_bf16_f32 v220, v216, v217
	v_cvt_pk_bf16_f32 v221, v218, v219
	global_store_dwordx2 v194, v[220:221], s[26:27] offset:3584
	s_add_i32 s0, s6, 8
	s_add_i32 s0, s6, 8
	s_lshr_b32 s8, s0, 11
	s_cmp_lt_u32 s0, 0x4000
	s_cselect_b32 s8, s8, 8
	s_cmp_eq_u32 s8, s7
	s_cbranch_scc1 .Lp6_np8
; __device__ __forceinline__ void modulate_store(const f32x4 (&v)[8], float rstd, const float* pn, const float* modr, bf16_t* orow, int lane) {
; #pragma unroll
;     for (int j = 0; j < 8; ++j) { const int col = 4 * lane + 256 * j;
;         const f32x4 g = *(const f32x4*)(pn + col), sh = *(const f32x4*)(modr + col), sc = *(const f32x4*)(modr + DM + col);
;         const f32x4 hh = v[j] * rstd * g * (sc + 1.f) + sh;
; __global__ void __launch_bounds__(NWAVES * 64, 2) mk_fwd(Args args) {
;     ...
;                 const float* m0 = mod + (size_t)r * 6144;
; #pragma unroll
;                 for (int j = 0; j < 8; ++j) { const int col = 4 * F.lane + 256 * j; const f32x4 gt = *(const f32x4*)(m0 + 2 * DM + col), pn = *(const f32x4*)(post_norm + col);
	s_mov_b32 s7, s8
	s_add_i32 s1, s8, 9
	s_mul_i32 s1, s1, 0x6000
	s_add_u32 s44, s84, s1
	s_addc_u32 s45, s85, 0
	s_add_u32 s44, s44, 0x2000
	s_addc_u32 s45, s45, 0
	s_add_i32 s1, s8, 9
	s_mul_i32 s1, s1, 0x6000
	s_add_u32 s36, s84, s1
	s_addc_u32 s37, s85, 0
	s_add_u32 s38, s80, 0x2000
	s_addc_u32 s39, s81, 0
	s_mul_i32 s1, s8, 0x6000
	s_add_u32 s34, s84, s1
	s_addc_u32 s35, s85, 0
	s_add_u32 s34, s34, 0x4000
	s_addc_u32 s35, s35, 0
	global_load_dwordx4 v[96:99], v192, s[34:35] offset:0
	global_load_dwordx4 v[200:203], v192, s[82:83] offset:0
	global_load_dwordx4 v[100:103], v192, s[34:35] offset:1024
	global_load_dwordx4 v[204:207], v192, s[82:83] offset:1024
	global_load_dwordx4 v[104:107], v192, s[34:35] offset:2048
	global_load_dwordx4 v[208:211], v192, s[82:83] offset:2048
	global_load_dwordx4 v[108:111], v192, s[34:35] offset:3072
	global_load_dwordx4 v[212:215], v192, s[82:83] offset:3072
	s_waitcnt vmcnt(0)
	v_mul_f32_e32 v96, v96, v200
	v_mul_f32_e32 v97, v97, v201
	v_mul_f32_e32 v98, v98, v202
	v_mul_f32_e32 v99, v99, v203
	v_mul_f32_e32 v100, v100, v204
	v_mul_f32_e32 v101, v101, v205
	v_mul_f32_e32 v102, v102, v206
	v_mul_f32_e32 v103, v103, v207
	v_mul_f32_e32 v104, v104, v208
	v_mul_f32_e32 v105, v105, v209
	v_mul_f32_e32 v106, v106, v210
	v_mul_f32_e32 v107, v107, v211
	v_mul_f32_e32 v108, v108, v212
	v_mul_f32_e32 v109, v109, v213
	v_mul_f32_e32 v110, v110, v214
	v_mul_f32_e32 v111, v111, v215
	global_load_dwordx4 v[128:131], v192, s[38:39] offset:0
	global_load_dwordx4 v[200:203], v192, s[44:45] offset:0
	global_load_dwordx4 v[160:163], v192, s[36:37] offset:0
	global_load_dwordx4 v[132:135], v192, s[38:39] offset:1024
	global_load_dwordx4 v[204:207], v192, s[44:45] offset:1024
	global_load_dwordx4 v[164:167], v192, s[36:37] offset:1024
	global_load_dwordx4 v[136:139], v192, s[38:39] offset:2048
	global_load_dwordx4 v[208:211], v192, s[44:45] offset:2048
	global_load_dwordx4 v[168:171], v192, s[36:37] offset:2048
	global_load_dwordx4 v[140:143], v192, s[38:39] offset:3072
	global_load_dwordx4 v[212:215], v192, s[44:45] offset:3072
	global_load_dwordx4 v[172:175], v192, s[36:37] offset:3072
	s_waitcnt vmcnt(0)
	v_add_f32_e32 v200, 1.0, v200
	v_add_f32_e32 v201, 1.0, v201
	v_add_f32_e32 v202, 1.0, v202
	v_add_f32_e32 v203, 1.0, v203
	v_mul_f32_e32 v128, v128, v200
	v_mul_f32_e32 v129, v129, v201
	v_mul_f32_e32 v130, v130, v202
	v_mul_f32_e32 v131, v131, v203
	v_add_f32_e32 v204, 1.0, v204
	v_add_f32_e32 v205, 1.0, v205
	v_add_f32_e32 v206, 1.0, v206
	v_add_f32_e32 v207, 1.0, v207
	v_mul_f32_e32 v132, v132, v204
	v_mul_f32_e32 v133, v133, v205
	v_mul_f32_e32 v134, v134, v206
	v_mul_f32_e32 v135, v135, v207
	v_add_f32_e32 v208, 1.0, v208
	v_add_f32_e32 v209, 1.0, v209
	v_add_f32_e32 v210, 1.0, v210
	v_add_f32_e32 v211, 1.0, v211
	v_mul_f32_e32 v136, v136, v208
	v_mul_f32_e32 v137, v137, v209
	v_mul_f32_e32 v138, v138, v210
	v_mul_f32_e32 v139, v139, v211
	v_add_f32_e32 v212, 1.0, v212
	v_add_f32_e32 v213, 1.0, v213
	v_add_f32_e32 v214, 1.0, v214
	v_add_f32_e32 v215, 1.0, v215
	v_mul_f32_e32 v140, v140, v212
	v_mul_f32_e32 v141, v141, v213
	v_mul_f32_e32 v142, v142, v214
	v_mul_f32_e32 v143, v143, v215
	global_load_dwordx4 v[112:115], v193, s[34:35] offset:0
	global_load_dwordx4 v[200:203], v193, s[82:83] offset:0
	global_load_dwordx4 v[116:119], v193, s[34:35] offset:1024
	global_load_dwordx4 v[204:207], v193, s[82:83] offset:1024
	global_load_dwordx4 v[120:123], v193, s[34:35] offset:2048
	global_load_dwordx4 v[208:211], v193, s[82:83] offset:2048
	global_load_dwordx4 v[124:127], v193, s[34:35] offset:3072
	global_load_dwordx4 v[212:215], v193, s[82:83] offset:3072
	s_waitcnt vmcnt(0)
	v_mul_f32_e32 v112, v112, v200
	v_mul_f32_e32 v113, v113, v201
	v_mul_f32_e32 v114, v114, v202
	v_mul_f32_e32 v115, v115, v203
	v_mul_f32_e32 v116, v116, v204
	v_mul_f32_e32 v117, v117, v205
	v_mul_f32_e32 v118, v118, v206
	v_mul_f32_e32 v119, v119, v207
	v_mul_f32_e32 v120, v120, v208
	v_mul_f32_e32 v121, v121, v209
	v_mul_f32_e32 v122, v122, v210
	v_mul_f32_e32 v123, v123, v211
	v_mul_f32_e32 v124, v124, v212
	v_mul_f32_e32 v125, v125, v213
	v_mul_f32_e32 v126, v126, v214
	v_mul_f32_e32 v127, v127, v215
	global_load_dwordx4 v[144:147], v193, s[38:39] offset:0
	global_load_dwordx4 v[200:203], v193, s[44:45] offset:0
	global_load_dwordx4 v[176:179], v193, s[36:37] offset:0
	global_load_dwordx4 v[148:151], v193, s[38:39] offset:1024
	global_load_dwordx4 v[204:207], v193, s[44:45] offset:1024
	global_load_dwordx4 v[180:183], v193, s[36:37] offset:1024
	global_load_dwordx4 v[152:155], v193, s[38:39] offset:2048
	global_load_dwordx4 v[208:211], v193, s[44:45] offset:2048
	global_load_dwordx4 v[184:187], v193, s[36:37] offset:2048
	global_load_dwordx4 v[156:159], v193, s[38:39] offset:3072
	global_load_dwordx4 v[212:215], v193, s[44:45] offset:3072
	global_load_dwordx4 v[188:191], v193, s[36:37] offset:3072
	s_waitcnt vmcnt(0)
	v_add_f32_e32 v200, 1.0, v200
	v_add_f32_e32 v201, 1.0, v201
	v_add_f32_e32 v202, 1.0, v202
	v_add_f32_e32 v203, 1.0, v203
	v_mul_f32_e32 v144, v144, v200
	v_mul_f32_e32 v145, v145, v201
	v_mul_f32_e32 v146, v146, v202
	v_mul_f32_e32 v147, v147, v203
	v_add_f32_e32 v204, 1.0, v204
	v_add_f32_e32 v205, 1.0, v205
	v_add_f32_e32 v206, 1.0, v206
	v_add_f32_e32 v207, 1.0, v207
	v_mul_f32_e32 v148, v148, v204
	v_mul_f32_e32 v149, v149, v205
	v_mul_f32_e32 v150, v150, v206
	v_mul_f32_e32 v151, v151, v207
	v_add_f32_e32 v208, 1.0, v208
	v_add_f32_e32 v209, 1.0, v209
	v_add_f32_e32 v210, 1.0, v210
	v_add_f32_e32 v211, 1.0, v211
	v_mul_f32_e32 v152, v152, v208
	v_mul_f32_e32 v153, v153, v209
	v_mul_f32_e32 v154, v154, v210
	v_mul_f32_e32 v155, v155, v211
	v_add_f32_e32 v212, 1.0, v212
	v_add_f32_e32 v213, 1.0, v213
	v_add_f32_e32 v214, 1.0, v214
	v_add_f32_e32 v215, 1.0, v215
	v_mul_f32_e32 v156, v156, v212
	v_mul_f32_e32 v157, v157, v213
	v_mul_f32_e32 v158, v158, v214
	v_mul_f32_e32 v159, v159, v215
; __device__ __forceinline__ float bf_lo(unsigned w) { return __uint_as_float(w << 16); }
; __device__ __forceinline__ float bf_hi(unsigned w) { return __uint_as_float(w & 0xffff0000u); }
; __global__ void __launch_bounds__(NWAVES * 64, 2) mk_fwd(Args args) {
;     ...
;                 float sy = 0.f;
; #pragma unroll
;                 for (int j = 0; j < 8; ++j) { const float a = bf_lo(yw[q][j].x), b = bf_hi(yw[q][j].x), c2 = bf_lo(yw[q][j].y), d = bf_hi(yw[q][j].y); sy += (a * a + b * b) + (c2 * c2 + d * d); }
;                 const float rsy = __builtin_amdgcn_rsqf(wave_sum(sy) * (1.f / DM) + EPS);
;                 const float* m0 = mod + (size_t)r * 6144;
; #pragma unroll
;                 for (int j = 0; j < 8; ++j) { const int col = 4 * F.lane + 256 * j; const f32x4 gt = *(const f32x4*)(m0 + 2 * DM + col), pn = *(const f32x4*)(post_norm + col);
;                     const f32x4 y4 = (f32x4){bf_lo(yw[q][j].x), bf_hi(yw[q][j].x), bf_lo(yw[q][j].y), bf_hi(yw[q][j].y)};
;                     v[q][j] = v[q][j] + gt * (y4 * rsy * pn);
.Lp6_np8:
	s_waitcnt vmcnt(8)
	v_lshlrev_b32_e32 v216, 16, v32
	v_and_b32_e32 v217, 0xffff0000, v32
	v_lshlrev_b32_e32 v218, 16, v33
	v_and_b32_e32 v219, 0xffff0000, v33
	v_mul_f32_e32 v222, v216, v216
	v_mul_f32_e32 v223, v217, v217
	v_fmac_f32_e32 v222, v218, v218
	v_fmac_f32_e32 v223, v219, v219
	v_lshlrev_b32_e32 v216, 16, v34
	v_and_b32_e32 v217, 0xffff0000, v34
	v_lshlrev_b32_e32 v218, 16, v35
	v_and_b32_e32 v219, 0xffff0000, v35
	v_fmac_f32_e32 v222, v216, v216
	v_fmac_f32_e32 v223, v217, v217
	v_fmac_f32_e32 v222, v218, v218
	v_fmac_f32_e32 v223, v219, v219
	v_lshlrev_b32_e32 v216, 16, v36
	v_and_b32_e32 v217, 0xffff0000, v36
	v_lshlrev_b32_e32 v218, 16, v37
	v_and_b32_e32 v219, 0xffff0000, v37
	v_fmac_f32_e32 v222, v216, v216
	v_fmac_f32_e32 v223, v217, v217
	v_fmac_f32_e32 v222, v218, v218
	v_fmac_f32_e32 v223, v219, v219
	v_lshlrev_b32_e32 v216, 16, v38
	v_and_b32_e32 v217, 0xffff0000, v38
	v_lshlrev_b32_e32 v218, 16, v39
	v_and_b32_e32 v219, 0xffff0000, v39
	v_fmac_f32_e32 v222, v216, v216
	v_fmac_f32_e32 v223, v217, v217
	v_fmac_f32_e32 v222, v218, v218
	v_fmac_f32_e32 v223, v219, v219
	v_lshlrev_b32_e32 v216, 16, v40
	v_and_b32_e32 v217, 0xffff0000, v40
	v_lshlrev_b32_e32 v218, 16, v41
	v_and_b32_e32 v219, 0xffff0000, v41
	v_fmac_f32_e32 v222, v216, v216
	v_fmac_f32_e32 v223, v217, v217
	v_fmac_f32_e32 v222, v218, v218
	v_fmac_f32_e32 v223, v219, v219
	v_lshlrev_b32_e32 v216, 16, v42
	v_and_b32_e32 v217, 0xffff0000, v42
	v_lshlrev_b32_e32 v218, 16, v43
	v_and_b32_e32 v219, 0xffff0000, v43
	v_fmac_f32_e32 v222, v216, v216
	v_fmac_f32_e32 v223, v217, v217
	v_fmac_f32_e32 v222, v218, v218
	v_fmac_f32_e32 v223, v219, v219
	v_lshlrev_b32_e32 v216, 16, v44
	v_and_b32_e32 v217, 0xffff0000, v44
	v_lshlrev_b32_e32 v218, 16, v45
	v_and_b32_e32 v219, 0xffff0000, v45
	v_fmac_f32_e32 v222, v216, v216
	v_fmac_f32_e32 v223, v217, v217
	v_fmac_f32_e32 v222, v218, v218
	v_fmac_f32_e32 v223, v219, v219
	v_lshlrev_b32_e32 v216, 16, v46
	v_and_b32_e32 v217, 0xffff0000, v46
	v_lshlrev_b32_e32 v218, 16, v47
	v_and_b32_e32 v219, 0xffff0000, v47
	v_fmac_f32_e32 v222, v216, v216
	v_fmac_f32_e32 v223, v217, v217
	v_fmac_f32_e32 v222, v218, v218
	v_fmac_f32_e32 v223, v219, v219
	v_add_f32_e32 v222, v222, v223
	s_nop 1
	v_add_f32_dpp v224, v222, v222 quad_perm:[1,0,3,2] row_mask:0xf bank_mask:0xf
	s_nop 1
	v_add_f32_dpp v224, v224, v224 quad_perm:[2,3,0,1] row_mask:0xf bank_mask:0xf
	s_nop 1
	v_add_f32_dpp v224, v224, v224 row_half_mirror row_mask:0xf bank_mask:0xf
	s_nop 1
	v_add_f32_dpp v224, v224, v224 row_mirror row_mask:0xf bank_mask:0xf
	s_nop 1
	v_readlane_b32 s40, v224, 0
	v_readlane_b32 s41, v224, 16
	v_readlane_b32 s42, v224, 32
	v_readlane_b32 s43, v224, 48
	s_nop 1
	v_mov_b32_e32 v225, s40
	v_add_f32_e32 v225, s41, v225
	v_add_f32_e32 v225, s42, v225
	v_add_f32_e32 v225, s43, v225
	v_fmamk_f32 v225, v225, 0x3a000000, v195
	v_rsq_f32_e32 v225, v225
	s_nop 0
	v_lshlrev_b32_e32 v216, 16, v32
	v_and_b32_e32 v217, 0xffff0000, v32
	v_lshlrev_b32_e32 v218, 16, v33
	v_and_b32_e32 v219, 0xffff0000, v33
	v_mul_f32_e32 v216, v225, v216
	v_mul_f32_e32 v217, v225, v217
	v_mul_f32_e32 v218, v225, v218
	v_mul_f32_e32 v219, v225, v219
	v_fmac_f32_e32 v0, v96, v216
	v_fmac_f32_e32 v1, v97, v217
	v_fmac_f32_e32 v2, v98, v218
	v_fmac_f32_e32 v3, v99, v219
	v_lshlrev_b32_e32 v216, 16, v34
	v_and_b32_e32 v217, 0xffff0000, v34
	v_lshlrev_b32_e32 v218, 16, v35
	v_and_b32_e32 v219, 0xffff0000, v35
	v_mul_f32_e32 v216, v225, v216
	v_mul_f32_e32 v217, v225, v217
	v_mul_f32_e32 v218, v225, v218
	v_mul_f32_e32 v219, v225, v219
	v_fmac_f32_e32 v4, v100, v216
	v_fmac_f32_e32 v5, v101, v217
	v_fmac_f32_e32 v6, v102, v218
	v_fmac_f32_e32 v7, v103, v219
	v_lshlrev_b32_e32 v216, 16, v36
	v_and_b32_e32 v217, 0xffff0000, v36
	v_lshlrev_b32_e32 v218, 16, v37
	v_and_b32_e32 v219, 0xffff0000, v37
	v_mul_f32_e32 v216, v225, v216
	v_mul_f32_e32 v217, v225, v217
	v_mul_f32_e32 v218, v225, v218
	v_mul_f32_e32 v219, v225, v219
	v_fmac_f32_e32 v8, v104, v216
	v_fmac_f32_e32 v9, v105, v217
	v_fmac_f32_e32 v10, v106, v218
	v_fmac_f32_e32 v11, v107, v219
	v_lshlrev_b32_e32 v216, 16, v38
	v_and_b32_e32 v217, 0xffff0000, v38
	v_lshlrev_b32_e32 v218, 16, v39
	v_and_b32_e32 v219, 0xffff0000, v39
	v_mul_f32_e32 v216, v225, v216
	v_mul_f32_e32 v217, v225, v217
	v_mul_f32_e32 v218, v225, v218
	v_mul_f32_e32 v219, v225, v219
	v_fmac_f32_e32 v12, v108, v216
	v_fmac_f32_e32 v13, v109, v217
	v_fmac_f32_e32 v14, v110, v218
	v_fmac_f32_e32 v15, v111, v219
	v_lshlrev_b32_e32 v216, 16, v40
	v_and_b32_e32 v217, 0xffff0000, v40
	v_lshlrev_b32_e32 v218, 16, v41
	v_and_b32_e32 v219, 0xffff0000, v41
	v_mul_f32_e32 v216, v225, v216
	v_mul_f32_e32 v217, v225, v217
	v_mul_f32_e32 v218, v225, v218
	v_mul_f32_e32 v219, v225, v219
	v_fmac_f32_e32 v16, v112, v216
	v_fmac_f32_e32 v17, v113, v217
	v_fmac_f32_e32 v18, v114, v218
	v_fmac_f32_e32 v19, v115, v219
	v_lshlrev_b32_e32 v216, 16, v42
	v_and_b32_e32 v217, 0xffff0000, v42
	v_lshlrev_b32_e32 v218, 16, v43
	v_and_b32_e32 v219, 0xffff0000, v43
	v_mul_f32_e32 v216, v225, v216
	v_mul_f32_e32 v217, v225, v217
	v_mul_f32_e32 v218, v225, v218
	v_mul_f32_e32 v219, v225, v219
	v_fmac_f32_e32 v20, v116, v216
	v_fmac_f32_e32 v21, v117, v217
	v_fmac_f32_e32 v22, v118, v218
	v_fmac_f32_e32 v23, v119, v219
	v_lshlrev_b32_e32 v216, 16, v44
	v_and_b32_e32 v217, 0xffff0000, v44
	v_lshlrev_b32_e32 v218, 16, v45
	v_and_b32_e32 v219, 0xffff0000, v45
	v_mul_f32_e32 v216, v225, v216
	v_mul_f32_e32 v217, v225, v217
	v_mul_f32_e32 v218, v225, v218
; __device__ __forceinline__ unsigned cvt_pk_bf16(float lo, float hi) { unsigned r; asm volatile("v_cvt_pk_bf16_f32 %0, %1, %2" : "=v"(r) : "v"(lo), "v"(hi)); return r; }
; __device__ __forceinline__ float sumsq8(const f32x4 (&v)[8]) {
;     float s = 0.f;
; #pragma unroll
;     for (int j = 0; j < 8; ++j) s += (v[j][0] * v[j][0] + v[j][1] * v[j][1]) + (v[j][2] * v[j][2] + v[j][3] * v[j][3]);
;     return wave_sum(s);
; }
; __device__ __forceinline__ void modulate_store(const f32x4 (&v)[8], float rstd, const float* pn, const float* modr, bf16_t* orow, int lane) {
; #pragma unroll
;     for (int j = 0; j < 8; ++j) { const int col = 4 * lane + 256 * j;
;         const f32x4 g = *(const f32x4*)(pn + col), sh = *(const f32x4*)(modr + col), sc = *(const f32x4*)(modr + DM + col);
;         const f32x4 hh = v[j] * rstd * g * (sc + 1.f) + sh;
;         u32x2 w; w.x = cvt_pk_bf16(hh[0], hh[1]); w.y = cvt_pk_bf16(hh[2], hh[3]);
;         *(u32x2*)(orow + col) = w; }
; __global__ void __launch_bounds__(NWAVES * 64, 2) mk_fwd(Args args) {
;     ...
;                 const float rstd = __builtin_amdgcn_rsqf(sumsq8(v[q]) * (1.f / DM) + EPS);
;                 modulate_store(v[q], rstd, pre_norm + DM, mod + (size_t)(9 + r) * 6144, H + (size_t)row * DM, F.lane); }
	v_mul_f32_e32 v219, v225, v219
	v_fmac_f32_e32 v24, v120, v216
	v_fmac_f32_e32 v25, v121, v217
	v_fmac_f32_e32 v26, v122, v218
	v_fmac_f32_e32 v27, v123, v219
	v_lshlrev_b32_e32 v216, 16, v46
	v_and_b32_e32 v217, 0xffff0000, v46
	v_lshlrev_b32_e32 v218, 16, v47
	v_and_b32_e32 v219, 0xffff0000, v47
	v_mul_f32_e32 v216, v225, v216
	v_mul_f32_e32 v217, v225, v217
	v_mul_f32_e32 v218, v225, v218
	v_mul_f32_e32 v219, v225, v219
	v_fmac_f32_e32 v28, v124, v216
	v_fmac_f32_e32 v29, v125, v217
	v_fmac_f32_e32 v30, v126, v218
	v_fmac_f32_e32 v31, v127, v219
	v_mul_f32_e32 v222, v0, v0
	v_mul_f32_e32 v223, v1, v1
	v_fmac_f32_e32 v222, v2, v2
	v_fmac_f32_e32 v223, v3, v3
	v_fmac_f32_e32 v222, v4, v4
	v_fmac_f32_e32 v223, v5, v5
	v_fmac_f32_e32 v222, v6, v6
	v_fmac_f32_e32 v223, v7, v7
	v_fmac_f32_e32 v222, v8, v8
	v_fmac_f32_e32 v223, v9, v9
	v_fmac_f32_e32 v222, v10, v10
	v_fmac_f32_e32 v223, v11, v11
	v_fmac_f32_e32 v222, v12, v12
	v_fmac_f32_e32 v223, v13, v13
	v_fmac_f32_e32 v222, v14, v14
	v_fmac_f32_e32 v223, v15, v15
	v_fmac_f32_e32 v222, v16, v16
	v_fmac_f32_e32 v223, v17, v17
	v_fmac_f32_e32 v222, v18, v18
	v_fmac_f32_e32 v223, v19, v19
	v_fmac_f32_e32 v222, v20, v20
	v_fmac_f32_e32 v223, v21, v21
	v_fmac_f32_e32 v222, v22, v22
	v_fmac_f32_e32 v223, v23, v23
	v_fmac_f32_e32 v222, v24, v24
	v_fmac_f32_e32 v223, v25, v25
	v_fmac_f32_e32 v222, v26, v26
	v_fmac_f32_e32 v223, v27, v27
	v_fmac_f32_e32 v222, v28, v28
	v_fmac_f32_e32 v223, v29, v29
	v_fmac_f32_e32 v222, v30, v30
	v_fmac_f32_e32 v223, v31, v31
	v_add_f32_e32 v222, v222, v223
	s_nop 1
	v_add_f32_dpp v224, v222, v222 quad_perm:[1,0,3,2] row_mask:0xf bank_mask:0xf
	s_nop 1
	v_add_f32_dpp v224, v224, v224 quad_perm:[2,3,0,1] row_mask:0xf bank_mask:0xf
	s_nop 1
	v_add_f32_dpp v224, v224, v224 row_half_mirror row_mask:0xf bank_mask:0xf
	s_nop 1
	v_add_f32_dpp v224, v224, v224 row_mirror row_mask:0xf bank_mask:0xf
	s_nop 1
	v_readlane_b32 s40, v224, 0
	v_readlane_b32 s41, v224, 16
	v_readlane_b32 s42, v224, 32
	v_readlane_b32 s43, v224, 48
	s_nop 1
	v_mov_b32_e32 v225, s40
	v_add_f32_e32 v225, s41, v225
	v_add_f32_e32 v225, s42, v225
	v_add_f32_e32 v225, s43, v225
	v_fmamk_f32 v225, v225, 0x3a000000, v195
	v_rsq_f32_e32 v225, v225
	s_nop 0
	s_add_i32 s0, s6, 8
	s_lshl_b32 s1, s0, 12
	s_add_u32 s26, s84, s1
	s_addc_u32 s27, s85, 0
	s_add_u32 s26, s26, 0xd000000
	s_addc_u32 s27, s27, 0
	v_mul_f32_e32 v216, v225, v0
	v_mul_f32_e32 v217, v225, v1
	v_mul_f32_e32 v218, v225, v2
	v_mul_f32_e32 v219, v225, v3
	v_fma_f32 v216, v216, v128, v160
	v_fma_f32 v217, v217, v129, v161
	v_fma_f32 v218, v218, v130, v162
	v_fma_f32 v219, v219, v131, v163
	v_cvt_pk_bf16_f32 v196, v216, v217
	v_cvt_pk_bf16_f32 v197, v218, v219
	global_store_dwordx2 v194, v[196:197], s[26:27] offset:0
	v_mul_f32_e32 v216, v225, v4
	v_mul_f32_e32 v217, v225, v5
	v_mul_f32_e32 v218, v225, v6
	v_mul_f32_e32 v219, v225, v7
	v_fma_f32 v216, v216, v132, v164
	v_fma_f32 v217, v217, v133, v165
	v_fma_f32 v218, v218, v134, v166
	v_fma_f32 v219, v219, v135, v167
	v_cvt_pk_bf16_f32 v220, v216, v217
	v_cvt_pk_bf16_f32 v221, v218, v219
	global_store_dwordx2 v194, v[220:221], s[26:27] offset:512
	v_mul_f32_e32 v216, v225, v8
	v_mul_f32_e32 v217, v225, v9
	v_mul_f32_e32 v218, v225, v10
	v_mul_f32_e32 v219, v225, v11
	v_fma_f32 v216, v216, v136, v168
	v_fma_f32 v217, v217, v137, v169
	v_fma_f32 v218, v218, v138, v170
	v_fma_f32 v219, v219, v139, v171
	v_cvt_pk_bf16_f32 v196, v216, v217
	v_cvt_pk_bf16_f32 v197, v218, v219
	global_store_dwordx2 v194, v[196:197], s[26:27] offset:1024
	v_mul_f32_e32 v216, v225, v12
	v_mul_f32_e32 v217, v225, v13
	v_mul_f32_e32 v218, v225, v14
	v_mul_f32_e32 v219, v225, v15
	v_fma_f32 v216, v216, v140, v172
	v_fma_f32 v217, v217, v141, v173
	v_fma_f32 v218, v218, v142, v174
	v_fma_f32 v219, v219, v143, v175
	v_cvt_pk_bf16_f32 v220, v216, v217
	v_cvt_pk_bf16_f32 v221, v218, v219
	global_store_dwordx2 v194, v[220:221], s[26:27] offset:1536
	v_mul_f32_e32 v216, v225, v16
	v_mul_f32_e32 v217, v225, v17
	v_mul_f32_e32 v218, v225, v18
	v_mul_f32_e32 v219, v225, v19
	v_fma_f32 v216, v216, v144, v176
	v_fma_f32 v217, v217, v145, v177
	v_fma_f32 v218, v218, v146, v178
	v_fma_f32 v219, v219, v147, v179
	v_cvt_pk_bf16_f32 v196, v216, v217
	v_cvt_pk_bf16_f32 v197, v218, v219
	global_store_dwordx2 v194, v[196:197], s[26:27] offset:2048
	v_mul_f32_e32 v216, v225, v20
	v_mul_f32_e32 v217, v225, v21
	v_mul_f32_e32 v218, v225, v22
	v_mul_f32_e32 v219, v225, v23
	v_fma_f32 v216, v216, v148, v180
	v_fma_f32 v217, v217, v149, v181
	v_fma_f32 v218, v218, v150, v182
	v_fma_f32 v219, v219, v151, v183
	v_cvt_pk_bf16_f32 v220, v216, v217
	v_cvt_pk_bf16_f32 v221, v218, v219
	global_store_dwordx2 v194, v[220:221], s[26:27] offset:2560
	v_mul_f32_e32 v216, v225, v24
	v_mul_f32_e32 v217, v225, v25
	v_mul_f32_e32 v218, v225, v26
	v_mul_f32_e32 v219, v225, v27
	v_fma_f32 v216, v216, v152, v184
	v_fma_f32 v217, v217, v153, v185
	v_fma_f32 v218, v218, v154, v186
	v_fma_f32 v219, v219, v155, v187
	v_cvt_pk_bf16_f32 v196, v216, v217
	v_cvt_pk_bf16_f32 v197, v218, v219
	global_store_dwordx2 v194, v[196:197], s[26:27] offset:3072
	v_mul_f32_e32 v216, v225, v28
	v_mul_f32_e32 v217, v225, v29
	v_mul_f32_e32 v218, v225, v30
	v_mul_f32_e32 v219, v225, v31
	v_fma_f32 v216, v216, v156, v188
	v_fma_f32 v217, v217, v157, v189
	v_fma_f32 v218, v218, v158, v190
	v_fma_f32 v219, v219, v159, v191
	v_cvt_pk_bf16_f32 v220, v216, v217
	v_cvt_pk_bf16_f32 v221, v218, v219
	global_store_dwordx2 v194, v[220:221], s[26:27] offset:3584
	s_branch .LBB0_778

; __global__ void __launch_bounds__(NWAVES * 64, 2) mk_fwd(Args args) {
;     ...
;     if (IN(7)) {
;         pg8::Gemm g{H, WMLA, MT, NMLA, DM, DM, DM, 0}; pg8::StaticOrder S; S.init(MT, NMLA, F.G, (int)blockIdx.x);
;         pg8::EpiMlaIn E{CQ, CKV, KR, SG, ssq, tab};
;         pg8::gemm_phase<pg8::EpiMlaIn>(F.lds, g, S, E);
.LBB0_828:
	s_cmpk_lg_i32 s63, 0x100
	s_cbranch_scc1 .Lh1reloc_skip
	s_add_u32 s12, s84, 0xd000000
	s_addc_u32 s13, s85, 0

; __global__ void __launch_bounds__(NWAVES * 64, 2) mk_fwd(Args args) {
;     ...
;         { pg8::Gemm g{CKV, WUKV, MT, 4096, 512, 512, 512, 0}; pg8::StaticOrder S; S.init(MT, 4096, F.G, (int)blockIdx.x);
;           pg8::EpiKV E{KN, V, ssq + MT};
;           pg8::gemm_phase<pg8::EpiKV>(F.lds, g, S, E); }
.LBB0_940:
	s_add_u32 s12, s84, 0x4000000
	s_addc_u32 s13, s85, 0
	s_cmpk_lg_i32 s63, 0x100
	s_cbranch_scc1 .Lvreloc_skip
	s_mov_b32 s20, s94
	s_mov_b32 s21, s95
